# gemm mainloops: per-block s_setprio toggling removed
# speedup vs baseline: 1.0595x; 1.0018x over previous
; #define PG8_STAGE(bufoff, gbase, voff) do { _Pragma("unroll") for (int _i = 0; _i < 2; ++_i) \
;         __builtin_amdgcn_global_load_lds((const unsigned*)((const char*)(gbase) + (voff)[_i]), (PG8_LAS unsigned*)(lds + (bufoff) + ldsw + _i * 8192), 16, 0, 0); } while (0)
; #define PG8_LDA(dst, b, h) do { _Pragma("unroll") for (int m = 0; m < 4; ++m) _Pragma("unroll") for (int k = 0; k < 2; ++k) dst[m][k] = *(const PG8_LAS bf16x8*)(lds + PG8_SA(b, h) + aoff + m * 2048 + k * 1024); } while (0)
; #define PG8_LDB(dst, b, h) do { _Pragma("unroll") for (int n = 0; n < 2; ++n) _Pragma("unroll") for (int k = 0; k < 2; ++k) dst[n][k] = *(const PG8_LAS bf16x8*)(lds + PG8_SB(b, h) + boff + n * 2048 + k * 1024); } while (0)
; #define PG8_MMA(ai, bj, At, Bt) do { __builtin_amdgcn_s_setprio(1); _Pragma("unroll") for (int m = 0; m < 4; ++m) _Pragma("unroll") for (int n = 0; n < 2; ++n) _Pragma("unroll") for (int k = 0; k < 2; ++k) \
;         acc[ai][bj][m][n] = __builtin_amdgcn_mfma_f32_16x16x32_bf16(Bt[n][k], At[m][k], acc[ai][bj][m][n], 0, 0, 0); __builtin_amdgcn_s_setprio(0); } while (0)
; #define PG8_WAIT_V(n) asm volatile("s_waitcnt vmcnt(" #n ")" ::: "memory")
; #define PG8_WAIT_L(n) asm volatile("s_waitcnt lgkmcnt(" #n ")" ::: "memory")
; template <class Epi, class Sched, bool ALIGN_EPI = false, bool SP2 = false>
; __device__ __forceinline__ void gemm_phase(PG8_LAS unsigned char* lds, const Gemm g, const Sched& S, const Epi& E, const int tid) {
;     ...
;             const bool last = (t == nt - 2);
;             const char* a1 = cA + (size_t)(t + 1) * kstep;
;             const char* a2 = last ? nA : cA + (size_t)(t + 2) * kstep; const char* b2 = last ? nB : cB + (size_t)(t + 2) * kstep;
;             const char* a3 = a2 + kstep; const char* b3 = b2 + kstep;
;             if (last && has_next) S.a_ready(nxt);
;             if constexpr (SP2) {
;             PG8_LDB(B0, 0, 0); PG8_LDB(B1, 0, 1); PG8_SCHED; PG8_LDA(At, 0, 0); PG8_STAGE(PG8_SA(1, 1), a1 + hstep, voffA);
;             PG8_WAIT_V(8); PG8_WAIT_L(0); PG8_BAR; PG8_MMA(0, 0, At, B0); PG8_MMA(0, 1, At, B1); PG8_BAR; PG8_SCHED;
;             PG8_LDA(At, 0, 1); PG8_STAGE(PG8_SB(0, 0), b2, voffB); PG8_STAGE(PG8_SB(0, 1), b2 + hstep, voffB); PG8_STAGE(PG8_SA(0, 0), a2, voffA);
;             PG8_WAIT_V(8); PG8_WAIT_L(0); PG8_BAR; PG8_MMA(1, 0, At, B0); PG8_MMA(1, 1, At, B1); PG8_BAR; PG8_SCHED;
.LBB0_154:
	s_add_u32 s12, s36, 0xfffc0080
	s_addc_u32 s14, s37, -1
	s_add_i32 s48, 0, 0x10000
	s_cmp_eq_u32 s47, 12
	s_cselect_b32 s45, s15, s14
	s_cselect_b32 s44, s22, s12
	v_add_u32_e32 v2, s48, v149
	s_cselect_b32 s43, s23, s46
	s_cselect_b32 s42, s25, s29
	s_add_i32 s12, 0, 0x14000
	ds_read_b128 v[142:145], v2
	ds_read_b128 v[170:173], v2 offset:1024
	ds_read_b128 v[174:177], v2 offset:2048
	ds_read_b128 v[178:181], v2 offset:3072
	v_add_u32_e32 v2, s12, v149
	ds_read_b128 v[182:185], v2
	ds_read_b128 v[186:189], v2 offset:1024
	ds_read_b128 v[190:193], v2 offset:2048
	ds_read_b128 v[194:197], v2 offset:3072
	v_lshl_add_u64 v[146:147], s[36:37], 0, v[138:139]
	s_add_i32 m0, s7, 0xc000
	ds_read_b128 v[212:215], v151
	ds_read_b128 v[216:219], v151 offset:1024
	ds_read_b128 v[220:223], v151 offset:2048
	ds_read_b128 v[224:227], v151 offset:3072
	ds_read_b128 v[228:231], v151 offset:4096
	ds_read_b128 v[236:239], v151 offset:5120
	ds_read_b128 v[240:243], v151 offset:6144
	ds_read_b128 v[244:247], v151 offset:7168
	global_load_lds_dwordx4 v[146:147], off
	v_lshl_add_u64 v[146:147], s[36:37], 0, v[140:141]
	s_add_i32 m0, s7, 0xe000
	s_nop 0
	global_load_lds_dwordx4 v[146:147], off
	s_waitcnt vmcnt(8)
	s_waitcnt lgkmcnt(0)
	s_barrier
	s_waitcnt lgkmcnt(0)
	v_mfma_f32_16x16x32_bf16 v[128:131], v[142:145], v[212:215], v[128:131]
	v_mfma_f32_16x16x32_bf16 v[124:127], v[174:177], v[212:215], v[124:127]
	v_mfma_f32_16x16x32_bf16 v[112:115], v[142:145], v[220:223], v[112:115]
	v_mfma_f32_16x16x32_bf16 v[108:111], v[174:177], v[220:223], v[108:111]
	v_mfma_f32_16x16x32_bf16 v[96:99], v[142:145], v[228:231], v[96:99]
	v_mfma_f32_16x16x32_bf16 v[92:95], v[174:177], v[228:231], v[92:95]
	v_mfma_f32_16x16x32_bf16 v[80:83], v[142:145], v[240:243], v[80:83]
	v_mfma_f32_16x16x32_bf16 v[76:79], v[174:177], v[240:243], v[76:79]
	v_mfma_f32_16x16x32_bf16 v[128:131], v[170:173], v[216:219], v[128:131]
	v_mfma_f32_16x16x32_bf16 v[124:127], v[178:181], v[216:219], v[124:127]
	v_mfma_f32_16x16x32_bf16 v[112:115], v[170:173], v[224:227], v[112:115]
	v_mfma_f32_16x16x32_bf16 v[108:111], v[178:181], v[224:227], v[108:111]
	v_mfma_f32_16x16x32_bf16 v[96:99], v[170:173], v[236:239], v[96:99]
	v_mfma_f32_16x16x32_bf16 v[92:95], v[178:181], v[236:239], v[92:95]
	v_mfma_f32_16x16x32_bf16 v[80:83], v[170:173], v[244:247], v[80:83]
	v_mfma_f32_16x16x32_bf16 v[76:79], v[178:181], v[244:247], v[76:79]
	v_mfma_f32_16x16x32_bf16 v[120:123], v[182:185], v[212:215], v[120:123]
	v_mfma_f32_16x16x32_bf16 v[116:119], v[190:193], v[212:215], v[116:119]
	v_mfma_f32_16x16x32_bf16 v[104:107], v[182:185], v[220:223], v[104:107]
	v_mfma_f32_16x16x32_bf16 v[100:103], v[190:193], v[220:223], v[100:103]
	v_mfma_f32_16x16x32_bf16 v[88:91], v[182:185], v[228:231], v[88:91]
	v_mfma_f32_16x16x32_bf16 v[84:87], v[190:193], v[228:231], v[84:87]
	v_mfma_f32_16x16x32_bf16 v[72:75], v[182:185], v[240:243], v[72:75]
	v_mfma_f32_16x16x32_bf16 v[68:71], v[190:193], v[240:243], v[68:71]
	v_mfma_f32_16x16x32_bf16 v[120:123], v[186:189], v[216:219], v[120:123]
	v_mfma_f32_16x16x32_bf16 v[116:119], v[194:197], v[216:219], v[116:119]
	v_mfma_f32_16x16x32_bf16 v[104:107], v[186:189], v[224:227], v[104:107]
	v_mfma_f32_16x16x32_bf16 v[100:103], v[194:197], v[224:227], v[100:103]
	v_mfma_f32_16x16x32_bf16 v[88:91], v[186:189], v[236:239], v[88:91]
	v_mfma_f32_16x16x32_bf16 v[84:87], v[194:197], v[236:239], v[84:87]
	v_mfma_f32_16x16x32_bf16 v[72:75], v[186:189], v[244:247], v[72:75]
	v_mfma_f32_16x16x32_bf16 v[68:71], v[194:197], v[244:247], v[68:71]
	s_barrier
	s_add_i32 s14, s48, s6
	v_lshl_add_u64 v[146:147], s[42:43], 0, v[134:135]
	s_mov_b32 m0, s14
	ds_read_b128 v[212:215], v151 offset:16384
	ds_read_b128 v[216:219], v151 offset:17408
	ds_read_b128 v[220:223], v151 offset:18432
	ds_read_b128 v[224:227], v151 offset:19456
	ds_read_b128 v[228:231], v151 offset:20480
	ds_read_b128 v[236:239], v151 offset:21504
	ds_read_b128 v[240:243], v151 offset:22528
	ds_read_b128 v[244:247], v151 offset:23552
	global_load_lds_dwordx4 v[146:147], off
	s_add_i32 m0, s14, 0x2000
	s_add_u32 s48, s42, 0x40000
	v_lshl_add_u64 v[152:153], s[42:43], 0, v[0:1]
	s_addc_u32 s49, s43, 0
	s_add_i32 s12, s12, s6
	global_load_lds_dwordx4 v[152:153], off
	v_lshl_add_u64 v[160:161], s[48:49], 0, v[134:135]
	s_mov_b32 m0, s12
	v_lshl_add_u64 v[198:199], s[44:45], 0, v[132:133]
	global_load_lds_dwordx4 v[160:161], off
	v_lshl_add_u64 v[160:161], s[48:49], 0, v[0:1]
	s_add_i32 m0, s12, 0x2000
	s_nop 0
	global_load_lds_dwordx4 v[160:161], off
	v_lshl_add_u64 v[160:161], s[44:45], 0, v[136:137]
	s_mov_b32 m0, s7
	s_nop 0
	global_load_lds_dwordx4 v[160:161], off
	s_mov_b32 m0, s8
	s_nop 0
	global_load_lds_dwordx4 v[198:199], off
	s_waitcnt vmcnt(8)
	s_waitcnt lgkmcnt(0)
	s_barrier
; #define PG8_STAGE(bufoff, gbase, voff) do { _Pragma("unroll") for (int _i = 0; _i < 2; ++_i) \
;         __builtin_amdgcn_global_load_lds((const unsigned*)((const char*)(gbase) + (voff)[_i]), (PG8_LAS unsigned*)(lds + (bufoff) + ldsw + _i * 8192), 16, 0, 0); } while (0)
; #define PG8_LDA(dst, b, h) do { _Pragma("unroll") for (int m = 0; m < 4; ++m) _Pragma("unroll") for (int k = 0; k < 2; ++k) dst[m][k] = *(const PG8_LAS bf16x8*)(lds + PG8_SA(b, h) + aoff + m * 2048 + k * 1024); } while (0)
; #define PG8_LDB(dst, b, h) do { _Pragma("unroll") for (int n = 0; n < 2; ++n) _Pragma("unroll") for (int k = 0; k < 2; ++k) dst[n][k] = *(const PG8_LAS bf16x8*)(lds + PG8_SB(b, h) + boff + n * 2048 + k * 1024); } while (0)
; #define PG8_MMA(ai, bj, At, Bt) do { __builtin_amdgcn_s_setprio(1); _Pragma("unroll") for (int m = 0; m < 4; ++m) _Pragma("unroll") for (int n = 0; n < 2; ++n) _Pragma("unroll") for (int k = 0; k < 2; ++k) \
;         acc[ai][bj][m][n] = __builtin_amdgcn_mfma_f32_16x16x32_bf16(Bt[n][k], At[m][k], acc[ai][bj][m][n], 0, 0, 0); __builtin_amdgcn_s_setprio(0); } while (0)
; #define PG8_WAIT_V(n) asm volatile("s_waitcnt vmcnt(" #n ")" ::: "memory")
; #define PG8_WAIT_L(n) asm volatile("s_waitcnt lgkmcnt(" #n ")" ::: "memory")
; #define PG8_BAR __builtin_amdgcn_s_barrier()
; #define PG8_SCHED __builtin_amdgcn_sched_barrier(0)
; template <class Epi, class Sched, bool ALIGN_EPI = false, bool SP2 = false>
; __device__ __forceinline__ void gemm_phase(PG8_LAS unsigned char* lds, const Gemm g, const Sched& S, const Epi& E, const int tid) {
;     ...
;             PG8_WAIT_V(8); PG8_WAIT_L(0); PG8_BAR; PG8_MMA(1, 0, At, B0); PG8_MMA(1, 1, At, B1); PG8_BAR; PG8_SCHED;
;             PG8_LDB(B0, 1, 0); PG8_LDB(B1, 1, 1); PG8_SCHED; PG8_LDA(At, 1, 0); PG8_STAGE(PG8_SA(0, 1), a2 + hstep, voffA);
;             PG8_WAIT_V(8); PG8_WAIT_L(0); PG8_BAR; PG8_MMA(0, 0, At, B0); PG8_MMA(0, 1, At, B1); PG8_BAR; PG8_SCHED;
	s_waitcnt lgkmcnt(0)
	v_mfma_f32_16x16x32_bf16 v[64:67], v[142:145], v[212:215], v[64:67]
	v_mfma_f32_16x16x32_bf16 v[60:63], v[174:177], v[212:215], v[60:63]
	v_mfma_f32_16x16x32_bf16 v[48:51], v[142:145], v[220:223], v[48:51]
	v_mfma_f32_16x16x32_bf16 v[44:47], v[174:177], v[220:223], v[44:47]
	v_mfma_f32_16x16x32_bf16 v[32:35], v[142:145], v[228:231], v[32:35]
	v_mfma_f32_16x16x32_bf16 v[28:31], v[174:177], v[228:231], v[28:31]
	v_mfma_f32_16x16x32_bf16 v[16:19], v[142:145], v[240:243], v[16:19]
	v_mfma_f32_16x16x32_bf16 v[12:15], v[174:177], v[240:243], v[12:15]
	v_mfma_f32_16x16x32_bf16 v[64:67], v[170:173], v[216:219], v[64:67]
	v_mfma_f32_16x16x32_bf16 v[60:63], v[178:181], v[216:219], v[60:63]
	v_mfma_f32_16x16x32_bf16 v[48:51], v[170:173], v[224:227], v[48:51]
	v_mfma_f32_16x16x32_bf16 v[44:47], v[178:181], v[224:227], v[44:47]
	v_mfma_f32_16x16x32_bf16 v[32:35], v[170:173], v[236:239], v[32:35]
	v_mfma_f32_16x16x32_bf16 v[28:31], v[178:181], v[236:239], v[28:31]
	v_mfma_f32_16x16x32_bf16 v[16:19], v[170:173], v[244:247], v[16:19]
	v_mfma_f32_16x16x32_bf16 v[12:15], v[178:181], v[244:247], v[12:15]
	v_mfma_f32_16x16x32_bf16 v[56:59], v[182:185], v[212:215], v[56:59]
	v_mfma_f32_16x16x32_bf16 v[52:55], v[190:193], v[212:215], v[52:55]
	v_mfma_f32_16x16x32_bf16 v[40:43], v[182:185], v[220:223], v[40:43]
	v_mfma_f32_16x16x32_bf16 v[36:39], v[190:193], v[220:223], v[36:39]
	v_mfma_f32_16x16x32_bf16 v[24:27], v[182:185], v[228:231], v[24:27]
	v_mfma_f32_16x16x32_bf16 v[20:23], v[190:193], v[228:231], v[20:23]
	v_mfma_f32_16x16x32_bf16 v[8:11], v[182:185], v[240:243], v[8:11]
	v_mfma_f32_16x16x32_bf16 v[4:7], v[190:193], v[240:243], v[4:7]
	v_mfma_f32_16x16x32_bf16 v[56:59], v[186:189], v[216:219], v[56:59]
	v_mfma_f32_16x16x32_bf16 v[52:55], v[194:197], v[216:219], v[52:55]
	v_mfma_f32_16x16x32_bf16 v[40:43], v[186:189], v[224:227], v[40:43]
	v_mfma_f32_16x16x32_bf16 v[36:39], v[194:197], v[224:227], v[36:39]
	v_mfma_f32_16x16x32_bf16 v[24:27], v[186:189], v[236:239], v[24:27]
	v_mfma_f32_16x16x32_bf16 v[20:23], v[194:197], v[236:239], v[20:23]
	v_mfma_f32_16x16x32_bf16 v[8:11], v[186:189], v[244:247], v[8:11]
	v_mfma_f32_16x16x32_bf16 v[4:7], v[194:197], v[244:247], v[4:7]
	s_barrier
	s_add_i32 s12, 0, 0x18000
	v_add_u32_e32 v2, s12, v149
	s_add_i32 s14, 0, 0x1c000
	ds_read_b128 v[142:145], v2
	ds_read_b128 v[170:173], v2 offset:1024
	ds_read_b128 v[174:177], v2 offset:2048
	ds_read_b128 v[178:181], v2 offset:3072
	v_add_u32_e32 v2, s14, v149
	ds_read_b128 v[182:185], v2
	ds_read_b128 v[186:189], v2 offset:1024
	ds_read_b128 v[190:193], v2 offset:2048
	ds_read_b128 v[194:197], v2 offset:3072
	s_add_u32 s44, s44, 0x40000
	s_addc_u32 s45, s45, 0
	s_mov_b32 m0, s9
	v_lshl_add_u64 v[248:249], s[44:45], 0, v[136:137]
	ds_read_b128 v[212:215], v151 offset:32768
	ds_read_b128 v[216:219], v151 offset:33792
	ds_read_b128 v[220:223], v151 offset:34816
	ds_read_b128 v[224:227], v151 offset:35840
	ds_read_b128 v[228:231], v151 offset:36864
	ds_read_b128 v[236:239], v151 offset:37888
	ds_read_b128 v[240:243], v151 offset:38912
	ds_read_b128 v[244:247], v151 offset:39936
	global_load_lds_dwordx4 v[248:249], off
	v_lshl_add_u64 v[248:249], s[44:45], 0, v[132:133]
	s_mov_b32 m0, s30
	s_nop 0
	global_load_lds_dwordx4 v[248:249], off
	s_waitcnt vmcnt(8)
	s_waitcnt lgkmcnt(0)
	s_barrier
	s_waitcnt lgkmcnt(0)
	v_mfma_f32_16x16x32_bf16 v[128:131], v[142:145], v[212:215], v[128:131]
	v_mfma_f32_16x16x32_bf16 v[124:127], v[174:177], v[212:215], v[124:127]
	v_mfma_f32_16x16x32_bf16 v[112:115], v[142:145], v[220:223], v[112:115]
	v_mfma_f32_16x16x32_bf16 v[108:111], v[174:177], v[220:223], v[108:111]
	v_mfma_f32_16x16x32_bf16 v[96:99], v[142:145], v[228:231], v[96:99]
	v_mfma_f32_16x16x32_bf16 v[92:95], v[174:177], v[228:231], v[92:95]
	v_mfma_f32_16x16x32_bf16 v[80:83], v[142:145], v[240:243], v[80:83]
	v_mfma_f32_16x16x32_bf16 v[76:79], v[174:177], v[240:243], v[76:79]
	v_mfma_f32_16x16x32_bf16 v[128:131], v[170:173], v[216:219], v[128:131]
	v_mfma_f32_16x16x32_bf16 v[124:127], v[178:181], v[216:219], v[124:127]
	v_mfma_f32_16x16x32_bf16 v[112:115], v[170:173], v[224:227], v[112:115]
	v_mfma_f32_16x16x32_bf16 v[108:111], v[178:181], v[224:227], v[108:111]
	v_mfma_f32_16x16x32_bf16 v[96:99], v[170:173], v[236:239], v[96:99]
	v_mfma_f32_16x16x32_bf16 v[92:95], v[178:181], v[236:239], v[92:95]
	v_mfma_f32_16x16x32_bf16 v[80:83], v[170:173], v[244:247], v[80:83]
	v_mfma_f32_16x16x32_bf16 v[76:79], v[178:181], v[244:247], v[76:79]
	v_mfma_f32_16x16x32_bf16 v[120:123], v[182:185], v[212:215], v[120:123]
	v_mfma_f32_16x16x32_bf16 v[116:119], v[190:193], v[212:215], v[116:119]
	v_mfma_f32_16x16x32_bf16 v[104:107], v[182:185], v[220:223], v[104:107]
	v_mfma_f32_16x16x32_bf16 v[100:103], v[190:193], v[220:223], v[100:103]
	v_mfma_f32_16x16x32_bf16 v[88:91], v[182:185], v[228:231], v[88:91]
	v_mfma_f32_16x16x32_bf16 v[84:87], v[190:193], v[228:231], v[84:87]
	v_mfma_f32_16x16x32_bf16 v[72:75], v[182:185], v[240:243], v[72:75]
	v_mfma_f32_16x16x32_bf16 v[68:71], v[190:193], v[240:243], v[68:71]
	v_mfma_f32_16x16x32_bf16 v[120:123], v[186:189], v[216:219], v[120:123]
	v_mfma_f32_16x16x32_bf16 v[116:119], v[194:197], v[216:219], v[116:119]
	v_mfma_f32_16x16x32_bf16 v[104:107], v[186:189], v[224:227], v[104:107]
	v_mfma_f32_16x16x32_bf16 v[100:103], v[194:197], v[224:227], v[100:103]
	v_mfma_f32_16x16x32_bf16 v[88:91], v[186:189], v[236:239], v[88:91]
	v_mfma_f32_16x16x32_bf16 v[84:87], v[194:197], v[236:239], v[84:87]
	v_mfma_f32_16x16x32_bf16 v[72:75], v[186:189], v[244:247], v[72:75]
	v_mfma_f32_16x16x32_bf16 v[68:71], v[194:197], v[244:247], v[68:71]
	s_barrier
; #define PG8_STAGE(bufoff, gbase, voff) do { _Pragma("unroll") for (int _i = 0; _i < 2; ++_i) \
;         __builtin_amdgcn_global_load_lds((const unsigned*)((const char*)(gbase) + (voff)[_i]), (PG8_LAS unsigned*)(lds + (bufoff) + ldsw + _i * 8192), 16, 0, 0); } while (0)
; #define PG8_LDA(dst, b, h) do { _Pragma("unroll") for (int m = 0; m < 4; ++m) _Pragma("unroll") for (int k = 0; k < 2; ++k) dst[m][k] = *(const PG8_LAS bf16x8*)(lds + PG8_SA(b, h) + aoff + m * 2048 + k * 1024); } while (0)
; #define PG8_MMA(ai, bj, At, Bt) do { __builtin_amdgcn_s_setprio(1); _Pragma("unroll") for (int m = 0; m < 4; ++m) _Pragma("unroll") for (int n = 0; n < 2; ++n) _Pragma("unroll") for (int k = 0; k < 2; ++k) \
;         acc[ai][bj][m][n] = __builtin_amdgcn_mfma_f32_16x16x32_bf16(Bt[n][k], At[m][k], acc[ai][bj][m][n], 0, 0, 0); __builtin_amdgcn_s_setprio(0); } while (0)
; #define PG8_WAIT_V(n) asm volatile("s_waitcnt vmcnt(" #n ")" ::: "memory")
; #define PG8_WAIT_L(n) asm volatile("s_waitcnt lgkmcnt(" #n ")" ::: "memory")
; #define PG8_BAR __builtin_amdgcn_s_barrier()
; #define PG8_SCHED __builtin_amdgcn_sched_barrier(0)
; template <class Epi, class Sched, bool ALIGN_EPI = false, bool SP2 = false>
; __device__ __forceinline__ void gemm_phase(PG8_LAS unsigned char* lds, const Gemm g, const Sched& S, const Epi& E, const int tid) {
;     ...
;         for (int t = 0; t < nt; t += 2) {
;     ...
;             PG8_LDA(At, 1, 1); PG8_STAGE(PG8_SB(1, 0), b3, voffB); PG8_STAGE(PG8_SB(1, 1), b3 + hstep, voffB); PG8_STAGE(PG8_SA(1, 0), a3, voffA);
;             PG8_WAIT_V(8); PG8_WAIT_L(0); PG8_BAR; PG8_MMA(1, 0, At, B0); PG8_MMA(1, 1, At, B1); PG8_BAR; PG8_SCHED;
;     ...
;         if constexpr (ALIGN_EPI) { if (wr == 0) PG8_BAR; }
	s_add_i32 s12, s12, s6
	v_lshl_add_u64 v[146:147], v[146:147], 0, s[18:19]
	s_mov_b32 m0, s12
	ds_read_b128 v[212:215], v151 offset:49152
	ds_read_b128 v[216:219], v151 offset:50176
	ds_read_b128 v[220:223], v151 offset:51200
	ds_read_b128 v[224:227], v151 offset:52224
	ds_read_b128 v[228:231], v151 offset:53248
	ds_read_b128 v[236:239], v151 offset:54272
	ds_read_b128 v[240:243], v151 offset:55296
	ds_read_b128 v[244:247], v151 offset:56320
	global_load_lds_dwordx4 v[146:147], off
	s_add_i32 m0, s12, 0x2000
	s_add_u32 s42, s42, 0x40080
	v_lshl_add_u64 v[146:147], v[152:153], 0, s[18:19]
	s_addc_u32 s43, s43, 0
	s_add_i32 s12, s14, s6
	global_load_lds_dwordx4 v[146:147], off
	v_lshl_add_u64 v[146:147], s[42:43], 0, v[134:135]
	s_mov_b32 m0, s12
	s_nop 0
	global_load_lds_dwordx4 v[146:147], off
	v_lshl_add_u64 v[146:147], s[42:43], 0, v[0:1]
	s_add_i32 m0, s12, 0x2000
	s_nop 0
	global_load_lds_dwordx4 v[146:147], off
	v_lshl_add_u64 v[146:147], v[160:161], 0, s[18:19]
	s_mov_b32 m0, s54
	s_nop 0
	global_load_lds_dwordx4 v[146:147], off
	v_lshl_add_u64 v[146:147], v[198:199], 0, s[18:19]
	s_mov_b32 m0, s55
	s_nop 0
	global_load_lds_dwordx4 v[146:147], off
	s_waitcnt vmcnt(8)
	s_waitcnt lgkmcnt(0)
	s_barrier
	s_waitcnt lgkmcnt(0)
	v_mfma_f32_16x16x32_bf16 v[64:67], v[142:145], v[212:215], v[64:67]
	v_mfma_f32_16x16x32_bf16 v[60:63], v[174:177], v[212:215], v[60:63]
	v_mfma_f32_16x16x32_bf16 v[48:51], v[142:145], v[220:223], v[48:51]
	v_mfma_f32_16x16x32_bf16 v[44:47], v[174:177], v[220:223], v[44:47]
	v_mfma_f32_16x16x32_bf16 v[32:35], v[142:145], v[228:231], v[32:35]
	v_mfma_f32_16x16x32_bf16 v[28:31], v[174:177], v[228:231], v[28:31]
	v_mfma_f32_16x16x32_bf16 v[16:19], v[142:145], v[240:243], v[16:19]
	v_mfma_f32_16x16x32_bf16 v[12:15], v[174:177], v[240:243], v[12:15]
	v_mfma_f32_16x16x32_bf16 v[64:67], v[170:173], v[216:219], v[64:67]
	v_mfma_f32_16x16x32_bf16 v[60:63], v[178:181], v[216:219], v[60:63]
	v_mfma_f32_16x16x32_bf16 v[48:51], v[170:173], v[224:227], v[48:51]
	v_mfma_f32_16x16x32_bf16 v[44:47], v[178:181], v[224:227], v[44:47]
	v_mfma_f32_16x16x32_bf16 v[32:35], v[170:173], v[236:239], v[32:35]
	v_mfma_f32_16x16x32_bf16 v[28:31], v[178:181], v[236:239], v[28:31]
	v_mfma_f32_16x16x32_bf16 v[16:19], v[170:173], v[244:247], v[16:19]
	v_mfma_f32_16x16x32_bf16 v[12:15], v[178:181], v[244:247], v[12:15]
	v_mfma_f32_16x16x32_bf16 v[56:59], v[182:185], v[212:215], v[56:59]
	v_mfma_f32_16x16x32_bf16 v[52:55], v[190:193], v[212:215], v[52:55]
	v_mfma_f32_16x16x32_bf16 v[40:43], v[182:185], v[220:223], v[40:43]
	v_mfma_f32_16x16x32_bf16 v[36:39], v[190:193], v[220:223], v[36:39]
	v_mfma_f32_16x16x32_bf16 v[24:27], v[182:185], v[228:231], v[24:27]
	v_mfma_f32_16x16x32_bf16 v[20:23], v[190:193], v[228:231], v[20:23]
	v_mfma_f32_16x16x32_bf16 v[8:11], v[182:185], v[240:243], v[8:11]
	v_mfma_f32_16x16x32_bf16 v[4:7], v[190:193], v[240:243], v[4:7]
	v_mfma_f32_16x16x32_bf16 v[56:59], v[186:189], v[216:219], v[56:59]
	v_mfma_f32_16x16x32_bf16 v[52:55], v[194:197], v[216:219], v[52:55]
	v_mfma_f32_16x16x32_bf16 v[40:43], v[186:189], v[224:227], v[40:43]
	v_mfma_f32_16x16x32_bf16 v[36:39], v[194:197], v[224:227], v[36:39]
	v_mfma_f32_16x16x32_bf16 v[24:27], v[186:189], v[236:239], v[24:27]
	v_mfma_f32_16x16x32_bf16 v[20:23], v[194:197], v[236:239], v[20:23]
	v_mfma_f32_16x16x32_bf16 v[8:11], v[186:189], v[244:247], v[8:11]
	v_mfma_f32_16x16x32_bf16 v[4:7], v[194:197], v[244:247], v[4:7]
	s_barrier
	s_add_i32 s47, s47, 2
	s_add_u32 s36, s36, 0x100
	s_addc_u32 s37, s37, 0
	s_add_u32 s29, s29, 0x100
	s_addc_u32 s46, s46, 0
	s_cmp_gt_u32 s47, 13
	s_cbranch_scc0 .LBB0_154
	s_and_b64 vcc, exec, s[20:21]
	s_cbranch_vccz .LBB0_157
	s_barrier

; #define PG8_STAGE(bufoff, gbase, voff) do { _Pragma("unroll") for (int _i = 0; _i < 2; ++_i) \
;         __builtin_amdgcn_global_load_lds((const unsigned*)((const char*)(gbase) + (voff)[_i]), (PG8_LAS unsigned*)(lds + (bufoff) + ldsw + _i * 8192), 16, 0, 0); } while (0)
; #define PG8_LDA(dst, b, h) do { _Pragma("unroll") for (int m = 0; m < 4; ++m) _Pragma("unroll") for (int k = 0; k < 2; ++k) dst[m][k] = *(const PG8_LAS bf16x8*)(lds + PG8_SA(b, h) + aoff + m * 2048 + k * 1024); } while (0)
; #define PG8_LDB(dst, b, h) do { _Pragma("unroll") for (int n = 0; n < 2; ++n) _Pragma("unroll") for (int k = 0; k < 2; ++k) dst[n][k] = *(const PG8_LAS bf16x8*)(lds + PG8_SB(b, h) + boff + n * 2048 + k * 1024); } while (0)
; #define PG8_MMA(ai, bj, At, Bt) do { __builtin_amdgcn_s_setprio(1); _Pragma("unroll") for (int m = 0; m < 4; ++m) _Pragma("unroll") for (int n = 0; n < 2; ++n) _Pragma("unroll") for (int k = 0; k < 2; ++k) \
;         acc[ai][bj][m][n] = __builtin_amdgcn_mfma_f32_16x16x32_bf16(Bt[n][k], At[m][k], acc[ai][bj][m][n], 0, 0, 0); __builtin_amdgcn_s_setprio(0); } while (0)
; #define PG8_WAIT_V(n) asm volatile("s_waitcnt vmcnt(" #n ")" ::: "memory")
; #define PG8_WAIT_L(n) asm volatile("s_waitcnt lgkmcnt(" #n ")" ::: "memory")
; template <class Epi, class Sched, bool ALIGN_EPI = false, bool SP2 = false>
; __device__ __forceinline__ void gemm_phase(PG8_LAS unsigned char* lds, const Gemm g, const Sched& S, const Epi& E, const int tid) {
;     ...
;             const bool last = (t == nt - 2);
;             const char* a1 = cA + (size_t)(t + 1) * kstep;
;             const char* a2 = last ? nA : cA + (size_t)(t + 2) * kstep; const char* b2 = last ? nB : cB + (size_t)(t + 2) * kstep;
;             const char* a3 = a2 + kstep; const char* b3 = b2 + kstep;
;             if (last && has_next) S.a_ready(nxt);
;             if constexpr (SP2) {
;             PG8_LDB(B0, 0, 0); PG8_LDB(B1, 0, 1); PG8_SCHED; PG8_LDA(At, 0, 0); PG8_STAGE(PG8_SA(1, 1), a1 + hstep, voffA);
;             PG8_WAIT_V(8); PG8_WAIT_L(0); PG8_BAR; PG8_MMA(0, 0, At, B0); PG8_MMA(0, 1, At, B1); PG8_BAR; PG8_SCHED;
;             PG8_LDA(At, 0, 1); PG8_STAGE(PG8_SB(0, 0), b2, voffB); PG8_STAGE(PG8_SB(0, 1), b2 + hstep, voffB); PG8_STAGE(PG8_SA(0, 0), a2, voffA);
;             PG8_WAIT_V(8); PG8_WAIT_L(0); PG8_BAR; PG8_MMA(1, 0, At, B0); PG8_MMA(1, 1, At, B1); PG8_BAR; PG8_SCHED;
.LBB0_269:
	s_add_u32 s12, s24, 0xfff80080
	s_addc_u32 s14, s25, -1
	s_add_i32 s42, 0, 0x10000
	s_cmp_eq_u32 s23, 28
	s_cselect_b32 s37, s8, s14
	s_cselect_b32 s36, s9, s12
	v_add_u32_e32 v2, s42, v170
	s_cselect_b32 s29, s13, s22
	s_cselect_b32 s28, s15, s21
	s_add_i32 s12, 0, 0x14000
	ds_read_b128 v[132:135], v2
	ds_read_b128 v[136:139], v2 offset:1024
	ds_read_b128 v[150:153], v2 offset:2048
	ds_read_b128 v[174:177], v2 offset:3072
	v_add_u32_e32 v2, s12, v170
	ds_read_b128 v[178:181], v2
	ds_read_b128 v[182:185], v2 offset:1024
	ds_read_b128 v[186:189], v2 offset:2048
	ds_read_b128 v[190:193], v2 offset:3072
	v_lshl_add_u64 v[160:161], s[24:25], 0, v[146:147]
	s_add_i32 m0, s54, 0xc000
	ds_read_b128 v[194:197], v172
	ds_read_b128 v[212:215], v172 offset:1024
	ds_read_b128 v[216:219], v172 offset:2048
	ds_read_b128 v[220:223], v172 offset:3072
	ds_read_b128 v[224:227], v172 offset:4096
	ds_read_b128 v[228:231], v172 offset:5120
	ds_read_b128 v[236:239], v172 offset:6144
	ds_read_b128 v[240:243], v172 offset:7168
	global_load_lds_dwordx4 v[160:161], off
	v_lshl_add_u64 v[160:161], s[24:25], 0, v[148:149]
	s_add_i32 m0, s54, 0xe000
	s_nop 0
	global_load_lds_dwordx4 v[160:161], off
	s_waitcnt vmcnt(8)
	s_waitcnt lgkmcnt(0)
	s_barrier
	s_waitcnt lgkmcnt(0)
	v_mfma_f32_16x16x32_bf16 v[128:131], v[132:135], v[194:197], v[128:131]
	v_mfma_f32_16x16x32_bf16 v[124:127], v[150:153], v[194:197], v[124:127]
	v_mfma_f32_16x16x32_bf16 v[112:115], v[132:135], v[216:219], v[112:115]
	v_mfma_f32_16x16x32_bf16 v[108:111], v[150:153], v[216:219], v[108:111]
	v_mfma_f32_16x16x32_bf16 v[96:99], v[132:135], v[224:227], v[96:99]
	v_mfma_f32_16x16x32_bf16 v[92:95], v[150:153], v[224:227], v[92:95]
	v_mfma_f32_16x16x32_bf16 v[80:83], v[132:135], v[236:239], v[80:83]
	v_mfma_f32_16x16x32_bf16 v[76:79], v[150:153], v[236:239], v[76:79]
	v_mfma_f32_16x16x32_bf16 v[128:131], v[136:139], v[212:215], v[128:131]
	v_mfma_f32_16x16x32_bf16 v[124:127], v[174:177], v[212:215], v[124:127]
	v_mfma_f32_16x16x32_bf16 v[112:115], v[136:139], v[220:223], v[112:115]
	v_mfma_f32_16x16x32_bf16 v[108:111], v[174:177], v[220:223], v[108:111]
	v_mfma_f32_16x16x32_bf16 v[96:99], v[136:139], v[228:231], v[96:99]
	v_mfma_f32_16x16x32_bf16 v[92:95], v[174:177], v[228:231], v[92:95]
	v_mfma_f32_16x16x32_bf16 v[80:83], v[136:139], v[240:243], v[80:83]
	v_mfma_f32_16x16x32_bf16 v[76:79], v[174:177], v[240:243], v[76:79]
	v_mfma_f32_16x16x32_bf16 v[120:123], v[178:181], v[194:197], v[120:123]
	v_mfma_f32_16x16x32_bf16 v[116:119], v[186:189], v[194:197], v[116:119]
	v_mfma_f32_16x16x32_bf16 v[104:107], v[178:181], v[216:219], v[104:107]
	v_mfma_f32_16x16x32_bf16 v[100:103], v[186:189], v[216:219], v[100:103]
	v_mfma_f32_16x16x32_bf16 v[88:91], v[178:181], v[224:227], v[88:91]
	v_mfma_f32_16x16x32_bf16 v[84:87], v[186:189], v[224:227], v[84:87]
	v_mfma_f32_16x16x32_bf16 v[72:75], v[178:181], v[236:239], v[72:75]
	v_mfma_f32_16x16x32_bf16 v[68:71], v[186:189], v[236:239], v[68:71]
	v_mfma_f32_16x16x32_bf16 v[120:123], v[182:185], v[212:215], v[120:123]
	v_mfma_f32_16x16x32_bf16 v[116:119], v[190:193], v[212:215], v[116:119]
	v_mfma_f32_16x16x32_bf16 v[104:107], v[182:185], v[220:223], v[104:107]
	v_mfma_f32_16x16x32_bf16 v[100:103], v[190:193], v[220:223], v[100:103]
	v_mfma_f32_16x16x32_bf16 v[88:91], v[182:185], v[228:231], v[88:91]
	v_mfma_f32_16x16x32_bf16 v[84:87], v[190:193], v[228:231], v[84:87]
	v_mfma_f32_16x16x32_bf16 v[72:75], v[182:185], v[240:243], v[72:75]
	v_mfma_f32_16x16x32_bf16 v[68:71], v[190:193], v[240:243], v[68:71]
	s_barrier
	s_add_i32 s14, s42, s53
	v_lshl_add_u64 v[160:161], s[28:29], 0, v[142:143]
	s_mov_b32 m0, s14
	ds_read_b128 v[194:197], v172 offset:16384
	ds_read_b128 v[212:215], v172 offset:17408
	ds_read_b128 v[216:219], v172 offset:18432
	ds_read_b128 v[220:223], v172 offset:19456
	ds_read_b128 v[224:227], v172 offset:20480
	ds_read_b128 v[228:231], v172 offset:21504
	ds_read_b128 v[236:239], v172 offset:22528
	ds_read_b128 v[240:243], v172 offset:23552
	global_load_lds_dwordx4 v[160:161], off
	s_add_i32 m0, s14, 0x2000
	s_add_u32 s42, s28, 0x80000
	v_lshl_add_u64 v[198:199], s[28:29], 0, v[0:1]
	s_addc_u32 s43, s29, 0
	s_add_i32 s12, s12, s53
	global_load_lds_dwordx4 v[198:199], off
	v_lshl_add_u64 v[244:245], s[42:43], 0, v[142:143]
	s_mov_b32 m0, s12
	v_lshl_add_u64 v[246:247], s[36:37], 0, v[140:141]
	global_load_lds_dwordx4 v[244:245], off
	v_lshl_add_u64 v[244:245], s[42:43], 0, v[0:1]
	s_add_i32 m0, s12, 0x2000
	s_nop 0
	global_load_lds_dwordx4 v[244:245], off
	v_lshl_add_u64 v[244:245], s[36:37], 0, v[144:145]
	s_mov_b32 m0, s54
	s_nop 0
	global_load_lds_dwordx4 v[244:245], off
	s_mov_b32 m0, s55
	s_nop 0
	global_load_lds_dwordx4 v[246:247], off
	s_waitcnt vmcnt(8)
	s_waitcnt lgkmcnt(0)
	s_barrier
; #define PG8_STAGE(bufoff, gbase, voff) do { _Pragma("unroll") for (int _i = 0; _i < 2; ++_i) \
;         __builtin_amdgcn_global_load_lds((const unsigned*)((const char*)(gbase) + (voff)[_i]), (PG8_LAS unsigned*)(lds + (bufoff) + ldsw + _i * 8192), 16, 0, 0); } while (0)
; #define PG8_LDA(dst, b, h) do { _Pragma("unroll") for (int m = 0; m < 4; ++m) _Pragma("unroll") for (int k = 0; k < 2; ++k) dst[m][k] = *(const PG8_LAS bf16x8*)(lds + PG8_SA(b, h) + aoff + m * 2048 + k * 1024); } while (0)
; #define PG8_LDB(dst, b, h) do { _Pragma("unroll") for (int n = 0; n < 2; ++n) _Pragma("unroll") for (int k = 0; k < 2; ++k) dst[n][k] = *(const PG8_LAS bf16x8*)(lds + PG8_SB(b, h) + boff + n * 2048 + k * 1024); } while (0)
; #define PG8_MMA(ai, bj, At, Bt) do { __builtin_amdgcn_s_setprio(1); _Pragma("unroll") for (int m = 0; m < 4; ++m) _Pragma("unroll") for (int n = 0; n < 2; ++n) _Pragma("unroll") for (int k = 0; k < 2; ++k) \
;         acc[ai][bj][m][n] = __builtin_amdgcn_mfma_f32_16x16x32_bf16(Bt[n][k], At[m][k], acc[ai][bj][m][n], 0, 0, 0); __builtin_amdgcn_s_setprio(0); } while (0)
; #define PG8_WAIT_V(n) asm volatile("s_waitcnt vmcnt(" #n ")" ::: "memory")
; #define PG8_WAIT_L(n) asm volatile("s_waitcnt lgkmcnt(" #n ")" ::: "memory")
; #define PG8_BAR __builtin_amdgcn_s_barrier()
; #define PG8_SCHED __builtin_amdgcn_sched_barrier(0)
; template <class Epi, class Sched, bool ALIGN_EPI = false, bool SP2 = false>
; __device__ __forceinline__ void gemm_phase(PG8_LAS unsigned char* lds, const Gemm g, const Sched& S, const Epi& E, const int tid) {
;     ...
;             PG8_WAIT_V(8); PG8_WAIT_L(0); PG8_BAR; PG8_MMA(1, 0, At, B0); PG8_MMA(1, 1, At, B1); PG8_BAR; PG8_SCHED;
;             PG8_LDB(B0, 1, 0); PG8_LDB(B1, 1, 1); PG8_SCHED; PG8_LDA(At, 1, 0); PG8_STAGE(PG8_SA(0, 1), a2 + hstep, voffA);
;             PG8_WAIT_V(8); PG8_WAIT_L(0); PG8_BAR; PG8_MMA(0, 0, At, B0); PG8_MMA(0, 1, At, B1); PG8_BAR; PG8_SCHED;
	s_waitcnt lgkmcnt(0)
	v_mfma_f32_16x16x32_bf16 v[64:67], v[132:135], v[194:197], v[64:67]
	v_mfma_f32_16x16x32_bf16 v[60:63], v[150:153], v[194:197], v[60:63]
	v_mfma_f32_16x16x32_bf16 v[48:51], v[132:135], v[216:219], v[48:51]
	v_mfma_f32_16x16x32_bf16 v[44:47], v[150:153], v[216:219], v[44:47]
	v_mfma_f32_16x16x32_bf16 v[32:35], v[132:135], v[224:227], v[32:35]
	v_mfma_f32_16x16x32_bf16 v[28:31], v[150:153], v[224:227], v[28:31]
	v_mfma_f32_16x16x32_bf16 v[16:19], v[132:135], v[236:239], v[16:19]
	v_mfma_f32_16x16x32_bf16 v[12:15], v[150:153], v[236:239], v[12:15]
	v_mfma_f32_16x16x32_bf16 v[64:67], v[136:139], v[212:215], v[64:67]
	v_mfma_f32_16x16x32_bf16 v[60:63], v[174:177], v[212:215], v[60:63]
	v_mfma_f32_16x16x32_bf16 v[48:51], v[136:139], v[220:223], v[48:51]
	v_mfma_f32_16x16x32_bf16 v[44:47], v[174:177], v[220:223], v[44:47]
	v_mfma_f32_16x16x32_bf16 v[32:35], v[136:139], v[228:231], v[32:35]
	v_mfma_f32_16x16x32_bf16 v[28:31], v[174:177], v[228:231], v[28:31]
	v_mfma_f32_16x16x32_bf16 v[16:19], v[136:139], v[240:243], v[16:19]
	v_mfma_f32_16x16x32_bf16 v[12:15], v[174:177], v[240:243], v[12:15]
	v_mfma_f32_16x16x32_bf16 v[56:59], v[178:181], v[194:197], v[56:59]
	v_mfma_f32_16x16x32_bf16 v[52:55], v[186:189], v[194:197], v[52:55]
	v_mfma_f32_16x16x32_bf16 v[40:43], v[178:181], v[216:219], v[40:43]
	v_mfma_f32_16x16x32_bf16 v[36:39], v[186:189], v[216:219], v[36:39]
	v_mfma_f32_16x16x32_bf16 v[24:27], v[178:181], v[224:227], v[24:27]
	v_mfma_f32_16x16x32_bf16 v[20:23], v[186:189], v[224:227], v[20:23]
	v_mfma_f32_16x16x32_bf16 v[8:11], v[178:181], v[236:239], v[8:11]
	v_mfma_f32_16x16x32_bf16 v[4:7], v[186:189], v[236:239], v[4:7]
	v_mfma_f32_16x16x32_bf16 v[56:59], v[182:185], v[212:215], v[56:59]
	v_mfma_f32_16x16x32_bf16 v[52:55], v[190:193], v[212:215], v[52:55]
	v_mfma_f32_16x16x32_bf16 v[40:43], v[182:185], v[220:223], v[40:43]
	v_mfma_f32_16x16x32_bf16 v[36:39], v[190:193], v[220:223], v[36:39]
	v_mfma_f32_16x16x32_bf16 v[24:27], v[182:185], v[228:231], v[24:27]
	v_mfma_f32_16x16x32_bf16 v[20:23], v[190:193], v[228:231], v[20:23]
	v_mfma_f32_16x16x32_bf16 v[8:11], v[182:185], v[240:243], v[8:11]
	v_mfma_f32_16x16x32_bf16 v[4:7], v[190:193], v[240:243], v[4:7]
	s_barrier
	s_add_i32 s12, 0, 0x18000
	v_add_u32_e32 v2, s12, v170
	s_add_i32 s14, 0, 0x1c000
	ds_read_b128 v[132:135], v2
	ds_read_b128 v[136:139], v2 offset:1024
	ds_read_b128 v[150:153], v2 offset:2048
	ds_read_b128 v[174:177], v2 offset:3072
	v_add_u32_e32 v2, s14, v170
	ds_read_b128 v[178:181], v2
	ds_read_b128 v[182:185], v2 offset:1024
	ds_read_b128 v[186:189], v2 offset:2048
	ds_read_b128 v[190:193], v2 offset:3072
	s_add_u32 s36, s36, 0x80000
	s_addc_u32 s37, s37, 0
	s_mov_b32 m0, s93
	v_lshl_add_u64 v[248:249], s[36:37], 0, v[144:145]
	ds_read_b128 v[194:197], v172 offset:32768
	ds_read_b128 v[212:215], v172 offset:33792
	ds_read_b128 v[216:219], v172 offset:34816
	ds_read_b128 v[220:223], v172 offset:35840
	ds_read_b128 v[224:227], v172 offset:36864
	ds_read_b128 v[228:231], v172 offset:37888
	ds_read_b128 v[236:239], v172 offset:38912
	ds_read_b128 v[240:243], v172 offset:39936
	global_load_lds_dwordx4 v[248:249], off
	v_lshl_add_u64 v[248:249], s[36:37], 0, v[140:141]
	s_mov_b32 m0, s4
	s_nop 0
	global_load_lds_dwordx4 v[248:249], off
	s_waitcnt vmcnt(8)
	s_waitcnt lgkmcnt(0)
	s_barrier
	s_waitcnt lgkmcnt(0)
	v_mfma_f32_16x16x32_bf16 v[128:131], v[132:135], v[194:197], v[128:131]
	v_mfma_f32_16x16x32_bf16 v[124:127], v[150:153], v[194:197], v[124:127]
	v_mfma_f32_16x16x32_bf16 v[112:115], v[132:135], v[216:219], v[112:115]
	v_mfma_f32_16x16x32_bf16 v[108:111], v[150:153], v[216:219], v[108:111]
	v_mfma_f32_16x16x32_bf16 v[96:99], v[132:135], v[224:227], v[96:99]
	v_mfma_f32_16x16x32_bf16 v[92:95], v[150:153], v[224:227], v[92:95]
	v_mfma_f32_16x16x32_bf16 v[80:83], v[132:135], v[236:239], v[80:83]
	v_mfma_f32_16x16x32_bf16 v[76:79], v[150:153], v[236:239], v[76:79]
	v_mfma_f32_16x16x32_bf16 v[128:131], v[136:139], v[212:215], v[128:131]
	v_mfma_f32_16x16x32_bf16 v[124:127], v[174:177], v[212:215], v[124:127]
	v_mfma_f32_16x16x32_bf16 v[112:115], v[136:139], v[220:223], v[112:115]
	v_mfma_f32_16x16x32_bf16 v[108:111], v[174:177], v[220:223], v[108:111]
	v_mfma_f32_16x16x32_bf16 v[96:99], v[136:139], v[228:231], v[96:99]
	v_mfma_f32_16x16x32_bf16 v[92:95], v[174:177], v[228:231], v[92:95]
	v_mfma_f32_16x16x32_bf16 v[80:83], v[136:139], v[240:243], v[80:83]
	v_mfma_f32_16x16x32_bf16 v[76:79], v[174:177], v[240:243], v[76:79]
	v_mfma_f32_16x16x32_bf16 v[120:123], v[178:181], v[194:197], v[120:123]
	v_mfma_f32_16x16x32_bf16 v[116:119], v[186:189], v[194:197], v[116:119]
	v_mfma_f32_16x16x32_bf16 v[104:107], v[178:181], v[216:219], v[104:107]
	v_mfma_f32_16x16x32_bf16 v[100:103], v[186:189], v[216:219], v[100:103]
	v_mfma_f32_16x16x32_bf16 v[88:91], v[178:181], v[224:227], v[88:91]
	v_mfma_f32_16x16x32_bf16 v[84:87], v[186:189], v[224:227], v[84:87]
	v_mfma_f32_16x16x32_bf16 v[72:75], v[178:181], v[236:239], v[72:75]
	v_mfma_f32_16x16x32_bf16 v[68:71], v[186:189], v[236:239], v[68:71]
	v_mfma_f32_16x16x32_bf16 v[120:123], v[182:185], v[212:215], v[120:123]
	v_mfma_f32_16x16x32_bf16 v[116:119], v[190:193], v[212:215], v[116:119]
	v_mfma_f32_16x16x32_bf16 v[104:107], v[182:185], v[220:223], v[104:107]
	v_mfma_f32_16x16x32_bf16 v[100:103], v[190:193], v[220:223], v[100:103]
	v_mfma_f32_16x16x32_bf16 v[88:91], v[182:185], v[228:231], v[88:91]
	v_mfma_f32_16x16x32_bf16 v[84:87], v[190:193], v[228:231], v[84:87]
	v_mfma_f32_16x16x32_bf16 v[72:75], v[182:185], v[240:243], v[72:75]
	v_mfma_f32_16x16x32_bf16 v[68:71], v[190:193], v[240:243], v[68:71]
	s_barrier
; #define PG8_STAGE(bufoff, gbase, voff) do { _Pragma("unroll") for (int _i = 0; _i < 2; ++_i) \
;         __builtin_amdgcn_global_load_lds((const unsigned*)((const char*)(gbase) + (voff)[_i]), (PG8_LAS unsigned*)(lds + (bufoff) + ldsw + _i * 8192), 16, 0, 0); } while (0)
; #define PG8_LDA(dst, b, h) do { _Pragma("unroll") for (int m = 0; m < 4; ++m) _Pragma("unroll") for (int k = 0; k < 2; ++k) dst[m][k] = *(const PG8_LAS bf16x8*)(lds + PG8_SA(b, h) + aoff + m * 2048 + k * 1024); } while (0)
; #define PG8_MMA(ai, bj, At, Bt) do { __builtin_amdgcn_s_setprio(1); _Pragma("unroll") for (int m = 0; m < 4; ++m) _Pragma("unroll") for (int n = 0; n < 2; ++n) _Pragma("unroll") for (int k = 0; k < 2; ++k) \
;         acc[ai][bj][m][n] = __builtin_amdgcn_mfma_f32_16x16x32_bf16(Bt[n][k], At[m][k], acc[ai][bj][m][n], 0, 0, 0); __builtin_amdgcn_s_setprio(0); } while (0)
; #define PG8_WAIT_V(n) asm volatile("s_waitcnt vmcnt(" #n ")" ::: "memory")
; #define PG8_WAIT_L(n) asm volatile("s_waitcnt lgkmcnt(" #n ")" ::: "memory")
; #define PG8_BAR __builtin_amdgcn_s_barrier()
; #define PG8_SCHED __builtin_amdgcn_sched_barrier(0)
; template <class Epi, class Sched, bool ALIGN_EPI = false, bool SP2 = false>
; __device__ __forceinline__ void gemm_phase(PG8_LAS unsigned char* lds, const Gemm g, const Sched& S, const Epi& E, const int tid) {
;     ...
;         for (int t = 0; t < nt; t += 2) {
;     ...
;             PG8_LDA(At, 1, 1); PG8_STAGE(PG8_SB(1, 0), b3, voffB); PG8_STAGE(PG8_SB(1, 1), b3 + hstep, voffB); PG8_STAGE(PG8_SA(1, 0), a3, voffA);
;             PG8_WAIT_V(8); PG8_WAIT_L(0); PG8_BAR; PG8_MMA(1, 0, At, B0); PG8_MMA(1, 1, At, B1); PG8_BAR; PG8_SCHED;
;     ...
;         if constexpr (ALIGN_EPI) { if (wr == 0) PG8_BAR; }
	s_add_i32 s12, s12, s53
	v_lshl_add_u64 v[160:161], v[160:161], 0, s[18:19]
	s_mov_b32 m0, s12
	ds_read_b128 v[194:197], v172 offset:49152
	ds_read_b128 v[212:215], v172 offset:50176
	ds_read_b128 v[216:219], v172 offset:51200
	ds_read_b128 v[220:223], v172 offset:52224
	ds_read_b128 v[224:227], v172 offset:53248
	ds_read_b128 v[228:231], v172 offset:54272
	ds_read_b128 v[236:239], v172 offset:55296
	ds_read_b128 v[240:243], v172 offset:56320
	global_load_lds_dwordx4 v[160:161], off
	s_add_i32 m0, s12, 0x2000
	s_add_u32 s28, s28, 0x80080
	v_lshl_add_u64 v[160:161], v[198:199], 0, s[18:19]
	s_addc_u32 s29, s29, 0
	s_add_i32 s12, s14, s53
	global_load_lds_dwordx4 v[160:161], off
	v_lshl_add_u64 v[160:161], s[28:29], 0, v[142:143]
	s_mov_b32 m0, s12
	s_nop 0
	global_load_lds_dwordx4 v[160:161], off
	v_lshl_add_u64 v[160:161], s[28:29], 0, v[0:1]
	s_add_i32 m0, s12, 0x2000
	s_nop 0
	global_load_lds_dwordx4 v[160:161], off
	v_lshl_add_u64 v[160:161], v[244:245], 0, s[18:19]
	s_mov_b32 m0, s5
	s_nop 0
	global_load_lds_dwordx4 v[160:161], off
	v_lshl_add_u64 v[160:161], v[246:247], 0, s[18:19]
	s_mov_b32 m0, s6
	s_nop 0
	global_load_lds_dwordx4 v[160:161], off
	s_waitcnt vmcnt(8)
	s_waitcnt lgkmcnt(0)
	s_barrier
	s_waitcnt lgkmcnt(0)
	v_mfma_f32_16x16x32_bf16 v[64:67], v[132:135], v[194:197], v[64:67]
	v_mfma_f32_16x16x32_bf16 v[60:63], v[150:153], v[194:197], v[60:63]
	v_mfma_f32_16x16x32_bf16 v[48:51], v[132:135], v[216:219], v[48:51]
	v_mfma_f32_16x16x32_bf16 v[44:47], v[150:153], v[216:219], v[44:47]
	v_mfma_f32_16x16x32_bf16 v[32:35], v[132:135], v[224:227], v[32:35]
	v_mfma_f32_16x16x32_bf16 v[28:31], v[150:153], v[224:227], v[28:31]
	v_mfma_f32_16x16x32_bf16 v[16:19], v[132:135], v[236:239], v[16:19]
	v_mfma_f32_16x16x32_bf16 v[12:15], v[150:153], v[236:239], v[12:15]
	v_mfma_f32_16x16x32_bf16 v[64:67], v[136:139], v[212:215], v[64:67]
	v_mfma_f32_16x16x32_bf16 v[60:63], v[174:177], v[212:215], v[60:63]
	v_mfma_f32_16x16x32_bf16 v[48:51], v[136:139], v[220:223], v[48:51]
	v_mfma_f32_16x16x32_bf16 v[44:47], v[174:177], v[220:223], v[44:47]
	v_mfma_f32_16x16x32_bf16 v[32:35], v[136:139], v[228:231], v[32:35]
	v_mfma_f32_16x16x32_bf16 v[28:31], v[174:177], v[228:231], v[28:31]
	v_mfma_f32_16x16x32_bf16 v[16:19], v[136:139], v[240:243], v[16:19]
	v_mfma_f32_16x16x32_bf16 v[12:15], v[174:177], v[240:243], v[12:15]
	v_mfma_f32_16x16x32_bf16 v[56:59], v[178:181], v[194:197], v[56:59]
	v_mfma_f32_16x16x32_bf16 v[52:55], v[186:189], v[194:197], v[52:55]
	v_mfma_f32_16x16x32_bf16 v[40:43], v[178:181], v[216:219], v[40:43]
	v_mfma_f32_16x16x32_bf16 v[36:39], v[186:189], v[216:219], v[36:39]
	v_mfma_f32_16x16x32_bf16 v[24:27], v[178:181], v[224:227], v[24:27]
	v_mfma_f32_16x16x32_bf16 v[20:23], v[186:189], v[224:227], v[20:23]
	v_mfma_f32_16x16x32_bf16 v[8:11], v[178:181], v[236:239], v[8:11]
	v_mfma_f32_16x16x32_bf16 v[4:7], v[186:189], v[236:239], v[4:7]
	v_mfma_f32_16x16x32_bf16 v[56:59], v[182:185], v[212:215], v[56:59]
	v_mfma_f32_16x16x32_bf16 v[52:55], v[190:193], v[212:215], v[52:55]
	v_mfma_f32_16x16x32_bf16 v[40:43], v[182:185], v[220:223], v[40:43]
	v_mfma_f32_16x16x32_bf16 v[36:39], v[190:193], v[220:223], v[36:39]
	v_mfma_f32_16x16x32_bf16 v[24:27], v[182:185], v[228:231], v[24:27]
	v_mfma_f32_16x16x32_bf16 v[20:23], v[190:193], v[228:231], v[20:23]
	v_mfma_f32_16x16x32_bf16 v[8:11], v[182:185], v[240:243], v[8:11]
	v_mfma_f32_16x16x32_bf16 v[4:7], v[190:193], v[240:243], v[4:7]
	s_barrier
	s_add_i32 s23, s23, 2
	s_add_u32 s24, s24, 0x100
	s_addc_u32 s25, s25, 0
	s_add_u32 s21, s21, 0x100
	s_addc_u32 s22, s22, 0
	s_cmp_gt_u32 s23, 29
	s_cbranch_scc0 .LBB0_269
	s_and_b64 vcc, exec, s[34:35]
	s_cbranch_vccz .LBB0_272
	s_barrier

; #define PG8_STAGE(bufoff, gbase, voff) do { _Pragma("unroll") for (int _i = 0; _i < 2; ++_i) \
;         __builtin_amdgcn_global_load_lds((const unsigned*)((const char*)(gbase) + (voff)[_i]), (PG8_LAS unsigned*)(lds + (bufoff) + ldsw + _i * 8192), 16, 0, 0); } while (0)
; #define PG8_LDA(dst, b, h) do { _Pragma("unroll") for (int m = 0; m < 4; ++m) _Pragma("unroll") for (int k = 0; k < 2; ++k) dst[m][k] = *(const PG8_LAS bf16x8*)(lds + PG8_SA(b, h) + aoff + m * 2048 + k * 1024); } while (0)
; #define PG8_LDB(dst, b, h) do { _Pragma("unroll") for (int n = 0; n < 2; ++n) _Pragma("unroll") for (int k = 0; k < 2; ++k) dst[n][k] = *(const PG8_LAS bf16x8*)(lds + PG8_SB(b, h) + boff + n * 2048 + k * 1024); } while (0)
; #define PG8_MMA(ai, bj, At, Bt) do { __builtin_amdgcn_s_setprio(1); _Pragma("unroll") for (int m = 0; m < 4; ++m) _Pragma("unroll") for (int n = 0; n < 2; ++n) _Pragma("unroll") for (int k = 0; k < 2; ++k) \
;         acc[ai][bj][m][n] = __builtin_amdgcn_mfma_f32_16x16x32_bf16(Bt[n][k], At[m][k], acc[ai][bj][m][n], 0, 0, 0); __builtin_amdgcn_s_setprio(0); } while (0)
; #define PG8_WAIT_V(n) asm volatile("s_waitcnt vmcnt(" #n ")" ::: "memory")
; #define PG8_WAIT_L(n) asm volatile("s_waitcnt lgkmcnt(" #n ")" ::: "memory")
; template <class Epi, class Sched, bool ALIGN_EPI = false, bool SP2 = false>
; __device__ __forceinline__ void gemm_phase(PG8_LAS unsigned char* lds, const Gemm g, const Sched& S, const Epi& E, const int tid) {
;     ...
;             const bool last = (t == nt - 2);
;             const char* a1 = cA + (size_t)(t + 1) * kstep;
;             const char* a2 = last ? nA : cA + (size_t)(t + 2) * kstep; const char* b2 = last ? nB : cB + (size_t)(t + 2) * kstep;
;             const char* a3 = a2 + kstep; const char* b3 = b2 + kstep;
;             if (last && has_next) S.a_ready(nxt);
;             if constexpr (SP2) {
;             PG8_LDB(B0, 0, 0); PG8_LDB(B1, 0, 1); PG8_SCHED; PG8_LDA(At, 0, 0); PG8_STAGE(PG8_SA(1, 1), a1 + hstep, voffA);
;             PG8_WAIT_V(8); PG8_WAIT_L(0); PG8_BAR; PG8_MMA(0, 0, At, B0); PG8_MMA(0, 1, At, B1); PG8_BAR; PG8_SCHED;
;             PG8_LDA(At, 0, 1); PG8_STAGE(PG8_SB(0, 0), b2, voffB); PG8_STAGE(PG8_SB(0, 1), b2 + hstep, voffB); PG8_STAGE(PG8_SA(0, 0), a2, voffA);
;             PG8_WAIT_V(8); PG8_WAIT_L(0); PG8_BAR; PG8_MMA(1, 0, At, B0); PG8_MMA(1, 1, At, B1); PG8_BAR; PG8_SCHED;
.LBB0_975:
	s_add_u32 s12, s36, 0xfffc0080
	s_addc_u32 s14, s37, -1
	s_add_i32 s51, 0, 0x10000
	s_cmp_eq_u32 s50, 12
	s_cselect_b32 s45, s13, s14
	s_cselect_b32 s44, s15, s12
	v_add_u32_e32 v2, s51, v152
	s_cselect_b32 s43, s22, s35
	s_cselect_b32 s42, s23, s29
	s_add_i32 s12, 0, 0x14000
	ds_read_b128 v[142:145], v2
	ds_read_b128 v[146:149], v2 offset:1024
	ds_read_b128 v[170:173], v2 offset:2048
	ds_read_b128 v[174:177], v2 offset:3072
	v_add_u32_e32 v2, s12, v152
	ds_read_b128 v[178:181], v2
	ds_read_b128 v[182:185], v2 offset:1024
	ds_read_b128 v[186:189], v2 offset:2048
	ds_read_b128 v[190:193], v2 offset:3072
	v_lshl_add_u64 v[160:161], s[36:37], 0, v[138:139]
	s_add_i32 m0, s7, 0xc000
	ds_read_b128 v[194:197], v153
	ds_read_b128 v[212:215], v153 offset:1024
	ds_read_b128 v[216:219], v153 offset:2048
	ds_read_b128 v[220:223], v153 offset:3072
	ds_read_b128 v[224:227], v153 offset:4096
	ds_read_b128 v[228:231], v153 offset:5120
	ds_read_b128 v[236:239], v153 offset:6144
	ds_read_b128 v[240:243], v153 offset:7168
	global_load_lds_dwordx4 v[160:161], off
	v_lshl_add_u64 v[160:161], s[36:37], 0, v[140:141]
	s_add_i32 m0, s7, 0xe000
	s_nop 0
	global_load_lds_dwordx4 v[160:161], off
	s_waitcnt vmcnt(8)
	s_waitcnt lgkmcnt(0)
	s_barrier
	s_waitcnt lgkmcnt(0)
	v_mfma_f32_16x16x32_bf16 v[128:131], v[142:145], v[194:197], v[128:131]
	v_mfma_f32_16x16x32_bf16 v[124:127], v[170:173], v[194:197], v[124:127]
	v_mfma_f32_16x16x32_bf16 v[112:115], v[142:145], v[216:219], v[112:115]
	v_mfma_f32_16x16x32_bf16 v[108:111], v[170:173], v[216:219], v[108:111]
	v_mfma_f32_16x16x32_bf16 v[96:99], v[142:145], v[224:227], v[96:99]
	v_mfma_f32_16x16x32_bf16 v[92:95], v[170:173], v[224:227], v[92:95]
	v_mfma_f32_16x16x32_bf16 v[80:83], v[142:145], v[236:239], v[80:83]
	v_mfma_f32_16x16x32_bf16 v[76:79], v[170:173], v[236:239], v[76:79]
	v_mfma_f32_16x16x32_bf16 v[128:131], v[146:149], v[212:215], v[128:131]
	v_mfma_f32_16x16x32_bf16 v[124:127], v[174:177], v[212:215], v[124:127]
	v_mfma_f32_16x16x32_bf16 v[112:115], v[146:149], v[220:223], v[112:115]
	v_mfma_f32_16x16x32_bf16 v[108:111], v[174:177], v[220:223], v[108:111]
	v_mfma_f32_16x16x32_bf16 v[96:99], v[146:149], v[228:231], v[96:99]
	v_mfma_f32_16x16x32_bf16 v[92:95], v[174:177], v[228:231], v[92:95]
	v_mfma_f32_16x16x32_bf16 v[80:83], v[146:149], v[240:243], v[80:83]
	v_mfma_f32_16x16x32_bf16 v[76:79], v[174:177], v[240:243], v[76:79]
	v_mfma_f32_16x16x32_bf16 v[120:123], v[178:181], v[194:197], v[120:123]
	v_mfma_f32_16x16x32_bf16 v[116:119], v[186:189], v[194:197], v[116:119]
	v_mfma_f32_16x16x32_bf16 v[104:107], v[178:181], v[216:219], v[104:107]
	v_mfma_f32_16x16x32_bf16 v[100:103], v[186:189], v[216:219], v[100:103]
	v_mfma_f32_16x16x32_bf16 v[88:91], v[178:181], v[224:227], v[88:91]
	v_mfma_f32_16x16x32_bf16 v[84:87], v[186:189], v[224:227], v[84:87]
	v_mfma_f32_16x16x32_bf16 v[72:75], v[178:181], v[236:239], v[72:75]
	v_mfma_f32_16x16x32_bf16 v[68:71], v[186:189], v[236:239], v[68:71]
	v_mfma_f32_16x16x32_bf16 v[120:123], v[182:185], v[212:215], v[120:123]
	v_mfma_f32_16x16x32_bf16 v[116:119], v[190:193], v[212:215], v[116:119]
	v_mfma_f32_16x16x32_bf16 v[104:107], v[182:185], v[220:223], v[104:107]
	v_mfma_f32_16x16x32_bf16 v[100:103], v[190:193], v[220:223], v[100:103]
	v_mfma_f32_16x16x32_bf16 v[88:91], v[182:185], v[228:231], v[88:91]
	v_mfma_f32_16x16x32_bf16 v[84:87], v[190:193], v[228:231], v[84:87]
	v_mfma_f32_16x16x32_bf16 v[72:75], v[182:185], v[240:243], v[72:75]
	v_mfma_f32_16x16x32_bf16 v[68:71], v[190:193], v[240:243], v[68:71]
	s_barrier
	s_add_i32 s14, s51, s6
	v_lshl_add_u64 v[160:161], s[42:43], 0, v[134:135]
	s_mov_b32 m0, s14
	ds_read_b128 v[194:197], v153 offset:16384
	ds_read_b128 v[212:215], v153 offset:17408
	ds_read_b128 v[216:219], v153 offset:18432
	ds_read_b128 v[220:223], v153 offset:19456
	ds_read_b128 v[224:227], v153 offset:20480
	ds_read_b128 v[228:231], v153 offset:21504
	ds_read_b128 v[236:239], v153 offset:22528
	ds_read_b128 v[240:243], v153 offset:23552
	global_load_lds_dwordx4 v[160:161], off
	s_add_i32 m0, s14, 0x2000
	s_add_u32 s52, s42, 0x40000
	v_lshl_add_u64 v[198:199], s[42:43], 0, v[0:1]
	s_addc_u32 s53, s43, 0
	s_add_i32 s12, s12, s6
	global_load_lds_dwordx4 v[198:199], off
	v_lshl_add_u64 v[244:245], s[52:53], 0, v[134:135]
	s_mov_b32 m0, s12
	v_lshl_add_u64 v[246:247], s[44:45], 0, v[132:133]
	global_load_lds_dwordx4 v[244:245], off
	v_lshl_add_u64 v[244:245], s[52:53], 0, v[0:1]
	s_add_i32 m0, s12, 0x2000
	s_nop 0
	global_load_lds_dwordx4 v[244:245], off
	v_lshl_add_u64 v[244:245], s[44:45], 0, v[136:137]
	s_mov_b32 m0, s7
	s_nop 0
	global_load_lds_dwordx4 v[244:245], off
	s_mov_b32 m0, s8
	s_nop 0
	global_load_lds_dwordx4 v[246:247], off
	s_waitcnt vmcnt(8)
	s_waitcnt lgkmcnt(0)
	s_barrier
; #define PG8_STAGE(bufoff, gbase, voff) do { _Pragma("unroll") for (int _i = 0; _i < 2; ++_i) \
;         __builtin_amdgcn_global_load_lds((const unsigned*)((const char*)(gbase) + (voff)[_i]), (PG8_LAS unsigned*)(lds + (bufoff) + ldsw + _i * 8192), 16, 0, 0); } while (0)
; #define PG8_LDA(dst, b, h) do { _Pragma("unroll") for (int m = 0; m < 4; ++m) _Pragma("unroll") for (int k = 0; k < 2; ++k) dst[m][k] = *(const PG8_LAS bf16x8*)(lds + PG8_SA(b, h) + aoff + m * 2048 + k * 1024); } while (0)
; #define PG8_LDB(dst, b, h) do { _Pragma("unroll") for (int n = 0; n < 2; ++n) _Pragma("unroll") for (int k = 0; k < 2; ++k) dst[n][k] = *(const PG8_LAS bf16x8*)(lds + PG8_SB(b, h) + boff + n * 2048 + k * 1024); } while (0)
; #define PG8_MMA(ai, bj, At, Bt) do { __builtin_amdgcn_s_setprio(1); _Pragma("unroll") for (int m = 0; m < 4; ++m) _Pragma("unroll") for (int n = 0; n < 2; ++n) _Pragma("unroll") for (int k = 0; k < 2; ++k) \
;         acc[ai][bj][m][n] = __builtin_amdgcn_mfma_f32_16x16x32_bf16(Bt[n][k], At[m][k], acc[ai][bj][m][n], 0, 0, 0); __builtin_amdgcn_s_setprio(0); } while (0)
; #define PG8_WAIT_V(n) asm volatile("s_waitcnt vmcnt(" #n ")" ::: "memory")
; #define PG8_WAIT_L(n) asm volatile("s_waitcnt lgkmcnt(" #n ")" ::: "memory")
; #define PG8_BAR __builtin_amdgcn_s_barrier()
; #define PG8_SCHED __builtin_amdgcn_sched_barrier(0)
; template <class Epi, class Sched, bool ALIGN_EPI = false, bool SP2 = false>
; __device__ __forceinline__ void gemm_phase(PG8_LAS unsigned char* lds, const Gemm g, const Sched& S, const Epi& E, const int tid) {
;     ...
;             PG8_WAIT_V(8); PG8_WAIT_L(0); PG8_BAR; PG8_MMA(1, 0, At, B0); PG8_MMA(1, 1, At, B1); PG8_BAR; PG8_SCHED;
;             PG8_LDB(B0, 1, 0); PG8_LDB(B1, 1, 1); PG8_SCHED; PG8_LDA(At, 1, 0); PG8_STAGE(PG8_SA(0, 1), a2 + hstep, voffA);
;             PG8_WAIT_V(8); PG8_WAIT_L(0); PG8_BAR; PG8_MMA(0, 0, At, B0); PG8_MMA(0, 1, At, B1); PG8_BAR; PG8_SCHED;
	s_waitcnt lgkmcnt(0)
	v_mfma_f32_16x16x32_bf16 v[64:67], v[142:145], v[194:197], v[64:67]
	v_mfma_f32_16x16x32_bf16 v[60:63], v[170:173], v[194:197], v[60:63]
	v_mfma_f32_16x16x32_bf16 v[48:51], v[142:145], v[216:219], v[48:51]
	v_mfma_f32_16x16x32_bf16 v[44:47], v[170:173], v[216:219], v[44:47]
	v_mfma_f32_16x16x32_bf16 v[32:35], v[142:145], v[224:227], v[32:35]
	v_mfma_f32_16x16x32_bf16 v[28:31], v[170:173], v[224:227], v[28:31]
	v_mfma_f32_16x16x32_bf16 v[16:19], v[142:145], v[236:239], v[16:19]
	v_mfma_f32_16x16x32_bf16 v[12:15], v[170:173], v[236:239], v[12:15]
	v_mfma_f32_16x16x32_bf16 v[64:67], v[146:149], v[212:215], v[64:67]
	v_mfma_f32_16x16x32_bf16 v[60:63], v[174:177], v[212:215], v[60:63]
	v_mfma_f32_16x16x32_bf16 v[48:51], v[146:149], v[220:223], v[48:51]
	v_mfma_f32_16x16x32_bf16 v[44:47], v[174:177], v[220:223], v[44:47]
	v_mfma_f32_16x16x32_bf16 v[32:35], v[146:149], v[228:231], v[32:35]
	v_mfma_f32_16x16x32_bf16 v[28:31], v[174:177], v[228:231], v[28:31]
	v_mfma_f32_16x16x32_bf16 v[16:19], v[146:149], v[240:243], v[16:19]
	v_mfma_f32_16x16x32_bf16 v[12:15], v[174:177], v[240:243], v[12:15]
	v_mfma_f32_16x16x32_bf16 v[56:59], v[178:181], v[194:197], v[56:59]
	v_mfma_f32_16x16x32_bf16 v[52:55], v[186:189], v[194:197], v[52:55]
	v_mfma_f32_16x16x32_bf16 v[40:43], v[178:181], v[216:219], v[40:43]
	v_mfma_f32_16x16x32_bf16 v[36:39], v[186:189], v[216:219], v[36:39]
	v_mfma_f32_16x16x32_bf16 v[24:27], v[178:181], v[224:227], v[24:27]
	v_mfma_f32_16x16x32_bf16 v[20:23], v[186:189], v[224:227], v[20:23]
	v_mfma_f32_16x16x32_bf16 v[8:11], v[178:181], v[236:239], v[8:11]
	v_mfma_f32_16x16x32_bf16 v[4:7], v[186:189], v[236:239], v[4:7]
	v_mfma_f32_16x16x32_bf16 v[56:59], v[182:185], v[212:215], v[56:59]
	v_mfma_f32_16x16x32_bf16 v[52:55], v[190:193], v[212:215], v[52:55]
	v_mfma_f32_16x16x32_bf16 v[40:43], v[182:185], v[220:223], v[40:43]
	v_mfma_f32_16x16x32_bf16 v[36:39], v[190:193], v[220:223], v[36:39]
	v_mfma_f32_16x16x32_bf16 v[24:27], v[182:185], v[228:231], v[24:27]
	v_mfma_f32_16x16x32_bf16 v[20:23], v[190:193], v[228:231], v[20:23]
	v_mfma_f32_16x16x32_bf16 v[8:11], v[182:185], v[240:243], v[8:11]
	v_mfma_f32_16x16x32_bf16 v[4:7], v[190:193], v[240:243], v[4:7]
	s_barrier
	s_add_i32 s12, 0, 0x18000
	v_add_u32_e32 v2, s12, v152
	s_add_i32 s14, 0, 0x1c000
	ds_read_b128 v[142:145], v2
	ds_read_b128 v[146:149], v2 offset:1024
	ds_read_b128 v[170:173], v2 offset:2048
	ds_read_b128 v[174:177], v2 offset:3072
	v_add_u32_e32 v2, s14, v152
	ds_read_b128 v[178:181], v2
	ds_read_b128 v[182:185], v2 offset:1024
	ds_read_b128 v[186:189], v2 offset:2048
	ds_read_b128 v[190:193], v2 offset:3072
	s_add_u32 s44, s44, 0x40000
	s_addc_u32 s45, s45, 0
	s_mov_b32 m0, s9
	v_lshl_add_u64 v[248:249], s[44:45], 0, v[136:137]
	ds_read_b128 v[194:197], v153 offset:32768
	ds_read_b128 v[212:215], v153 offset:33792
	ds_read_b128 v[216:219], v153 offset:34816
	ds_read_b128 v[220:223], v153 offset:35840
	ds_read_b128 v[224:227], v153 offset:36864
	ds_read_b128 v[228:231], v153 offset:37888
	ds_read_b128 v[236:239], v153 offset:38912
	ds_read_b128 v[240:243], v153 offset:39936
	global_load_lds_dwordx4 v[248:249], off
	v_lshl_add_u64 v[248:249], s[44:45], 0, v[132:133]
	s_mov_b32 m0, s30
	s_nop 0
	global_load_lds_dwordx4 v[248:249], off
	s_waitcnt vmcnt(8)
	s_waitcnt lgkmcnt(0)
	s_barrier
	s_waitcnt lgkmcnt(0)
	v_mfma_f32_16x16x32_bf16 v[128:131], v[142:145], v[194:197], v[128:131]
	v_mfma_f32_16x16x32_bf16 v[124:127], v[170:173], v[194:197], v[124:127]
	v_mfma_f32_16x16x32_bf16 v[112:115], v[142:145], v[216:219], v[112:115]
	v_mfma_f32_16x16x32_bf16 v[108:111], v[170:173], v[216:219], v[108:111]
	v_mfma_f32_16x16x32_bf16 v[96:99], v[142:145], v[224:227], v[96:99]
	v_mfma_f32_16x16x32_bf16 v[92:95], v[170:173], v[224:227], v[92:95]
	v_mfma_f32_16x16x32_bf16 v[80:83], v[142:145], v[236:239], v[80:83]
	v_mfma_f32_16x16x32_bf16 v[76:79], v[170:173], v[236:239], v[76:79]
	v_mfma_f32_16x16x32_bf16 v[128:131], v[146:149], v[212:215], v[128:131]
	v_mfma_f32_16x16x32_bf16 v[124:127], v[174:177], v[212:215], v[124:127]
	v_mfma_f32_16x16x32_bf16 v[112:115], v[146:149], v[220:223], v[112:115]
	v_mfma_f32_16x16x32_bf16 v[108:111], v[174:177], v[220:223], v[108:111]
	v_mfma_f32_16x16x32_bf16 v[96:99], v[146:149], v[228:231], v[96:99]
	v_mfma_f32_16x16x32_bf16 v[92:95], v[174:177], v[228:231], v[92:95]
	v_mfma_f32_16x16x32_bf16 v[80:83], v[146:149], v[240:243], v[80:83]
	v_mfma_f32_16x16x32_bf16 v[76:79], v[174:177], v[240:243], v[76:79]
	v_mfma_f32_16x16x32_bf16 v[120:123], v[178:181], v[194:197], v[120:123]
	v_mfma_f32_16x16x32_bf16 v[116:119], v[186:189], v[194:197], v[116:119]
	v_mfma_f32_16x16x32_bf16 v[104:107], v[178:181], v[216:219], v[104:107]
	v_mfma_f32_16x16x32_bf16 v[100:103], v[186:189], v[216:219], v[100:103]
	v_mfma_f32_16x16x32_bf16 v[88:91], v[178:181], v[224:227], v[88:91]
	v_mfma_f32_16x16x32_bf16 v[84:87], v[186:189], v[224:227], v[84:87]
	v_mfma_f32_16x16x32_bf16 v[72:75], v[178:181], v[236:239], v[72:75]
	v_mfma_f32_16x16x32_bf16 v[68:71], v[186:189], v[236:239], v[68:71]
	v_mfma_f32_16x16x32_bf16 v[120:123], v[182:185], v[212:215], v[120:123]
	v_mfma_f32_16x16x32_bf16 v[116:119], v[190:193], v[212:215], v[116:119]
	v_mfma_f32_16x16x32_bf16 v[104:107], v[182:185], v[220:223], v[104:107]
	v_mfma_f32_16x16x32_bf16 v[100:103], v[190:193], v[220:223], v[100:103]
	v_mfma_f32_16x16x32_bf16 v[88:91], v[182:185], v[228:231], v[88:91]
	v_mfma_f32_16x16x32_bf16 v[84:87], v[190:193], v[228:231], v[84:87]
	v_mfma_f32_16x16x32_bf16 v[72:75], v[182:185], v[240:243], v[72:75]
	v_mfma_f32_16x16x32_bf16 v[68:71], v[190:193], v[240:243], v[68:71]
	s_barrier
; #define PG8_STAGE(bufoff, gbase, voff) do { _Pragma("unroll") for (int _i = 0; _i < 2; ++_i) \
;         __builtin_amdgcn_global_load_lds((const unsigned*)((const char*)(gbase) + (voff)[_i]), (PG8_LAS unsigned*)(lds + (bufoff) + ldsw + _i * 8192), 16, 0, 0); } while (0)
; #define PG8_LDA(dst, b, h) do { _Pragma("unroll") for (int m = 0; m < 4; ++m) _Pragma("unroll") for (int k = 0; k < 2; ++k) dst[m][k] = *(const PG8_LAS bf16x8*)(lds + PG8_SA(b, h) + aoff + m * 2048 + k * 1024); } while (0)
; #define PG8_MMA(ai, bj, At, Bt) do { __builtin_amdgcn_s_setprio(1); _Pragma("unroll") for (int m = 0; m < 4; ++m) _Pragma("unroll") for (int n = 0; n < 2; ++n) _Pragma("unroll") for (int k = 0; k < 2; ++k) \
;         acc[ai][bj][m][n] = __builtin_amdgcn_mfma_f32_16x16x32_bf16(Bt[n][k], At[m][k], acc[ai][bj][m][n], 0, 0, 0); __builtin_amdgcn_s_setprio(0); } while (0)
; #define PG8_WAIT_V(n) asm volatile("s_waitcnt vmcnt(" #n ")" ::: "memory")
; #define PG8_WAIT_L(n) asm volatile("s_waitcnt lgkmcnt(" #n ")" ::: "memory")
; #define PG8_BAR __builtin_amdgcn_s_barrier()
; #define PG8_SCHED __builtin_amdgcn_sched_barrier(0)
; template <class Epi, class Sched, bool ALIGN_EPI = false, bool SP2 = false>
; __device__ __forceinline__ void gemm_phase(PG8_LAS unsigned char* lds, const Gemm g, const Sched& S, const Epi& E, const int tid) {
;     ...
;         for (int t = 0; t < nt; t += 2) {
;     ...
;             PG8_LDA(At, 1, 1); PG8_STAGE(PG8_SB(1, 0), b3, voffB); PG8_STAGE(PG8_SB(1, 1), b3 + hstep, voffB); PG8_STAGE(PG8_SA(1, 0), a3, voffA);
;             PG8_WAIT_V(8); PG8_WAIT_L(0); PG8_BAR; PG8_MMA(1, 0, At, B0); PG8_MMA(1, 1, At, B1); PG8_BAR; PG8_SCHED;
;     ...
;         if constexpr (ALIGN_EPI) { if (wr == 0) PG8_BAR; }
	s_add_i32 s12, s12, s6
	v_lshl_add_u64 v[160:161], v[160:161], 0, s[18:19]
	s_mov_b32 m0, s12
	ds_read_b128 v[194:197], v153 offset:49152
	ds_read_b128 v[212:215], v153 offset:50176
	ds_read_b128 v[216:219], v153 offset:51200
	ds_read_b128 v[220:223], v153 offset:52224
	ds_read_b128 v[224:227], v153 offset:53248
	ds_read_b128 v[228:231], v153 offset:54272
	ds_read_b128 v[236:239], v153 offset:55296
	ds_read_b128 v[240:243], v153 offset:56320
	global_load_lds_dwordx4 v[160:161], off
	s_add_i32 m0, s12, 0x2000
	s_add_u32 s42, s42, 0x40080
	v_lshl_add_u64 v[160:161], v[198:199], 0, s[18:19]
	s_addc_u32 s43, s43, 0
	s_add_i32 s12, s14, s6
	global_load_lds_dwordx4 v[160:161], off
	v_lshl_add_u64 v[160:161], s[42:43], 0, v[134:135]
	s_mov_b32 m0, s12
	s_nop 0
	global_load_lds_dwordx4 v[160:161], off
	v_lshl_add_u64 v[160:161], s[42:43], 0, v[0:1]
	s_add_i32 m0, s12, 0x2000
	s_nop 0
	global_load_lds_dwordx4 v[160:161], off
	v_lshl_add_u64 v[160:161], v[244:245], 0, s[18:19]
	s_mov_b32 m0, s55
	s_nop 0
	global_load_lds_dwordx4 v[160:161], off
	v_lshl_add_u64 v[160:161], v[246:247], 0, s[18:19]
	s_mov_b32 m0, s60
	s_nop 0
	global_load_lds_dwordx4 v[160:161], off
	s_waitcnt vmcnt(8)
	s_waitcnt lgkmcnt(0)
	s_barrier
	s_waitcnt lgkmcnt(0)
	v_mfma_f32_16x16x32_bf16 v[64:67], v[142:145], v[194:197], v[64:67]
	v_mfma_f32_16x16x32_bf16 v[60:63], v[170:173], v[194:197], v[60:63]
	v_mfma_f32_16x16x32_bf16 v[48:51], v[142:145], v[216:219], v[48:51]
	v_mfma_f32_16x16x32_bf16 v[44:47], v[170:173], v[216:219], v[44:47]
	v_mfma_f32_16x16x32_bf16 v[32:35], v[142:145], v[224:227], v[32:35]
	v_mfma_f32_16x16x32_bf16 v[28:31], v[170:173], v[224:227], v[28:31]
	v_mfma_f32_16x16x32_bf16 v[16:19], v[142:145], v[236:239], v[16:19]
	v_mfma_f32_16x16x32_bf16 v[12:15], v[170:173], v[236:239], v[12:15]
	v_mfma_f32_16x16x32_bf16 v[64:67], v[146:149], v[212:215], v[64:67]
	v_mfma_f32_16x16x32_bf16 v[60:63], v[174:177], v[212:215], v[60:63]
	v_mfma_f32_16x16x32_bf16 v[48:51], v[146:149], v[220:223], v[48:51]
	v_mfma_f32_16x16x32_bf16 v[44:47], v[174:177], v[220:223], v[44:47]
	v_mfma_f32_16x16x32_bf16 v[32:35], v[146:149], v[228:231], v[32:35]
	v_mfma_f32_16x16x32_bf16 v[28:31], v[174:177], v[228:231], v[28:31]
	v_mfma_f32_16x16x32_bf16 v[16:19], v[146:149], v[240:243], v[16:19]
	v_mfma_f32_16x16x32_bf16 v[12:15], v[174:177], v[240:243], v[12:15]
	v_mfma_f32_16x16x32_bf16 v[56:59], v[178:181], v[194:197], v[56:59]
	v_mfma_f32_16x16x32_bf16 v[52:55], v[186:189], v[194:197], v[52:55]
	v_mfma_f32_16x16x32_bf16 v[40:43], v[178:181], v[216:219], v[40:43]
	v_mfma_f32_16x16x32_bf16 v[36:39], v[186:189], v[216:219], v[36:39]
	v_mfma_f32_16x16x32_bf16 v[24:27], v[178:181], v[224:227], v[24:27]
	v_mfma_f32_16x16x32_bf16 v[20:23], v[186:189], v[224:227], v[20:23]
	v_mfma_f32_16x16x32_bf16 v[8:11], v[178:181], v[236:239], v[8:11]
	v_mfma_f32_16x16x32_bf16 v[4:7], v[186:189], v[236:239], v[4:7]
	v_mfma_f32_16x16x32_bf16 v[56:59], v[182:185], v[212:215], v[56:59]
	v_mfma_f32_16x16x32_bf16 v[52:55], v[190:193], v[212:215], v[52:55]
	v_mfma_f32_16x16x32_bf16 v[40:43], v[182:185], v[220:223], v[40:43]
	v_mfma_f32_16x16x32_bf16 v[36:39], v[190:193], v[220:223], v[36:39]
	v_mfma_f32_16x16x32_bf16 v[24:27], v[182:185], v[228:231], v[24:27]
	v_mfma_f32_16x16x32_bf16 v[20:23], v[190:193], v[228:231], v[20:23]
	v_mfma_f32_16x16x32_bf16 v[8:11], v[182:185], v[240:243], v[8:11]
	v_mfma_f32_16x16x32_bf16 v[4:7], v[190:193], v[240:243], v[4:7]
	s_barrier
	s_add_i32 s50, s50, 2
	s_add_u32 s36, s36, 0x100
	s_addc_u32 s37, s37, 0
	s_add_u32 s29, s29, 0x100
	s_addc_u32 s35, s35, 0
	s_cmp_gt_u32 s50, 13
	s_cbranch_scc0 .LBB0_975
	s_and_b64 vcc, exec, s[24:25]
	s_cbranch_vccz .LBB0_978
	s_barrier

; #define PG8_STAGE(bufoff, gbase, voff) do { _Pragma("unroll") for (int _i = 0; _i < 2; ++_i) \
;         __builtin_amdgcn_global_load_lds((const unsigned*)((const char*)(gbase) + (voff)[_i]), (PG8_LAS unsigned*)(lds + (bufoff) + ldsw + _i * 8192), 16, 0, 0); } while (0)
; #define PG8_LDA(dst, b, h) do { _Pragma("unroll") for (int m = 0; m < 4; ++m) _Pragma("unroll") for (int k = 0; k < 2; ++k) dst[m][k] = *(const PG8_LAS bf16x8*)(lds + PG8_SA(b, h) + aoff + m * 2048 + k * 1024); } while (0)
; #define PG8_LDB(dst, b, h) do { _Pragma("unroll") for (int n = 0; n < 2; ++n) _Pragma("unroll") for (int k = 0; k < 2; ++k) dst[n][k] = *(const PG8_LAS bf16x8*)(lds + PG8_SB(b, h) + boff + n * 2048 + k * 1024); } while (0)
; #define PG8_MMA(ai, bj, At, Bt) do { __builtin_amdgcn_s_setprio(1); _Pragma("unroll") for (int m = 0; m < 4; ++m) _Pragma("unroll") for (int n = 0; n < 2; ++n) _Pragma("unroll") for (int k = 0; k < 2; ++k) \
;         acc[ai][bj][m][n] = __builtin_amdgcn_mfma_f32_16x16x32_bf16(Bt[n][k], At[m][k], acc[ai][bj][m][n], 0, 0, 0); __builtin_amdgcn_s_setprio(0); } while (0)
; #define PG8_WAIT_V(n) asm volatile("s_waitcnt vmcnt(" #n ")" ::: "memory")
; #define PG8_WAIT_L(n) asm volatile("s_waitcnt lgkmcnt(" #n ")" ::: "memory")
; template <class Epi, class Sched, bool ALIGN_EPI = false, bool SP2 = false>
; __device__ __forceinline__ void gemm_phase(PG8_LAS unsigned char* lds, const Gemm g, const Sched& S, const Epi& E, const int tid) {
;     ...
;             const bool last = (t == nt - 2);
;             const char* a1 = cA + (size_t)(t + 1) * kstep;
;             const char* a2 = last ? nA : cA + (size_t)(t + 2) * kstep; const char* b2 = last ? nB : cB + (size_t)(t + 2) * kstep;
;             const char* a3 = a2 + kstep; const char* b3 = b2 + kstep;
;             if (last && has_next) S.a_ready(nxt);
;             if constexpr (SP2) {
;             PG8_LDB(B0, 0, 0); PG8_LDB(B1, 0, 1); PG8_SCHED; PG8_LDA(At, 0, 0); PG8_STAGE(PG8_SA(1, 1), a1 + hstep, voffA);
;             PG8_WAIT_V(8); PG8_WAIT_L(0); PG8_BAR; PG8_MMA(0, 0, At, B0); PG8_MMA(0, 1, At, B1); PG8_BAR; PG8_SCHED;
;             PG8_LDA(At, 0, 1); PG8_STAGE(PG8_SB(0, 0), b2, voffB); PG8_STAGE(PG8_SB(0, 1), b2 + hstep, voffB); PG8_STAGE(PG8_SA(0, 0), a2, voffA);
;             PG8_WAIT_V(8); PG8_WAIT_L(0); PG8_BAR; PG8_MMA(1, 0, At, B0); PG8_MMA(1, 1, At, B1); PG8_BAR; PG8_SCHED;
.LBB0_1149:
	s_add_u32 s12, s36, 0xfffc0080
	s_addc_u32 s14, s37, -1
	s_add_i32 s51, 0, 0x10000
	s_cmp_eq_u32 s49, 12
	s_cselect_b32 s47, s13, s14
	s_cselect_b32 s46, s15, s12
	v_add_u32_e32 v2, s51, v147
	s_cselect_b32 s45, s22, s48
	s_cselect_b32 s44, s23, s35
	s_add_i32 s12, 0, 0x14000
	ds_read_b128 v[138:141], v2
	ds_read_b128 v[170:173], v2 offset:1024
	ds_read_b128 v[174:177], v2 offset:2048
	ds_read_b128 v[178:181], v2 offset:3072
	v_add_u32_e32 v2, s12, v147
	ds_read_b128 v[182:185], v2
	ds_read_b128 v[186:189], v2 offset:1024
	ds_read_b128 v[190:193], v2 offset:2048
	ds_read_b128 v[194:197], v2 offset:3072
	v_lshl_add_u64 v[142:143], s[36:37], 0, v[134:135]
	s_add_i32 m0, s7, 0xc000
	ds_read_b128 v[212:215], v152
	ds_read_b128 v[216:219], v152 offset:1024
	ds_read_b128 v[220:223], v152 offset:2048
	ds_read_b128 v[224:227], v152 offset:3072
	ds_read_b128 v[228:231], v152 offset:4096
	ds_read_b128 v[236:239], v152 offset:5120
	ds_read_b128 v[240:243], v152 offset:6144
	ds_read_b128 v[244:247], v152 offset:7168
	global_load_lds_dwordx4 v[142:143], off
	v_lshl_add_u64 v[142:143], s[36:37], 0, v[136:137]
	s_add_i32 m0, s7, 0xe000
	s_nop 0
	global_load_lds_dwordx4 v[142:143], off
	s_waitcnt vmcnt(8)
	s_waitcnt lgkmcnt(0)
	s_barrier
	s_waitcnt lgkmcnt(0)
	v_mfma_f32_16x16x32_bf16 v[128:131], v[138:141], v[212:215], v[128:131]
	v_mfma_f32_16x16x32_bf16 v[124:127], v[174:177], v[212:215], v[124:127]
	v_mfma_f32_16x16x32_bf16 v[112:115], v[138:141], v[220:223], v[112:115]
	v_mfma_f32_16x16x32_bf16 v[108:111], v[174:177], v[220:223], v[108:111]
	v_mfma_f32_16x16x32_bf16 v[96:99], v[138:141], v[228:231], v[96:99]
	v_mfma_f32_16x16x32_bf16 v[92:95], v[174:177], v[228:231], v[92:95]
	v_mfma_f32_16x16x32_bf16 v[80:83], v[138:141], v[240:243], v[80:83]
	v_mfma_f32_16x16x32_bf16 v[76:79], v[174:177], v[240:243], v[76:79]
	v_mfma_f32_16x16x32_bf16 v[128:131], v[170:173], v[216:219], v[128:131]
	v_mfma_f32_16x16x32_bf16 v[124:127], v[178:181], v[216:219], v[124:127]
	v_mfma_f32_16x16x32_bf16 v[112:115], v[170:173], v[224:227], v[112:115]
	v_mfma_f32_16x16x32_bf16 v[108:111], v[178:181], v[224:227], v[108:111]
	v_mfma_f32_16x16x32_bf16 v[96:99], v[170:173], v[236:239], v[96:99]
	v_mfma_f32_16x16x32_bf16 v[92:95], v[178:181], v[236:239], v[92:95]
	v_mfma_f32_16x16x32_bf16 v[80:83], v[170:173], v[244:247], v[80:83]
	v_mfma_f32_16x16x32_bf16 v[76:79], v[178:181], v[244:247], v[76:79]
	v_mfma_f32_16x16x32_bf16 v[120:123], v[182:185], v[212:215], v[120:123]
	v_mfma_f32_16x16x32_bf16 v[116:119], v[190:193], v[212:215], v[116:119]
	v_mfma_f32_16x16x32_bf16 v[104:107], v[182:185], v[220:223], v[104:107]
	v_mfma_f32_16x16x32_bf16 v[100:103], v[190:193], v[220:223], v[100:103]
	v_mfma_f32_16x16x32_bf16 v[88:91], v[182:185], v[228:231], v[88:91]
	v_mfma_f32_16x16x32_bf16 v[84:87], v[190:193], v[228:231], v[84:87]
	v_mfma_f32_16x16x32_bf16 v[72:75], v[182:185], v[240:243], v[72:75]
	v_mfma_f32_16x16x32_bf16 v[68:71], v[190:193], v[240:243], v[68:71]
	v_mfma_f32_16x16x32_bf16 v[120:123], v[186:189], v[216:219], v[120:123]
	v_mfma_f32_16x16x32_bf16 v[116:119], v[194:197], v[216:219], v[116:119]
	v_mfma_f32_16x16x32_bf16 v[104:107], v[186:189], v[224:227], v[104:107]
	v_mfma_f32_16x16x32_bf16 v[100:103], v[194:197], v[224:227], v[100:103]
	v_mfma_f32_16x16x32_bf16 v[88:91], v[186:189], v[236:239], v[88:91]
	v_mfma_f32_16x16x32_bf16 v[84:87], v[194:197], v[236:239], v[84:87]
	v_mfma_f32_16x16x32_bf16 v[72:75], v[186:189], v[244:247], v[72:75]
	v_mfma_f32_16x16x32_bf16 v[68:71], v[194:197], v[244:247], v[68:71]
	s_barrier
	s_add_i32 s14, s51, s6
	v_lshl_add_u64 v[142:143], s[44:45], 0, v[132:133]
	s_mov_b32 m0, s14
	ds_read_b128 v[212:215], v152 offset:16384
	ds_read_b128 v[216:219], v152 offset:17408
	ds_read_b128 v[220:223], v152 offset:18432
	ds_read_b128 v[224:227], v152 offset:19456
	ds_read_b128 v[228:231], v152 offset:20480
	ds_read_b128 v[236:239], v152 offset:21504
	ds_read_b128 v[240:243], v152 offset:22528
	ds_read_b128 v[244:247], v152 offset:23552
	global_load_lds_dwordx4 v[142:143], off
	s_add_i32 m0, s14, 0x2000
	s_add_u32 s52, s44, 0x40000
	v_lshl_add_u64 v[160:161], s[44:45], 0, v[0:1]
	s_addc_u32 s53, s45, 0
	s_add_i32 s12, s12, s6
	global_load_lds_dwordx4 v[160:161], off
	v_lshl_add_u64 v[198:199], s[52:53], 0, v[132:133]
	s_mov_b32 m0, s12
	v_lshl_add_u64 v[248:249], s[46:47], 0, v[0:1]
	global_load_lds_dwordx4 v[198:199], off
	v_lshl_add_u64 v[198:199], s[52:53], 0, v[0:1]
	s_add_i32 m0, s12, 0x2000
	s_nop 0
	global_load_lds_dwordx4 v[198:199], off
	v_lshl_add_u64 v[198:199], s[46:47], 0, v[132:133]
	s_mov_b32 m0, s7
	s_nop 0
	global_load_lds_dwordx4 v[198:199], off
	s_mov_b32 m0, s30
	s_nop 0
	global_load_lds_dwordx4 v[248:249], off
	s_waitcnt vmcnt(8)
	s_waitcnt lgkmcnt(0)
	s_barrier
; #define PG8_STAGE(bufoff, gbase, voff) do { _Pragma("unroll") for (int _i = 0; _i < 2; ++_i) \
;         __builtin_amdgcn_global_load_lds((const unsigned*)((const char*)(gbase) + (voff)[_i]), (PG8_LAS unsigned*)(lds + (bufoff) + ldsw + _i * 8192), 16, 0, 0); } while (0)
; #define PG8_LDA(dst, b, h) do { _Pragma("unroll") for (int m = 0; m < 4; ++m) _Pragma("unroll") for (int k = 0; k < 2; ++k) dst[m][k] = *(const PG8_LAS bf16x8*)(lds + PG8_SA(b, h) + aoff + m * 2048 + k * 1024); } while (0)
; #define PG8_LDB(dst, b, h) do { _Pragma("unroll") for (int n = 0; n < 2; ++n) _Pragma("unroll") for (int k = 0; k < 2; ++k) dst[n][k] = *(const PG8_LAS bf16x8*)(lds + PG8_SB(b, h) + boff + n * 2048 + k * 1024); } while (0)
; #define PG8_MMA(ai, bj, At, Bt) do { __builtin_amdgcn_s_setprio(1); _Pragma("unroll") for (int m = 0; m < 4; ++m) _Pragma("unroll") for (int n = 0; n < 2; ++n) _Pragma("unroll") for (int k = 0; k < 2; ++k) \
;         acc[ai][bj][m][n] = __builtin_amdgcn_mfma_f32_16x16x32_bf16(Bt[n][k], At[m][k], acc[ai][bj][m][n], 0, 0, 0); __builtin_amdgcn_s_setprio(0); } while (0)
; #define PG8_WAIT_V(n) asm volatile("s_waitcnt vmcnt(" #n ")" ::: "memory")
; #define PG8_WAIT_L(n) asm volatile("s_waitcnt lgkmcnt(" #n ")" ::: "memory")
; #define PG8_BAR __builtin_amdgcn_s_barrier()
; #define PG8_SCHED __builtin_amdgcn_sched_barrier(0)
; template <class Epi, class Sched, bool ALIGN_EPI = false, bool SP2 = false>
; __device__ __forceinline__ void gemm_phase(PG8_LAS unsigned char* lds, const Gemm g, const Sched& S, const Epi& E, const int tid) {
;     ...
;             PG8_WAIT_V(8); PG8_WAIT_L(0); PG8_BAR; PG8_MMA(1, 0, At, B0); PG8_MMA(1, 1, At, B1); PG8_BAR; PG8_SCHED;
;             PG8_LDB(B0, 1, 0); PG8_LDB(B1, 1, 1); PG8_SCHED; PG8_LDA(At, 1, 0); PG8_STAGE(PG8_SA(0, 1), a2 + hstep, voffA);
;             PG8_WAIT_V(8); PG8_WAIT_L(0); PG8_BAR; PG8_MMA(0, 0, At, B0); PG8_MMA(0, 1, At, B1); PG8_BAR; PG8_SCHED;
	s_waitcnt lgkmcnt(0)
	v_mfma_f32_16x16x32_bf16 v[64:67], v[138:141], v[212:215], v[64:67]
	v_mfma_f32_16x16x32_bf16 v[60:63], v[174:177], v[212:215], v[60:63]
	v_mfma_f32_16x16x32_bf16 v[48:51], v[138:141], v[220:223], v[48:51]
	v_mfma_f32_16x16x32_bf16 v[44:47], v[174:177], v[220:223], v[44:47]
	v_mfma_f32_16x16x32_bf16 v[32:35], v[138:141], v[228:231], v[32:35]
	v_mfma_f32_16x16x32_bf16 v[28:31], v[174:177], v[228:231], v[28:31]
	v_mfma_f32_16x16x32_bf16 v[16:19], v[138:141], v[240:243], v[16:19]
	v_mfma_f32_16x16x32_bf16 v[12:15], v[174:177], v[240:243], v[12:15]
	v_mfma_f32_16x16x32_bf16 v[64:67], v[170:173], v[216:219], v[64:67]
	v_mfma_f32_16x16x32_bf16 v[60:63], v[178:181], v[216:219], v[60:63]
	v_mfma_f32_16x16x32_bf16 v[48:51], v[170:173], v[224:227], v[48:51]
	v_mfma_f32_16x16x32_bf16 v[44:47], v[178:181], v[224:227], v[44:47]
	v_mfma_f32_16x16x32_bf16 v[32:35], v[170:173], v[236:239], v[32:35]
	v_mfma_f32_16x16x32_bf16 v[28:31], v[178:181], v[236:239], v[28:31]
	v_mfma_f32_16x16x32_bf16 v[16:19], v[170:173], v[244:247], v[16:19]
	v_mfma_f32_16x16x32_bf16 v[12:15], v[178:181], v[244:247], v[12:15]
	v_mfma_f32_16x16x32_bf16 v[56:59], v[182:185], v[212:215], v[56:59]
	v_mfma_f32_16x16x32_bf16 v[52:55], v[190:193], v[212:215], v[52:55]
	v_mfma_f32_16x16x32_bf16 v[40:43], v[182:185], v[220:223], v[40:43]
	v_mfma_f32_16x16x32_bf16 v[36:39], v[190:193], v[220:223], v[36:39]
	v_mfma_f32_16x16x32_bf16 v[24:27], v[182:185], v[228:231], v[24:27]
	v_mfma_f32_16x16x32_bf16 v[20:23], v[190:193], v[228:231], v[20:23]
	v_mfma_f32_16x16x32_bf16 v[8:11], v[182:185], v[240:243], v[8:11]
	v_mfma_f32_16x16x32_bf16 v[4:7], v[190:193], v[240:243], v[4:7]
	v_mfma_f32_16x16x32_bf16 v[56:59], v[186:189], v[216:219], v[56:59]
	v_mfma_f32_16x16x32_bf16 v[52:55], v[194:197], v[216:219], v[52:55]
	v_mfma_f32_16x16x32_bf16 v[40:43], v[186:189], v[224:227], v[40:43]
	v_mfma_f32_16x16x32_bf16 v[36:39], v[194:197], v[224:227], v[36:39]
	v_mfma_f32_16x16x32_bf16 v[24:27], v[186:189], v[236:239], v[24:27]
	v_mfma_f32_16x16x32_bf16 v[20:23], v[194:197], v[236:239], v[20:23]
	v_mfma_f32_16x16x32_bf16 v[8:11], v[186:189], v[244:247], v[8:11]
	v_mfma_f32_16x16x32_bf16 v[4:7], v[194:197], v[244:247], v[4:7]
	s_barrier
	s_add_i32 s12, 0, 0x18000
	v_add_u32_e32 v2, s12, v147
	s_add_i32 s14, 0, 0x1c000
	ds_read_b128 v[138:141], v2
	ds_read_b128 v[170:173], v2 offset:1024
	ds_read_b128 v[174:177], v2 offset:2048
	ds_read_b128 v[178:181], v2 offset:3072
	v_add_u32_e32 v2, s14, v147
	ds_read_b128 v[182:185], v2
	ds_read_b128 v[186:189], v2 offset:1024
	ds_read_b128 v[190:193], v2 offset:2048
	ds_read_b128 v[194:197], v2 offset:3072
	s_add_u32 s46, s46, 0x40000
	s_addc_u32 s47, s47, 0
	s_mov_b32 m0, s54
	v_lshl_add_u64 v[250:251], s[46:47], 0, v[132:133]
	ds_read_b128 v[212:215], v152 offset:32768
	ds_read_b128 v[216:219], v152 offset:33792
	ds_read_b128 v[220:223], v152 offset:34816
	ds_read_b128 v[224:227], v152 offset:35840
	ds_read_b128 v[228:231], v152 offset:36864
	ds_read_b128 v[236:239], v152 offset:37888
	ds_read_b128 v[240:243], v152 offset:38912
	ds_read_b128 v[244:247], v152 offset:39936
	global_load_lds_dwordx4 v[250:251], off
	v_lshl_add_u64 v[250:251], s[46:47], 0, v[0:1]
	s_mov_b32 m0, s55
	s_nop 0
	global_load_lds_dwordx4 v[250:251], off
	s_waitcnt vmcnt(8)
	s_waitcnt lgkmcnt(0)
	s_barrier
	s_waitcnt lgkmcnt(0)
	v_mfma_f32_16x16x32_bf16 v[128:131], v[138:141], v[212:215], v[128:131]
	v_mfma_f32_16x16x32_bf16 v[124:127], v[174:177], v[212:215], v[124:127]
	v_mfma_f32_16x16x32_bf16 v[112:115], v[138:141], v[220:223], v[112:115]
	v_mfma_f32_16x16x32_bf16 v[108:111], v[174:177], v[220:223], v[108:111]
	v_mfma_f32_16x16x32_bf16 v[96:99], v[138:141], v[228:231], v[96:99]
	v_mfma_f32_16x16x32_bf16 v[92:95], v[174:177], v[228:231], v[92:95]
	v_mfma_f32_16x16x32_bf16 v[80:83], v[138:141], v[240:243], v[80:83]
	v_mfma_f32_16x16x32_bf16 v[76:79], v[174:177], v[240:243], v[76:79]
	v_mfma_f32_16x16x32_bf16 v[128:131], v[170:173], v[216:219], v[128:131]
	v_mfma_f32_16x16x32_bf16 v[124:127], v[178:181], v[216:219], v[124:127]
	v_mfma_f32_16x16x32_bf16 v[112:115], v[170:173], v[224:227], v[112:115]
	v_mfma_f32_16x16x32_bf16 v[108:111], v[178:181], v[224:227], v[108:111]
	v_mfma_f32_16x16x32_bf16 v[96:99], v[170:173], v[236:239], v[96:99]
	v_mfma_f32_16x16x32_bf16 v[92:95], v[178:181], v[236:239], v[92:95]
	v_mfma_f32_16x16x32_bf16 v[80:83], v[170:173], v[244:247], v[80:83]
	v_mfma_f32_16x16x32_bf16 v[76:79], v[178:181], v[244:247], v[76:79]
	v_mfma_f32_16x16x32_bf16 v[120:123], v[182:185], v[212:215], v[120:123]
	v_mfma_f32_16x16x32_bf16 v[116:119], v[190:193], v[212:215], v[116:119]
	v_mfma_f32_16x16x32_bf16 v[104:107], v[182:185], v[220:223], v[104:107]
	v_mfma_f32_16x16x32_bf16 v[100:103], v[190:193], v[220:223], v[100:103]
	v_mfma_f32_16x16x32_bf16 v[88:91], v[182:185], v[228:231], v[88:91]
	v_mfma_f32_16x16x32_bf16 v[84:87], v[190:193], v[228:231], v[84:87]
	v_mfma_f32_16x16x32_bf16 v[72:75], v[182:185], v[240:243], v[72:75]
	v_mfma_f32_16x16x32_bf16 v[68:71], v[190:193], v[240:243], v[68:71]
	v_mfma_f32_16x16x32_bf16 v[120:123], v[186:189], v[216:219], v[120:123]
	v_mfma_f32_16x16x32_bf16 v[116:119], v[194:197], v[216:219], v[116:119]
	v_mfma_f32_16x16x32_bf16 v[104:107], v[186:189], v[224:227], v[104:107]
	v_mfma_f32_16x16x32_bf16 v[100:103], v[194:197], v[224:227], v[100:103]
	v_mfma_f32_16x16x32_bf16 v[88:91], v[186:189], v[236:239], v[88:91]
	v_mfma_f32_16x16x32_bf16 v[84:87], v[194:197], v[236:239], v[84:87]
	v_mfma_f32_16x16x32_bf16 v[72:75], v[186:189], v[244:247], v[72:75]
	v_mfma_f32_16x16x32_bf16 v[68:71], v[194:197], v[244:247], v[68:71]
	s_barrier
; #define PG8_STAGE(bufoff, gbase, voff) do { _Pragma("unroll") for (int _i = 0; _i < 2; ++_i) \
;         __builtin_amdgcn_global_load_lds((const unsigned*)((const char*)(gbase) + (voff)[_i]), (PG8_LAS unsigned*)(lds + (bufoff) + ldsw + _i * 8192), 16, 0, 0); } while (0)
; #define PG8_LDA(dst, b, h) do { _Pragma("unroll") for (int m = 0; m < 4; ++m) _Pragma("unroll") for (int k = 0; k < 2; ++k) dst[m][k] = *(const PG8_LAS bf16x8*)(lds + PG8_SA(b, h) + aoff + m * 2048 + k * 1024); } while (0)
; #define PG8_MMA(ai, bj, At, Bt) do { __builtin_amdgcn_s_setprio(1); _Pragma("unroll") for (int m = 0; m < 4; ++m) _Pragma("unroll") for (int n = 0; n < 2; ++n) _Pragma("unroll") for (int k = 0; k < 2; ++k) \
;         acc[ai][bj][m][n] = __builtin_amdgcn_mfma_f32_16x16x32_bf16(Bt[n][k], At[m][k], acc[ai][bj][m][n], 0, 0, 0); __builtin_amdgcn_s_setprio(0); } while (0)
; #define PG8_WAIT_V(n) asm volatile("s_waitcnt vmcnt(" #n ")" ::: "memory")
; #define PG8_WAIT_L(n) asm volatile("s_waitcnt lgkmcnt(" #n ")" ::: "memory")
; #define PG8_BAR __builtin_amdgcn_s_barrier()
; #define PG8_SCHED __builtin_amdgcn_sched_barrier(0)
; template <class Epi, class Sched, bool ALIGN_EPI = false, bool SP2 = false>
; __device__ __forceinline__ void gemm_phase(PG8_LAS unsigned char* lds, const Gemm g, const Sched& S, const Epi& E, const int tid) {
;     ...
;         for (int t = 0; t < nt; t += 2) {
;     ...
;             PG8_LDA(At, 1, 1); PG8_STAGE(PG8_SB(1, 0), b3, voffB); PG8_STAGE(PG8_SB(1, 1), b3 + hstep, voffB); PG8_STAGE(PG8_SA(1, 0), a3, voffA);
;             PG8_WAIT_V(8); PG8_WAIT_L(0); PG8_BAR; PG8_MMA(1, 0, At, B0); PG8_MMA(1, 1, At, B1); PG8_BAR; PG8_SCHED;
;     ...
;         if constexpr (ALIGN_EPI) { if (wr == 0) PG8_BAR; }
	s_add_i32 s12, s12, s6
	v_lshl_add_u64 v[142:143], v[142:143], 0, s[18:19]
	s_mov_b32 m0, s12
	ds_read_b128 v[212:215], v152 offset:49152
	ds_read_b128 v[216:219], v152 offset:50176
	ds_read_b128 v[220:223], v152 offset:51200
	ds_read_b128 v[224:227], v152 offset:52224
	ds_read_b128 v[228:231], v152 offset:53248
	ds_read_b128 v[236:239], v152 offset:54272
	ds_read_b128 v[240:243], v152 offset:55296
	ds_read_b128 v[244:247], v152 offset:56320
	global_load_lds_dwordx4 v[142:143], off
	s_add_i32 m0, s12, 0x2000
	s_add_u32 s44, s44, 0x40080
	v_lshl_add_u64 v[142:143], v[160:161], 0, s[18:19]
	s_addc_u32 s45, s45, 0
	s_add_i32 s12, s14, s6
	global_load_lds_dwordx4 v[142:143], off
	v_lshl_add_u64 v[142:143], s[44:45], 0, v[132:133]
	s_mov_b32 m0, s12
	s_nop 0
	global_load_lds_dwordx4 v[142:143], off
	v_lshl_add_u64 v[142:143], s[44:45], 0, v[0:1]
	s_add_i32 m0, s12, 0x2000
	s_nop 0
	global_load_lds_dwordx4 v[142:143], off
	v_lshl_add_u64 v[142:143], v[198:199], 0, s[18:19]
	s_mov_b32 m0, s8
	s_nop 0
	global_load_lds_dwordx4 v[142:143], off
	v_lshl_add_u64 v[142:143], v[248:249], 0, s[18:19]
	s_mov_b32 m0, s9
	s_nop 0
	global_load_lds_dwordx4 v[142:143], off
	s_waitcnt vmcnt(8)
	s_waitcnt lgkmcnt(0)
	s_barrier
	s_waitcnt lgkmcnt(0)
	v_mfma_f32_16x16x32_bf16 v[64:67], v[138:141], v[212:215], v[64:67]
	v_mfma_f32_16x16x32_bf16 v[60:63], v[174:177], v[212:215], v[60:63]
	v_mfma_f32_16x16x32_bf16 v[48:51], v[138:141], v[220:223], v[48:51]
	v_mfma_f32_16x16x32_bf16 v[44:47], v[174:177], v[220:223], v[44:47]
	v_mfma_f32_16x16x32_bf16 v[32:35], v[138:141], v[228:231], v[32:35]
	v_mfma_f32_16x16x32_bf16 v[28:31], v[174:177], v[228:231], v[28:31]
	v_mfma_f32_16x16x32_bf16 v[16:19], v[138:141], v[240:243], v[16:19]
	v_mfma_f32_16x16x32_bf16 v[12:15], v[174:177], v[240:243], v[12:15]
	v_mfma_f32_16x16x32_bf16 v[64:67], v[170:173], v[216:219], v[64:67]
	v_mfma_f32_16x16x32_bf16 v[60:63], v[178:181], v[216:219], v[60:63]
	v_mfma_f32_16x16x32_bf16 v[48:51], v[170:173], v[224:227], v[48:51]
	v_mfma_f32_16x16x32_bf16 v[44:47], v[178:181], v[224:227], v[44:47]
	v_mfma_f32_16x16x32_bf16 v[32:35], v[170:173], v[236:239], v[32:35]
	v_mfma_f32_16x16x32_bf16 v[28:31], v[178:181], v[236:239], v[28:31]
	v_mfma_f32_16x16x32_bf16 v[16:19], v[170:173], v[244:247], v[16:19]
	v_mfma_f32_16x16x32_bf16 v[12:15], v[178:181], v[244:247], v[12:15]
	v_mfma_f32_16x16x32_bf16 v[56:59], v[182:185], v[212:215], v[56:59]
	v_mfma_f32_16x16x32_bf16 v[52:55], v[190:193], v[212:215], v[52:55]
	v_mfma_f32_16x16x32_bf16 v[40:43], v[182:185], v[220:223], v[40:43]
	v_mfma_f32_16x16x32_bf16 v[36:39], v[190:193], v[220:223], v[36:39]
	v_mfma_f32_16x16x32_bf16 v[24:27], v[182:185], v[228:231], v[24:27]
	v_mfma_f32_16x16x32_bf16 v[20:23], v[190:193], v[228:231], v[20:23]
	v_mfma_f32_16x16x32_bf16 v[8:11], v[182:185], v[240:243], v[8:11]
	v_mfma_f32_16x16x32_bf16 v[4:7], v[190:193], v[240:243], v[4:7]
	v_mfma_f32_16x16x32_bf16 v[56:59], v[186:189], v[216:219], v[56:59]
	v_mfma_f32_16x16x32_bf16 v[52:55], v[194:197], v[216:219], v[52:55]
	v_mfma_f32_16x16x32_bf16 v[40:43], v[186:189], v[224:227], v[40:43]
	v_mfma_f32_16x16x32_bf16 v[36:39], v[194:197], v[224:227], v[36:39]
	v_mfma_f32_16x16x32_bf16 v[24:27], v[186:189], v[236:239], v[24:27]
	v_mfma_f32_16x16x32_bf16 v[20:23], v[194:197], v[236:239], v[20:23]
	v_mfma_f32_16x16x32_bf16 v[8:11], v[186:189], v[244:247], v[8:11]
	v_mfma_f32_16x16x32_bf16 v[4:7], v[194:197], v[244:247], v[4:7]
	s_barrier
	s_add_i32 s49, s49, 2
	s_add_u32 s36, s36, 0x100
	s_addc_u32 s37, s37, 0
	s_add_u32 s35, s35, 0x100
	s_addc_u32 s48, s48, 0
	s_cmp_gt_u32 s49, 13
	s_cbranch_scc0 .LBB0_1149
	s_and_b64 vcc, exec, s[28:29]
	s_cbranch_vccz .LBB0_1152
	s_barrier

; #define PG8_STAGE(bufoff, gbase, voff) do { _Pragma("unroll") for (int _i = 0; _i < 2; ++_i) \
;         __builtin_amdgcn_global_load_lds((const unsigned*)((const char*)(gbase) + (voff)[_i]), (PG8_LAS unsigned*)(lds + (bufoff) + ldsw + _i * 8192), 16, 0, 0); } while (0)
; #define PG8_LDA(dst, b, h) do { _Pragma("unroll") for (int m = 0; m < 4; ++m) _Pragma("unroll") for (int k = 0; k < 2; ++k) dst[m][k] = *(const PG8_LAS bf16x8*)(lds + PG8_SA(b, h) + aoff + m * 2048 + k * 1024); } while (0)
; #define PG8_LDB(dst, b, h) do { _Pragma("unroll") for (int n = 0; n < 2; ++n) _Pragma("unroll") for (int k = 0; k < 2; ++k) dst[n][k] = *(const PG8_LAS bf16x8*)(lds + PG8_SB(b, h) + boff + n * 2048 + k * 1024); } while (0)
; #define PG8_MMA(ai, bj, At, Bt) do { __builtin_amdgcn_s_setprio(1); _Pragma("unroll") for (int m = 0; m < 4; ++m) _Pragma("unroll") for (int n = 0; n < 2; ++n) _Pragma("unroll") for (int k = 0; k < 2; ++k) \
;         acc[ai][bj][m][n] = __builtin_amdgcn_mfma_f32_16x16x32_bf16(Bt[n][k], At[m][k], acc[ai][bj][m][n], 0, 0, 0); __builtin_amdgcn_s_setprio(0); } while (0)
; #define PG8_WAIT_V(n) asm volatile("s_waitcnt vmcnt(" #n ")" ::: "memory")
; #define PG8_WAIT_L(n) asm volatile("s_waitcnt lgkmcnt(" #n ")" ::: "memory")
; template <class Epi, class Sched, bool ALIGN_EPI = false, bool SP2 = false>
; __device__ __forceinline__ void gemm_phase(PG8_LAS unsigned char* lds, const Gemm g, const Sched& S, const Epi& E, const int tid) {
;     ...
;             const bool last = (t == nt - 2);
;             const char* a1 = cA + (size_t)(t + 1) * kstep;
;             const char* a2 = last ? nA : cA + (size_t)(t + 2) * kstep; const char* b2 = last ? nB : cB + (size_t)(t + 2) * kstep;
;             const char* a3 = a2 + kstep; const char* b3 = b2 + kstep;
;             if (last && has_next) S.a_ready(nxt);
;             if constexpr (SP2) {
;             PG8_LDB(B0, 0, 0); PG8_LDB(B1, 0, 1); PG8_SCHED; PG8_LDA(At, 0, 0); PG8_STAGE(PG8_SA(1, 1), a1 + hstep, voffA);
;             PG8_WAIT_V(8); PG8_WAIT_L(0); PG8_BAR; PG8_MMA(0, 0, At, B0); PG8_MMA(0, 1, At, B1); PG8_BAR; PG8_SCHED;
;             PG8_LDA(At, 0, 1); PG8_STAGE(PG8_SB(0, 0), b2, voffB); PG8_STAGE(PG8_SB(0, 1), b2 + hstep, voffB); PG8_STAGE(PG8_SA(0, 0), a2, voffA);
;             PG8_WAIT_V(8); PG8_WAIT_L(0); PG8_BAR; PG8_MMA(1, 0, At, B0); PG8_MMA(1, 1, At, B1); PG8_BAR; PG8_SCHED;
.LBB0_1263:
	s_add_u32 s12, s42, s50
	s_addc_u32 s51, s43, 0
	s_add_u32 s54, s12, 0x100
	s_addc_u32 s55, s51, 0
	s_and_b64 s[52:53], s[48:49], exec
	s_cselect_b32 s53, s29, s55
	s_cselect_b32 s52, s62, s54
	s_add_u32 s50, s34, s50
	s_addc_u32 s54, s35, 0
	s_add_u32 s50, s50, 0x100
	s_addc_u32 s54, s54, 0
	s_add_i32 s70, 0, 0x10000
	s_and_b64 s[48:49], s[48:49], exec
	s_cselect_b32 s55, s25, s54
	s_cselect_b32 s54, s69, s50
	s_add_i32 s49, 0, 0x14000
	s_add_u32 s74, s12, 0x10080
	s_addc_u32 s75, s51, 0
	s_add_i32 vcc_lo, s70, s6
	s_add_i32 m0, s14, 0xc000
	s_add_i32 s7, s14, 0xe000
	s_add_i32 s89, vcc_lo, 0x2000
	v_add_u32_e32 v152, s70, v137
	s_add_u32 s60, s54, 0x10000
	ds_read_b128 v[140:143], v152
	ds_read_b128 v[144:147], v152 offset:1024
	ds_read_b128 v[148:151], v152 offset:2048
	ds_read_b128 v[170:173], v152 offset:3072
	v_add_u32_e32 v152, s49, v137
	s_addc_u32 s61, s55, 0
	s_add_i32 vcc_hi, s49, s6
	ds_read_b128 v[174:177], v152
	ds_read_b128 v[178:181], v152 offset:1024
	ds_read_b128 v[182:185], v152 offset:2048
	ds_read_b128 v[186:189], v152 offset:3072
	s_add_i32 s92, vcc_hi, 0x2000
	s_add_i32 s93, 0, 0x18000
	s_add_i32 s91, 0, 0x1c000
	s_add_u32 s50, s52, 0x10000
	s_addc_u32 s51, s53, 0
	s_add_i32 s90, s93, s6
	s_add_i32 s71, s90, 0x2000
	s_add_u32 s48, s54, 0x10080
	s_addc_u32 s49, s55, 0
	s_add_i32 s70, s91, s6
	s_add_i32 s12, s70, 0x2000
	v_lshl_add_u64 v[152:153], s[74:75], 0, v[134:135]
	ds_read_b128 v[190:193], v139
	ds_read_b128 v[194:197], v139 offset:1024
	ds_read_b128 v[212:215], v139 offset:2048
	ds_read_b128 v[216:219], v139 offset:3072
	ds_read_b128 v[220:223], v139 offset:4096
	ds_read_b128 v[224:227], v139 offset:5120
	ds_read_b128 v[228:231], v139 offset:6144
	ds_read_b128 v[236:239], v139 offset:7168
	global_load_lds_dwordx4 v[152:153], off
	v_lshl_add_u64 v[152:153], s[74:75], 0, v[132:133]
	s_mov_b32 m0, s7
	s_nop 0
	global_load_lds_dwordx4 v[152:153], off
	s_waitcnt vmcnt(8)
	s_waitcnt lgkmcnt(0)
	s_barrier
	s_waitcnt lgkmcnt(0)
	v_mfma_f32_16x16x32_bf16 v[128:131], v[140:143], v[190:193], v[128:131]
	v_mfma_f32_16x16x32_bf16 v[124:127], v[148:151], v[190:193], v[124:127]
	v_mfma_f32_16x16x32_bf16 v[120:123], v[140:143], v[212:215], v[120:123]
	v_mfma_f32_16x16x32_bf16 v[116:119], v[148:151], v[212:215], v[116:119]
	v_mfma_f32_16x16x32_bf16 v[104:107], v[140:143], v[220:223], v[104:107]
	v_mfma_f32_16x16x32_bf16 v[100:103], v[148:151], v[220:223], v[100:103]
	v_mfma_f32_16x16x32_bf16 v[88:91], v[140:143], v[228:231], v[88:91]
	v_mfma_f32_16x16x32_bf16 v[84:87], v[148:151], v[228:231], v[84:87]
	v_mfma_f32_16x16x32_bf16 v[128:131], v[144:147], v[194:197], v[128:131]
	v_mfma_f32_16x16x32_bf16 v[124:127], v[170:173], v[194:197], v[124:127]
	v_mfma_f32_16x16x32_bf16 v[120:123], v[144:147], v[216:219], v[120:123]
	v_mfma_f32_16x16x32_bf16 v[116:119], v[170:173], v[216:219], v[116:119]
	v_mfma_f32_16x16x32_bf16 v[104:107], v[144:147], v[224:227], v[104:107]
	v_mfma_f32_16x16x32_bf16 v[100:103], v[170:173], v[224:227], v[100:103]
	v_mfma_f32_16x16x32_bf16 v[88:91], v[144:147], v[236:239], v[88:91]
	v_mfma_f32_16x16x32_bf16 v[84:87], v[170:173], v[236:239], v[84:87]
	v_mfma_f32_16x16x32_bf16 v[112:115], v[174:177], v[190:193], v[112:115]
	v_mfma_f32_16x16x32_bf16 v[108:111], v[182:185], v[190:193], v[108:111]
	v_mfma_f32_16x16x32_bf16 v[96:99], v[174:177], v[212:215], v[96:99]
	v_mfma_f32_16x16x32_bf16 v[92:95], v[182:185], v[212:215], v[92:95]
	v_mfma_f32_16x16x32_bf16 v[80:83], v[174:177], v[220:223], v[80:83]
	v_mfma_f32_16x16x32_bf16 v[76:79], v[182:185], v[220:223], v[76:79]
	v_mfma_f32_16x16x32_bf16 v[72:75], v[174:177], v[228:231], v[72:75]
	v_mfma_f32_16x16x32_bf16 v[68:71], v[182:185], v[228:231], v[68:71]
	v_mfma_f32_16x16x32_bf16 v[112:115], v[178:181], v[194:197], v[112:115]
	v_mfma_f32_16x16x32_bf16 v[108:111], v[186:189], v[194:197], v[108:111]
	v_mfma_f32_16x16x32_bf16 v[96:99], v[178:181], v[216:219], v[96:99]
	v_mfma_f32_16x16x32_bf16 v[92:95], v[186:189], v[216:219], v[92:95]
	v_mfma_f32_16x16x32_bf16 v[80:83], v[178:181], v[224:227], v[80:83]
	v_mfma_f32_16x16x32_bf16 v[76:79], v[186:189], v[224:227], v[76:79]
	v_mfma_f32_16x16x32_bf16 v[72:75], v[178:181], v[236:239], v[72:75]
	v_mfma_f32_16x16x32_bf16 v[68:71], v[186:189], v[236:239], v[68:71]
	s_barrier
	s_mov_b32 m0, vcc_lo
	v_lshl_add_u64 v[152:153], s[54:55], 0, v[2:3]
	ds_read_b128 v[190:193], v139 offset:16384
	ds_read_b128 v[194:197], v139 offset:17408
	ds_read_b128 v[212:215], v139 offset:18432
	ds_read_b128 v[216:219], v139 offset:19456
	ds_read_b128 v[220:223], v139 offset:20480
	ds_read_b128 v[224:227], v139 offset:21504
	ds_read_b128 v[228:231], v139 offset:22528
	ds_read_b128 v[236:239], v139 offset:23552
	global_load_lds_dwordx4 v[152:153], off
	v_lshl_add_u64 v[160:161], s[54:55], 0, v[0:1]
	s_mov_b32 m0, s89
	v_lshl_add_u64 v[198:199], s[60:61], 0, v[2:3]
	global_load_lds_dwordx4 v[160:161], off
	s_mov_b32 m0, vcc_hi
	v_lshl_add_u64 v[240:241], s[52:53], 0, v[132:133]
	global_load_lds_dwordx4 v[198:199], off
	v_lshl_add_u64 v[198:199], s[60:61], 0, v[0:1]
	s_mov_b32 m0, s92
	s_nop 0
	global_load_lds_dwordx4 v[198:199], off
	v_lshl_add_u64 v[198:199], s[52:53], 0, v[134:135]
	s_mov_b32 m0, s14
	s_nop 0
	global_load_lds_dwordx4 v[198:199], off
	s_mov_b32 m0, s8
	s_nop 0
	global_load_lds_dwordx4 v[240:241], off
	s_waitcnt vmcnt(8)
	s_waitcnt lgkmcnt(0)
	s_barrier
; #define PG8_STAGE(bufoff, gbase, voff) do { _Pragma("unroll") for (int _i = 0; _i < 2; ++_i) \
;         __builtin_amdgcn_global_load_lds((const unsigned*)((const char*)(gbase) + (voff)[_i]), (PG8_LAS unsigned*)(lds + (bufoff) + ldsw + _i * 8192), 16, 0, 0); } while (0)
; #define PG8_LDA(dst, b, h) do { _Pragma("unroll") for (int m = 0; m < 4; ++m) _Pragma("unroll") for (int k = 0; k < 2; ++k) dst[m][k] = *(const PG8_LAS bf16x8*)(lds + PG8_SA(b, h) + aoff + m * 2048 + k * 1024); } while (0)
; #define PG8_LDB(dst, b, h) do { _Pragma("unroll") for (int n = 0; n < 2; ++n) _Pragma("unroll") for (int k = 0; k < 2; ++k) dst[n][k] = *(const PG8_LAS bf16x8*)(lds + PG8_SB(b, h) + boff + n * 2048 + k * 1024); } while (0)
; #define PG8_MMA(ai, bj, At, Bt) do { __builtin_amdgcn_s_setprio(1); _Pragma("unroll") for (int m = 0; m < 4; ++m) _Pragma("unroll") for (int n = 0; n < 2; ++n) _Pragma("unroll") for (int k = 0; k < 2; ++k) \
;         acc[ai][bj][m][n] = __builtin_amdgcn_mfma_f32_16x16x32_bf16(Bt[n][k], At[m][k], acc[ai][bj][m][n], 0, 0, 0); __builtin_amdgcn_s_setprio(0); } while (0)
; #define PG8_WAIT_V(n) asm volatile("s_waitcnt vmcnt(" #n ")" ::: "memory")
; #define PG8_WAIT_L(n) asm volatile("s_waitcnt lgkmcnt(" #n ")" ::: "memory")
; #define PG8_BAR __builtin_amdgcn_s_barrier()
; #define PG8_SCHED __builtin_amdgcn_sched_barrier(0)
; template <class Epi, class Sched, bool ALIGN_EPI = false, bool SP2 = false>
; __device__ __forceinline__ void gemm_phase(PG8_LAS unsigned char* lds, const Gemm g, const Sched& S, const Epi& E, const int tid) {
;     ...
;             PG8_WAIT_V(8); PG8_WAIT_L(0); PG8_BAR; PG8_MMA(1, 0, At, B0); PG8_MMA(1, 1, At, B1); PG8_BAR; PG8_SCHED;
;             PG8_LDB(B0, 1, 0); PG8_LDB(B1, 1, 1); PG8_SCHED; PG8_LDA(At, 1, 0); PG8_STAGE(PG8_SA(0, 1), a2 + hstep, voffA);
;             PG8_WAIT_V(8); PG8_WAIT_L(0); PG8_BAR; PG8_MMA(0, 0, At, B0); PG8_MMA(0, 1, At, B1); PG8_BAR; PG8_SCHED;
	s_waitcnt lgkmcnt(0)
	v_mfma_f32_16x16x32_bf16 v[64:67], v[140:143], v[190:193], v[64:67]
	v_mfma_f32_16x16x32_bf16 v[60:63], v[148:151], v[190:193], v[60:63]
	v_mfma_f32_16x16x32_bf16 v[56:59], v[140:143], v[212:215], v[56:59]
	v_mfma_f32_16x16x32_bf16 v[52:55], v[148:151], v[212:215], v[52:55]
	v_mfma_f32_16x16x32_bf16 v[40:43], v[140:143], v[220:223], v[40:43]
	v_mfma_f32_16x16x32_bf16 v[36:39], v[148:151], v[220:223], v[36:39]
	v_mfma_f32_16x16x32_bf16 v[24:27], v[140:143], v[228:231], v[24:27]
	v_mfma_f32_16x16x32_bf16 v[20:23], v[148:151], v[228:231], v[20:23]
	v_mfma_f32_16x16x32_bf16 v[64:67], v[144:147], v[194:197], v[64:67]
	v_mfma_f32_16x16x32_bf16 v[60:63], v[170:173], v[194:197], v[60:63]
	v_mfma_f32_16x16x32_bf16 v[56:59], v[144:147], v[216:219], v[56:59]
	v_mfma_f32_16x16x32_bf16 v[52:55], v[170:173], v[216:219], v[52:55]
	v_mfma_f32_16x16x32_bf16 v[40:43], v[144:147], v[224:227], v[40:43]
	v_mfma_f32_16x16x32_bf16 v[36:39], v[170:173], v[224:227], v[36:39]
	v_mfma_f32_16x16x32_bf16 v[24:27], v[144:147], v[236:239], v[24:27]
	v_mfma_f32_16x16x32_bf16 v[20:23], v[170:173], v[236:239], v[20:23]
	v_mfma_f32_16x16x32_bf16 v[48:51], v[174:177], v[190:193], v[48:51]
	v_mfma_f32_16x16x32_bf16 v[44:47], v[182:185], v[190:193], v[44:47]
	v_mfma_f32_16x16x32_bf16 v[32:35], v[174:177], v[212:215], v[32:35]
	v_mfma_f32_16x16x32_bf16 v[28:31], v[182:185], v[212:215], v[28:31]
	v_mfma_f32_16x16x32_bf16 v[16:19], v[174:177], v[220:223], v[16:19]
	v_mfma_f32_16x16x32_bf16 v[12:15], v[182:185], v[220:223], v[12:15]
	v_mfma_f32_16x16x32_bf16 v[8:11], v[174:177], v[228:231], v[8:11]
	v_mfma_f32_16x16x32_bf16 v[4:7], v[182:185], v[228:231], v[4:7]
	v_mfma_f32_16x16x32_bf16 v[48:51], v[178:181], v[194:197], v[48:51]
	v_mfma_f32_16x16x32_bf16 v[44:47], v[186:189], v[194:197], v[44:47]
	v_mfma_f32_16x16x32_bf16 v[32:35], v[178:181], v[216:219], v[32:35]
	v_mfma_f32_16x16x32_bf16 v[28:31], v[186:189], v[216:219], v[28:31]
	v_mfma_f32_16x16x32_bf16 v[16:19], v[178:181], v[224:227], v[16:19]
	v_mfma_f32_16x16x32_bf16 v[12:15], v[186:189], v[224:227], v[12:15]
	v_mfma_f32_16x16x32_bf16 v[8:11], v[178:181], v[236:239], v[8:11]
	v_mfma_f32_16x16x32_bf16 v[4:7], v[186:189], v[236:239], v[4:7]
	s_barrier
	v_add_u32_e32 v169, s93, v137
	ds_read_b128 v[140:143], v169
	ds_read_b128 v[144:147], v169 offset:1024
	ds_read_b128 v[148:151], v169 offset:2048
	ds_read_b128 v[170:173], v169 offset:3072
	v_add_u32_e32 v169, s91, v137
	ds_read_b128 v[174:177], v169
	ds_read_b128 v[178:181], v169 offset:1024
	ds_read_b128 v[182:185], v169 offset:2048
	ds_read_b128 v[186:189], v169 offset:3072
	s_mov_b32 m0, s9
	v_lshl_add_u64 v[242:243], s[50:51], 0, v[134:135]
	ds_read_b128 v[190:193], v139 offset:32768
	ds_read_b128 v[194:197], v139 offset:33792
	ds_read_b128 v[212:215], v139 offset:34816
	ds_read_b128 v[216:219], v139 offset:35840
	ds_read_b128 v[220:223], v139 offset:36864
	ds_read_b128 v[224:227], v139 offset:37888
	ds_read_b128 v[228:231], v139 offset:38912
	ds_read_b128 v[236:239], v139 offset:39936
	global_load_lds_dwordx4 v[242:243], off
	v_lshl_add_u64 v[242:243], s[50:51], 0, v[132:133]
	s_mov_b32 m0, s13
	s_nop 0
	global_load_lds_dwordx4 v[242:243], off
	s_waitcnt vmcnt(8)
	s_waitcnt lgkmcnt(0)
	s_barrier
	s_waitcnt lgkmcnt(0)
	v_mfma_f32_16x16x32_bf16 v[128:131], v[140:143], v[190:193], v[128:131]
	v_mfma_f32_16x16x32_bf16 v[124:127], v[148:151], v[190:193], v[124:127]
	v_mfma_f32_16x16x32_bf16 v[120:123], v[140:143], v[212:215], v[120:123]
	v_mfma_f32_16x16x32_bf16 v[116:119], v[148:151], v[212:215], v[116:119]
	v_mfma_f32_16x16x32_bf16 v[104:107], v[140:143], v[220:223], v[104:107]
	v_mfma_f32_16x16x32_bf16 v[100:103], v[148:151], v[220:223], v[100:103]
	v_mfma_f32_16x16x32_bf16 v[88:91], v[140:143], v[228:231], v[88:91]
	v_mfma_f32_16x16x32_bf16 v[84:87], v[148:151], v[228:231], v[84:87]
	v_mfma_f32_16x16x32_bf16 v[128:131], v[144:147], v[194:197], v[128:131]
	v_mfma_f32_16x16x32_bf16 v[124:127], v[170:173], v[194:197], v[124:127]
	v_mfma_f32_16x16x32_bf16 v[120:123], v[144:147], v[216:219], v[120:123]
	v_mfma_f32_16x16x32_bf16 v[116:119], v[170:173], v[216:219], v[116:119]
	v_mfma_f32_16x16x32_bf16 v[104:107], v[144:147], v[224:227], v[104:107]
	v_mfma_f32_16x16x32_bf16 v[100:103], v[170:173], v[224:227], v[100:103]
	v_mfma_f32_16x16x32_bf16 v[88:91], v[144:147], v[236:239], v[88:91]
	v_mfma_f32_16x16x32_bf16 v[84:87], v[170:173], v[236:239], v[84:87]
	v_mfma_f32_16x16x32_bf16 v[112:115], v[174:177], v[190:193], v[112:115]
	v_mfma_f32_16x16x32_bf16 v[108:111], v[182:185], v[190:193], v[108:111]
	v_mfma_f32_16x16x32_bf16 v[96:99], v[174:177], v[212:215], v[96:99]
	v_mfma_f32_16x16x32_bf16 v[92:95], v[182:185], v[212:215], v[92:95]
	v_mfma_f32_16x16x32_bf16 v[80:83], v[174:177], v[220:223], v[80:83]
	v_mfma_f32_16x16x32_bf16 v[76:79], v[182:185], v[220:223], v[76:79]
	v_mfma_f32_16x16x32_bf16 v[72:75], v[174:177], v[228:231], v[72:75]
	v_mfma_f32_16x16x32_bf16 v[68:71], v[182:185], v[228:231], v[68:71]
	v_mfma_f32_16x16x32_bf16 v[112:115], v[178:181], v[194:197], v[112:115]
	v_mfma_f32_16x16x32_bf16 v[108:111], v[186:189], v[194:197], v[108:111]
	v_mfma_f32_16x16x32_bf16 v[96:99], v[178:181], v[216:219], v[96:99]
	v_mfma_f32_16x16x32_bf16 v[92:95], v[186:189], v[216:219], v[92:95]
	v_mfma_f32_16x16x32_bf16 v[80:83], v[178:181], v[224:227], v[80:83]
	v_mfma_f32_16x16x32_bf16 v[76:79], v[186:189], v[224:227], v[76:79]
	v_mfma_f32_16x16x32_bf16 v[72:75], v[178:181], v[236:239], v[72:75]
	v_mfma_f32_16x16x32_bf16 v[68:71], v[186:189], v[236:239], v[68:71]
	s_barrier
; #define PG8_STAGE(bufoff, gbase, voff) do { _Pragma("unroll") for (int _i = 0; _i < 2; ++_i) \
;         __builtin_amdgcn_global_load_lds((const unsigned*)((const char*)(gbase) + (voff)[_i]), (PG8_LAS unsigned*)(lds + (bufoff) + ldsw + _i * 8192), 16, 0, 0); } while (0)
; #define PG8_LDA(dst, b, h) do { _Pragma("unroll") for (int m = 0; m < 4; ++m) _Pragma("unroll") for (int k = 0; k < 2; ++k) dst[m][k] = *(const PG8_LAS bf16x8*)(lds + PG8_SA(b, h) + aoff + m * 2048 + k * 1024); } while (0)
; #define PG8_MMA(ai, bj, At, Bt) do { __builtin_amdgcn_s_setprio(1); _Pragma("unroll") for (int m = 0; m < 4; ++m) _Pragma("unroll") for (int n = 0; n < 2; ++n) _Pragma("unroll") for (int k = 0; k < 2; ++k) \
;         acc[ai][bj][m][n] = __builtin_amdgcn_mfma_f32_16x16x32_bf16(Bt[n][k], At[m][k], acc[ai][bj][m][n], 0, 0, 0); __builtin_amdgcn_s_setprio(0); } while (0)
; #define PG8_WAIT_V(n) asm volatile("s_waitcnt vmcnt(" #n ")" ::: "memory")
; #define PG8_WAIT_L(n) asm volatile("s_waitcnt lgkmcnt(" #n ")" ::: "memory")
; #define PG8_BAR __builtin_amdgcn_s_barrier()
; #define PG8_SCHED __builtin_amdgcn_sched_barrier(0)
; template <class Epi, class Sched, bool ALIGN_EPI = false, bool SP2 = false>
; __device__ __forceinline__ void gemm_phase(PG8_LAS unsigned char* lds, const Gemm g, const Sched& S, const Epi& E, const int tid) {
;     ...
;         for (int t = 0; t < nt; t += 2) {
;     ...
;             PG8_LDA(At, 1, 1); PG8_STAGE(PG8_SB(1, 0), b3, voffB); PG8_STAGE(PG8_SB(1, 1), b3 + hstep, voffB); PG8_STAGE(PG8_SA(1, 0), a3, voffA);
;             PG8_WAIT_V(8); PG8_WAIT_L(0); PG8_BAR; PG8_MMA(1, 0, At, B0); PG8_MMA(1, 1, At, B1); PG8_BAR; PG8_SCHED;
;     ...
;         if constexpr (ALIGN_EPI) { if (wr == 0) PG8_BAR; }
	s_mov_b32 m0, s90
	v_lshl_add_u64 v[152:153], v[152:153], 0, s[18:19]
	ds_read_b128 v[190:193], v139 offset:49152
	ds_read_b128 v[194:197], v139 offset:50176
	ds_read_b128 v[212:215], v139 offset:51200
	ds_read_b128 v[216:219], v139 offset:52224
	ds_read_b128 v[220:223], v139 offset:53248
	ds_read_b128 v[224:227], v139 offset:54272
	ds_read_b128 v[228:231], v139 offset:55296
	ds_read_b128 v[236:239], v139 offset:56320
	global_load_lds_dwordx4 v[152:153], off
	v_lshl_add_u64 v[152:153], v[160:161], 0, s[18:19]
	s_mov_b32 m0, s71
	s_nop 0
	global_load_lds_dwordx4 v[152:153], off
	v_lshl_add_u64 v[152:153], s[48:49], 0, v[2:3]
	s_mov_b32 m0, s70
	s_nop 0
	global_load_lds_dwordx4 v[152:153], off
	v_lshl_add_u64 v[152:153], s[48:49], 0, v[0:1]
	s_mov_b32 m0, s12
	s_nop 0
	global_load_lds_dwordx4 v[152:153], off
	v_lshl_add_u64 v[152:153], v[198:199], 0, s[18:19]
	s_mov_b32 m0, s15
	s_nop 0
	global_load_lds_dwordx4 v[152:153], off
	v_lshl_add_u64 v[152:153], v[240:241], 0, s[18:19]
	s_mov_b32 m0, s22
	s_nop 0
	global_load_lds_dwordx4 v[152:153], off
	s_waitcnt vmcnt(8)
	s_waitcnt lgkmcnt(0)
	s_barrier
	s_waitcnt lgkmcnt(0)
	v_mfma_f32_16x16x32_bf16 v[64:67], v[140:143], v[190:193], v[64:67]
	v_mfma_f32_16x16x32_bf16 v[60:63], v[148:151], v[190:193], v[60:63]
	v_mfma_f32_16x16x32_bf16 v[56:59], v[140:143], v[212:215], v[56:59]
	v_mfma_f32_16x16x32_bf16 v[52:55], v[148:151], v[212:215], v[52:55]
	v_mfma_f32_16x16x32_bf16 v[40:43], v[140:143], v[220:223], v[40:43]
	v_mfma_f32_16x16x32_bf16 v[36:39], v[148:151], v[220:223], v[36:39]
	v_mfma_f32_16x16x32_bf16 v[24:27], v[140:143], v[228:231], v[24:27]
	v_mfma_f32_16x16x32_bf16 v[20:23], v[148:151], v[228:231], v[20:23]
	v_mfma_f32_16x16x32_bf16 v[64:67], v[144:147], v[194:197], v[64:67]
	v_mfma_f32_16x16x32_bf16 v[60:63], v[170:173], v[194:197], v[60:63]
	v_mfma_f32_16x16x32_bf16 v[56:59], v[144:147], v[216:219], v[56:59]
	v_mfma_f32_16x16x32_bf16 v[52:55], v[170:173], v[216:219], v[52:55]
	v_mfma_f32_16x16x32_bf16 v[40:43], v[144:147], v[224:227], v[40:43]
	v_mfma_f32_16x16x32_bf16 v[36:39], v[170:173], v[224:227], v[36:39]
	v_mfma_f32_16x16x32_bf16 v[24:27], v[144:147], v[236:239], v[24:27]
	v_mfma_f32_16x16x32_bf16 v[20:23], v[170:173], v[236:239], v[20:23]
	v_mfma_f32_16x16x32_bf16 v[48:51], v[174:177], v[190:193], v[48:51]
	v_mfma_f32_16x16x32_bf16 v[44:47], v[182:185], v[190:193], v[44:47]
	v_mfma_f32_16x16x32_bf16 v[32:35], v[174:177], v[212:215], v[32:35]
	v_mfma_f32_16x16x32_bf16 v[28:31], v[182:185], v[212:215], v[28:31]
	v_mfma_f32_16x16x32_bf16 v[16:19], v[174:177], v[220:223], v[16:19]
	v_mfma_f32_16x16x32_bf16 v[12:15], v[182:185], v[220:223], v[12:15]
	v_mfma_f32_16x16x32_bf16 v[8:11], v[174:177], v[228:231], v[8:11]
	v_mfma_f32_16x16x32_bf16 v[4:7], v[182:185], v[228:231], v[4:7]
	v_mfma_f32_16x16x32_bf16 v[48:51], v[178:181], v[194:197], v[48:51]
	v_mfma_f32_16x16x32_bf16 v[44:47], v[186:189], v[194:197], v[44:47]
	v_mfma_f32_16x16x32_bf16 v[32:35], v[178:181], v[216:219], v[32:35]
	v_mfma_f32_16x16x32_bf16 v[28:31], v[186:189], v[216:219], v[28:31]
	v_mfma_f32_16x16x32_bf16 v[16:19], v[178:181], v[224:227], v[16:19]
	v_mfma_f32_16x16x32_bf16 v[12:15], v[186:189], v[224:227], v[12:15]
	v_mfma_f32_16x16x32_bf16 v[8:11], v[178:181], v[236:239], v[8:11]
	v_mfma_f32_16x16x32_bf16 v[4:7], v[186:189], v[236:239], v[4:7]
	s_barrier
	s_movk_i32 s50, 0x100
	s_andn2_b64 vcc, exec, s[46:47]
	s_mov_b64 s[48:49], -1
	s_mov_b64 s[46:47], 0
	s_cbranch_vccz .LBB0_1263
	s_and_b64 vcc, exec, s[20:21]
	s_cbranch_vccz .LBB0_1266
	s_barrier

; #define PG8_STAGE(bufoff, gbase, voff) do { _Pragma("unroll") for (int _i = 0; _i < 2; ++_i) \
;         __builtin_amdgcn_global_load_lds((const unsigned*)((const char*)(gbase) + (voff)[_i]), (PG8_LAS unsigned*)(lds + (bufoff) + ldsw + _i * 8192), 16, 0, 0); } while (0)
; #define PG8_LDA(dst, b, h) do { _Pragma("unroll") for (int m = 0; m < 4; ++m) _Pragma("unroll") for (int k = 0; k < 2; ++k) dst[m][k] = *(const PG8_LAS bf16x8*)(lds + PG8_SA(b, h) + aoff + m * 2048 + k * 1024); } while (0)
; #define PG8_LDB(dst, b, h) do { _Pragma("unroll") for (int n = 0; n < 2; ++n) _Pragma("unroll") for (int k = 0; k < 2; ++k) dst[n][k] = *(const PG8_LAS bf16x8*)(lds + PG8_SB(b, h) + boff + n * 2048 + k * 1024); } while (0)
; #define PG8_MMA(ai, bj, At, Bt) do { __builtin_amdgcn_s_setprio(1); _Pragma("unroll") for (int m = 0; m < 4; ++m) _Pragma("unroll") for (int n = 0; n < 2; ++n) _Pragma("unroll") for (int k = 0; k < 2; ++k) \
;         acc[ai][bj][m][n] = __builtin_amdgcn_mfma_f32_16x16x32_bf16(Bt[n][k], At[m][k], acc[ai][bj][m][n], 0, 0, 0); __builtin_amdgcn_s_setprio(0); } while (0)
; #define PG8_WAIT_V(n) asm volatile("s_waitcnt vmcnt(" #n ")" ::: "memory")
; #define PG8_WAIT_L(n) asm volatile("s_waitcnt lgkmcnt(" #n ")" ::: "memory")
; template <class Epi, class Sched, bool ALIGN_EPI = false, bool SP2 = false>
; __device__ __forceinline__ void gemm_phase(PG8_LAS unsigned char* lds, const Gemm g, const Sched& S, const Epi& E, const int tid) {
;     ...
;             const bool last = (t == nt - 2);
;             const char* a1 = cA + (size_t)(t + 1) * kstep;
;             const char* a2 = last ? nA : cA + (size_t)(t + 2) * kstep; const char* b2 = last ? nB : cB + (size_t)(t + 2) * kstep;
;             const char* a3 = a2 + kstep; const char* b3 = b2 + kstep;
;             if (last && has_next) S.a_ready(nxt);
;             if constexpr (SP2) {
;             PG8_LDB(B0, 0, 0); PG8_LDB(B1, 0, 1); PG8_SCHED; PG8_LDA(At, 0, 0); PG8_STAGE(PG8_SA(1, 1), a1 + hstep, voffA);
;             PG8_WAIT_V(8); PG8_WAIT_L(0); PG8_BAR; PG8_MMA(0, 0, At, B0); PG8_MMA(0, 1, At, B1); PG8_BAR; PG8_SCHED;
;             PG8_LDA(At, 0, 1); PG8_STAGE(PG8_SB(0, 0), b2, voffB); PG8_STAGE(PG8_SB(0, 1), b2 + hstep, voffB); PG8_STAGE(PG8_SA(0, 0), a2, voffA);
;             PG8_WAIT_V(8); PG8_WAIT_L(0); PG8_BAR; PG8_MMA(1, 0, At, B0); PG8_MMA(1, 1, At, B1); PG8_BAR; PG8_SCHED;
.LBB0_1305:
	s_add_u32 s12, s42, 0xfff00080
	s_addc_u32 s44, s43, -1
	s_add_i32 s54, 0, 0x10000
	s_cmp_eq_u32 s53, 60
	s_cselect_b32 s47, s29, s44
	s_cselect_b32 s46, s49, s12
	v_add_u32_e32 v152, s54, v141
	s_cselect_b32 s45, s25, s52
	s_cselect_b32 s44, s50, s51
	s_add_i32 s12, 0, 0x14000
	ds_read_b128 v[144:147], v152
	ds_read_b128 v[148:151], v152 offset:1024
	ds_read_b128 v[170:173], v152 offset:2048
	ds_read_b128 v[174:177], v152 offset:3072
	v_add_u32_e32 v152, s12, v141
	ds_read_b128 v[178:181], v152
	ds_read_b128 v[182:185], v152 offset:1024
	ds_read_b128 v[186:189], v152 offset:2048
	ds_read_b128 v[190:193], v152 offset:3072
	v_lshl_add_u64 v[152:153], s[42:43], 0, v[136:137]
	s_add_i32 m0, s7, 0xc000
	ds_read_b128 v[194:197], v143
	ds_read_b128 v[212:215], v143 offset:1024
	ds_read_b128 v[216:219], v143 offset:2048
	ds_read_b128 v[220:223], v143 offset:3072
	ds_read_b128 v[224:227], v143 offset:4096
	ds_read_b128 v[228:231], v143 offset:5120
	ds_read_b128 v[236:239], v143 offset:6144
	ds_read_b128 v[240:243], v143 offset:7168
	global_load_lds_dwordx4 v[152:153], off
	v_lshl_add_u64 v[152:153], s[42:43], 0, v[138:139]
	s_add_i32 m0, s7, 0xe000
	s_nop 0
	global_load_lds_dwordx4 v[152:153], off
	s_waitcnt vmcnt(8)
	s_waitcnt lgkmcnt(0)
	s_barrier
	s_waitcnt lgkmcnt(0)
	v_mfma_f32_16x16x32_bf16 v[128:131], v[144:147], v[194:197], v[128:131]
	v_mfma_f32_16x16x32_bf16 v[124:127], v[170:173], v[194:197], v[124:127]
	v_mfma_f32_16x16x32_bf16 v[120:123], v[144:147], v[216:219], v[120:123]
	v_mfma_f32_16x16x32_bf16 v[116:119], v[170:173], v[216:219], v[116:119]
	v_mfma_f32_16x16x32_bf16 v[104:107], v[144:147], v[224:227], v[104:107]
	v_mfma_f32_16x16x32_bf16 v[100:103], v[170:173], v[224:227], v[100:103]
	v_mfma_f32_16x16x32_bf16 v[88:91], v[144:147], v[236:239], v[88:91]
	v_mfma_f32_16x16x32_bf16 v[84:87], v[170:173], v[236:239], v[84:87]
	v_mfma_f32_16x16x32_bf16 v[128:131], v[148:151], v[212:215], v[128:131]
	v_mfma_f32_16x16x32_bf16 v[124:127], v[174:177], v[212:215], v[124:127]
	v_mfma_f32_16x16x32_bf16 v[120:123], v[148:151], v[220:223], v[120:123]
	v_mfma_f32_16x16x32_bf16 v[116:119], v[174:177], v[220:223], v[116:119]
	v_mfma_f32_16x16x32_bf16 v[104:107], v[148:151], v[228:231], v[104:107]
	v_mfma_f32_16x16x32_bf16 v[100:103], v[174:177], v[228:231], v[100:103]
	v_mfma_f32_16x16x32_bf16 v[88:91], v[148:151], v[240:243], v[88:91]
	v_mfma_f32_16x16x32_bf16 v[84:87], v[174:177], v[240:243], v[84:87]
	v_mfma_f32_16x16x32_bf16 v[112:115], v[178:181], v[194:197], v[112:115]
	v_mfma_f32_16x16x32_bf16 v[108:111], v[186:189], v[194:197], v[108:111]
	v_mfma_f32_16x16x32_bf16 v[96:99], v[178:181], v[216:219], v[96:99]
	v_mfma_f32_16x16x32_bf16 v[92:95], v[186:189], v[216:219], v[92:95]
	v_mfma_f32_16x16x32_bf16 v[80:83], v[178:181], v[224:227], v[80:83]
	v_mfma_f32_16x16x32_bf16 v[76:79], v[186:189], v[224:227], v[76:79]
	v_mfma_f32_16x16x32_bf16 v[72:75], v[178:181], v[236:239], v[72:75]
	v_mfma_f32_16x16x32_bf16 v[68:71], v[186:189], v[236:239], v[68:71]
	v_mfma_f32_16x16x32_bf16 v[112:115], v[182:185], v[212:215], v[112:115]
	v_mfma_f32_16x16x32_bf16 v[108:111], v[190:193], v[212:215], v[108:111]
	v_mfma_f32_16x16x32_bf16 v[96:99], v[182:185], v[220:223], v[96:99]
	v_mfma_f32_16x16x32_bf16 v[92:95], v[190:193], v[220:223], v[92:95]
	v_mfma_f32_16x16x32_bf16 v[80:83], v[182:185], v[228:231], v[80:83]
	v_mfma_f32_16x16x32_bf16 v[76:79], v[190:193], v[228:231], v[76:79]
	v_mfma_f32_16x16x32_bf16 v[72:75], v[182:185], v[240:243], v[72:75]
	v_mfma_f32_16x16x32_bf16 v[68:71], v[190:193], v[240:243], v[68:71]
	s_barrier
	s_add_i32 s54, s54, s6
	v_lshl_add_u64 v[152:153], s[44:45], 0, v[2:3]
	s_mov_b32 m0, s54
	ds_read_b128 v[194:197], v143 offset:16384
	ds_read_b128 v[212:215], v143 offset:17408
	ds_read_b128 v[216:219], v143 offset:18432
	ds_read_b128 v[220:223], v143 offset:19456
	ds_read_b128 v[224:227], v143 offset:20480
	ds_read_b128 v[228:231], v143 offset:21504
	ds_read_b128 v[236:239], v143 offset:22528
	ds_read_b128 v[240:243], v143 offset:23552
	global_load_lds_dwordx4 v[152:153], off
	s_add_i32 m0, s54, 0x2000
	s_add_u32 s54, s44, 0x100000
	v_lshl_add_u64 v[160:161], s[44:45], 0, v[0:1]
	s_addc_u32 s55, s45, 0
	s_add_i32 s12, s12, s6
	global_load_lds_dwordx4 v[160:161], off
	v_lshl_add_u64 v[198:199], s[54:55], 0, v[2:3]
	s_mov_b32 m0, s12
	v_lshl_add_u64 v[244:245], s[46:47], 0, v[132:133]
	global_load_lds_dwordx4 v[198:199], off
	v_lshl_add_u64 v[198:199], s[54:55], 0, v[0:1]
	s_add_i32 m0, s12, 0x2000
	s_nop 0
	global_load_lds_dwordx4 v[198:199], off
	v_lshl_add_u64 v[198:199], s[46:47], 0, v[134:135]
	s_mov_b32 m0, s7
	s_nop 0
	global_load_lds_dwordx4 v[198:199], off
	s_mov_b32 m0, s8
	s_nop 0
	global_load_lds_dwordx4 v[244:245], off
	s_waitcnt vmcnt(8)
	s_waitcnt lgkmcnt(0)
	s_barrier
; #define PG8_STAGE(bufoff, gbase, voff) do { _Pragma("unroll") for (int _i = 0; _i < 2; ++_i) \
;         __builtin_amdgcn_global_load_lds((const unsigned*)((const char*)(gbase) + (voff)[_i]), (PG8_LAS unsigned*)(lds + (bufoff) + ldsw + _i * 8192), 16, 0, 0); } while (0)
; #define PG8_LDA(dst, b, h) do { _Pragma("unroll") for (int m = 0; m < 4; ++m) _Pragma("unroll") for (int k = 0; k < 2; ++k) dst[m][k] = *(const PG8_LAS bf16x8*)(lds + PG8_SA(b, h) + aoff + m * 2048 + k * 1024); } while (0)
; #define PG8_LDB(dst, b, h) do { _Pragma("unroll") for (int n = 0; n < 2; ++n) _Pragma("unroll") for (int k = 0; k < 2; ++k) dst[n][k] = *(const PG8_LAS bf16x8*)(lds + PG8_SB(b, h) + boff + n * 2048 + k * 1024); } while (0)
; #define PG8_MMA(ai, bj, At, Bt) do { __builtin_amdgcn_s_setprio(1); _Pragma("unroll") for (int m = 0; m < 4; ++m) _Pragma("unroll") for (int n = 0; n < 2; ++n) _Pragma("unroll") for (int k = 0; k < 2; ++k) \
;         acc[ai][bj][m][n] = __builtin_amdgcn_mfma_f32_16x16x32_bf16(Bt[n][k], At[m][k], acc[ai][bj][m][n], 0, 0, 0); __builtin_amdgcn_s_setprio(0); } while (0)
; #define PG8_WAIT_V(n) asm volatile("s_waitcnt vmcnt(" #n ")" ::: "memory")
; #define PG8_WAIT_L(n) asm volatile("s_waitcnt lgkmcnt(" #n ")" ::: "memory")
; #define PG8_BAR __builtin_amdgcn_s_barrier()
; #define PG8_SCHED __builtin_amdgcn_sched_barrier(0)
; template <class Epi, class Sched, bool ALIGN_EPI = false, bool SP2 = false>
; __device__ __forceinline__ void gemm_phase(PG8_LAS unsigned char* lds, const Gemm g, const Sched& S, const Epi& E, const int tid) {
;     ...
;             PG8_WAIT_V(8); PG8_WAIT_L(0); PG8_BAR; PG8_MMA(1, 0, At, B0); PG8_MMA(1, 1, At, B1); PG8_BAR; PG8_SCHED;
;             PG8_LDB(B0, 1, 0); PG8_LDB(B1, 1, 1); PG8_SCHED; PG8_LDA(At, 1, 0); PG8_STAGE(PG8_SA(0, 1), a2 + hstep, voffA);
;             PG8_WAIT_V(8); PG8_WAIT_L(0); PG8_BAR; PG8_MMA(0, 0, At, B0); PG8_MMA(0, 1, At, B1); PG8_BAR; PG8_SCHED;
	s_waitcnt lgkmcnt(0)
	v_mfma_f32_16x16x32_bf16 v[64:67], v[144:147], v[194:197], v[64:67]
	v_mfma_f32_16x16x32_bf16 v[60:63], v[170:173], v[194:197], v[60:63]
	v_mfma_f32_16x16x32_bf16 v[56:59], v[144:147], v[216:219], v[56:59]
	v_mfma_f32_16x16x32_bf16 v[52:55], v[170:173], v[216:219], v[52:55]
	v_mfma_f32_16x16x32_bf16 v[40:43], v[144:147], v[224:227], v[40:43]
	v_mfma_f32_16x16x32_bf16 v[36:39], v[170:173], v[224:227], v[36:39]
	v_mfma_f32_16x16x32_bf16 v[24:27], v[144:147], v[236:239], v[24:27]
	v_mfma_f32_16x16x32_bf16 v[20:23], v[170:173], v[236:239], v[20:23]
	v_mfma_f32_16x16x32_bf16 v[64:67], v[148:151], v[212:215], v[64:67]
	v_mfma_f32_16x16x32_bf16 v[60:63], v[174:177], v[212:215], v[60:63]
	v_mfma_f32_16x16x32_bf16 v[56:59], v[148:151], v[220:223], v[56:59]
	v_mfma_f32_16x16x32_bf16 v[52:55], v[174:177], v[220:223], v[52:55]
	v_mfma_f32_16x16x32_bf16 v[40:43], v[148:151], v[228:231], v[40:43]
	v_mfma_f32_16x16x32_bf16 v[36:39], v[174:177], v[228:231], v[36:39]
	v_mfma_f32_16x16x32_bf16 v[24:27], v[148:151], v[240:243], v[24:27]
	v_mfma_f32_16x16x32_bf16 v[20:23], v[174:177], v[240:243], v[20:23]
	v_mfma_f32_16x16x32_bf16 v[48:51], v[178:181], v[194:197], v[48:51]
	v_mfma_f32_16x16x32_bf16 v[44:47], v[186:189], v[194:197], v[44:47]
	v_mfma_f32_16x16x32_bf16 v[32:35], v[178:181], v[216:219], v[32:35]
	v_mfma_f32_16x16x32_bf16 v[28:31], v[186:189], v[216:219], v[28:31]
	v_mfma_f32_16x16x32_bf16 v[16:19], v[178:181], v[224:227], v[16:19]
	v_mfma_f32_16x16x32_bf16 v[12:15], v[186:189], v[224:227], v[12:15]
	v_mfma_f32_16x16x32_bf16 v[8:11], v[178:181], v[236:239], v[8:11]
	v_mfma_f32_16x16x32_bf16 v[4:7], v[186:189], v[236:239], v[4:7]
	v_mfma_f32_16x16x32_bf16 v[48:51], v[182:185], v[212:215], v[48:51]
	v_mfma_f32_16x16x32_bf16 v[44:47], v[190:193], v[212:215], v[44:47]
	v_mfma_f32_16x16x32_bf16 v[32:35], v[182:185], v[220:223], v[32:35]
	v_mfma_f32_16x16x32_bf16 v[28:31], v[190:193], v[220:223], v[28:31]
	v_mfma_f32_16x16x32_bf16 v[16:19], v[182:185], v[228:231], v[16:19]
	v_mfma_f32_16x16x32_bf16 v[12:15], v[190:193], v[228:231], v[12:15]
	v_mfma_f32_16x16x32_bf16 v[8:11], v[182:185], v[240:243], v[8:11]
	v_mfma_f32_16x16x32_bf16 v[4:7], v[190:193], v[240:243], v[4:7]
	s_barrier
	s_add_i32 s12, 0, 0x18000
	v_add_u32_e32 v169, s12, v141
	s_add_i32 s54, 0, 0x1c000
	ds_read_b128 v[144:147], v169
	ds_read_b128 v[148:151], v169 offset:1024
	ds_read_b128 v[170:173], v169 offset:2048
	ds_read_b128 v[174:177], v169 offset:3072
	v_add_u32_e32 v169, s54, v141
	ds_read_b128 v[178:181], v169
	ds_read_b128 v[182:185], v169 offset:1024
	ds_read_b128 v[186:189], v169 offset:2048
	ds_read_b128 v[190:193], v169 offset:3072
	s_add_u32 s46, s46, 0x100000
	s_addc_u32 s47, s47, 0
	s_mov_b32 m0, s9
	v_lshl_add_u64 v[246:247], s[46:47], 0, v[134:135]
	ds_read_b128 v[194:197], v143 offset:32768
	ds_read_b128 v[212:215], v143 offset:33792
	ds_read_b128 v[216:219], v143 offset:34816
	ds_read_b128 v[220:223], v143 offset:35840
	ds_read_b128 v[224:227], v143 offset:36864
	ds_read_b128 v[228:231], v143 offset:37888
	ds_read_b128 v[236:239], v143 offset:38912
	ds_read_b128 v[240:243], v143 offset:39936
	global_load_lds_dwordx4 v[246:247], off
	v_lshl_add_u64 v[246:247], s[46:47], 0, v[132:133]
	s_mov_b32 m0, s13
	s_nop 0
	global_load_lds_dwordx4 v[246:247], off
	s_waitcnt vmcnt(8)
	s_waitcnt lgkmcnt(0)
	s_barrier
	s_waitcnt lgkmcnt(0)
	v_mfma_f32_16x16x32_bf16 v[128:131], v[144:147], v[194:197], v[128:131]
	v_mfma_f32_16x16x32_bf16 v[124:127], v[170:173], v[194:197], v[124:127]
	v_mfma_f32_16x16x32_bf16 v[120:123], v[144:147], v[216:219], v[120:123]
	v_mfma_f32_16x16x32_bf16 v[116:119], v[170:173], v[216:219], v[116:119]
	v_mfma_f32_16x16x32_bf16 v[104:107], v[144:147], v[224:227], v[104:107]
	v_mfma_f32_16x16x32_bf16 v[100:103], v[170:173], v[224:227], v[100:103]
	v_mfma_f32_16x16x32_bf16 v[88:91], v[144:147], v[236:239], v[88:91]
	v_mfma_f32_16x16x32_bf16 v[84:87], v[170:173], v[236:239], v[84:87]
	v_mfma_f32_16x16x32_bf16 v[128:131], v[148:151], v[212:215], v[128:131]
	v_mfma_f32_16x16x32_bf16 v[124:127], v[174:177], v[212:215], v[124:127]
	v_mfma_f32_16x16x32_bf16 v[120:123], v[148:151], v[220:223], v[120:123]
	v_mfma_f32_16x16x32_bf16 v[116:119], v[174:177], v[220:223], v[116:119]
	v_mfma_f32_16x16x32_bf16 v[104:107], v[148:151], v[228:231], v[104:107]
	v_mfma_f32_16x16x32_bf16 v[100:103], v[174:177], v[228:231], v[100:103]
	v_mfma_f32_16x16x32_bf16 v[88:91], v[148:151], v[240:243], v[88:91]
	v_mfma_f32_16x16x32_bf16 v[84:87], v[174:177], v[240:243], v[84:87]
	v_mfma_f32_16x16x32_bf16 v[112:115], v[178:181], v[194:197], v[112:115]
	v_mfma_f32_16x16x32_bf16 v[108:111], v[186:189], v[194:197], v[108:111]
	v_mfma_f32_16x16x32_bf16 v[96:99], v[178:181], v[216:219], v[96:99]
	v_mfma_f32_16x16x32_bf16 v[92:95], v[186:189], v[216:219], v[92:95]
	v_mfma_f32_16x16x32_bf16 v[80:83], v[178:181], v[224:227], v[80:83]
	v_mfma_f32_16x16x32_bf16 v[76:79], v[186:189], v[224:227], v[76:79]
	v_mfma_f32_16x16x32_bf16 v[72:75], v[178:181], v[236:239], v[72:75]
	v_mfma_f32_16x16x32_bf16 v[68:71], v[186:189], v[236:239], v[68:71]
	v_mfma_f32_16x16x32_bf16 v[112:115], v[182:185], v[212:215], v[112:115]
	v_mfma_f32_16x16x32_bf16 v[108:111], v[190:193], v[212:215], v[108:111]
	v_mfma_f32_16x16x32_bf16 v[96:99], v[182:185], v[220:223], v[96:99]
	v_mfma_f32_16x16x32_bf16 v[92:95], v[190:193], v[220:223], v[92:95]
	v_mfma_f32_16x16x32_bf16 v[80:83], v[182:185], v[228:231], v[80:83]
	v_mfma_f32_16x16x32_bf16 v[76:79], v[190:193], v[228:231], v[76:79]
	v_mfma_f32_16x16x32_bf16 v[72:75], v[182:185], v[240:243], v[72:75]
	v_mfma_f32_16x16x32_bf16 v[68:71], v[190:193], v[240:243], v[68:71]
	s_barrier
; #define PG8_STAGE(bufoff, gbase, voff) do { _Pragma("unroll") for (int _i = 0; _i < 2; ++_i) \
;         __builtin_amdgcn_global_load_lds((const unsigned*)((const char*)(gbase) + (voff)[_i]), (PG8_LAS unsigned*)(lds + (bufoff) + ldsw + _i * 8192), 16, 0, 0); } while (0)
; #define PG8_LDA(dst, b, h) do { _Pragma("unroll") for (int m = 0; m < 4; ++m) _Pragma("unroll") for (int k = 0; k < 2; ++k) dst[m][k] = *(const PG8_LAS bf16x8*)(lds + PG8_SA(b, h) + aoff + m * 2048 + k * 1024); } while (0)
; #define PG8_MMA(ai, bj, At, Bt) do { __builtin_amdgcn_s_setprio(1); _Pragma("unroll") for (int m = 0; m < 4; ++m) _Pragma("unroll") for (int n = 0; n < 2; ++n) _Pragma("unroll") for (int k = 0; k < 2; ++k) \
;         acc[ai][bj][m][n] = __builtin_amdgcn_mfma_f32_16x16x32_bf16(Bt[n][k], At[m][k], acc[ai][bj][m][n], 0, 0, 0); __builtin_amdgcn_s_setprio(0); } while (0)
; #define PG8_WAIT_V(n) asm volatile("s_waitcnt vmcnt(" #n ")" ::: "memory")
; #define PG8_WAIT_L(n) asm volatile("s_waitcnt lgkmcnt(" #n ")" ::: "memory")
; #define PG8_BAR __builtin_amdgcn_s_barrier()
; #define PG8_SCHED __builtin_amdgcn_sched_barrier(0)
; template <class Epi, class Sched, bool ALIGN_EPI = false, bool SP2 = false>
; __device__ __forceinline__ void gemm_phase(PG8_LAS unsigned char* lds, const Gemm g, const Sched& S, const Epi& E, const int tid) {
;     ...
;         for (int t = 0; t < nt; t += 2) {
;     ...
;             PG8_LDA(At, 1, 1); PG8_STAGE(PG8_SB(1, 0), b3, voffB); PG8_STAGE(PG8_SB(1, 1), b3 + hstep, voffB); PG8_STAGE(PG8_SA(1, 0), a3, voffA);
;             PG8_WAIT_V(8); PG8_WAIT_L(0); PG8_BAR; PG8_MMA(1, 0, At, B0); PG8_MMA(1, 1, At, B1); PG8_BAR; PG8_SCHED;
;     ...
;         if constexpr (ALIGN_EPI) { if (wr == 0) PG8_BAR; }
	s_add_i32 s12, s12, s6
	v_lshl_add_u64 v[152:153], v[152:153], 0, s[18:19]
	s_mov_b32 m0, s12
	ds_read_b128 v[194:197], v143 offset:49152
	ds_read_b128 v[212:215], v143 offset:50176
	ds_read_b128 v[216:219], v143 offset:51200
	ds_read_b128 v[220:223], v143 offset:52224
	ds_read_b128 v[224:227], v143 offset:53248
	ds_read_b128 v[228:231], v143 offset:54272
	ds_read_b128 v[236:239], v143 offset:55296
	ds_read_b128 v[240:243], v143 offset:56320
	global_load_lds_dwordx4 v[152:153], off
	s_add_i32 m0, s12, 0x2000
	s_add_u32 s44, s44, 0x100080
	v_lshl_add_u64 v[152:153], v[160:161], 0, s[18:19]
	s_addc_u32 s45, s45, 0
	s_add_i32 s12, s54, s6
	global_load_lds_dwordx4 v[152:153], off
	v_lshl_add_u64 v[152:153], s[44:45], 0, v[2:3]
	s_mov_b32 m0, s12
	s_nop 0
	global_load_lds_dwordx4 v[152:153], off
	v_lshl_add_u64 v[152:153], s[44:45], 0, v[0:1]
	s_add_i32 m0, s12, 0x2000
	s_nop 0
	global_load_lds_dwordx4 v[152:153], off
	v_lshl_add_u64 v[152:153], v[198:199], 0, s[18:19]
	s_mov_b32 m0, s15
	s_nop 0
	global_load_lds_dwordx4 v[152:153], off
	v_lshl_add_u64 v[152:153], v[244:245], 0, s[18:19]
	s_mov_b32 m0, s22
	s_nop 0
	global_load_lds_dwordx4 v[152:153], off
	s_waitcnt vmcnt(8)
	s_waitcnt lgkmcnt(0)
	s_barrier
	s_waitcnt lgkmcnt(0)
	v_mfma_f32_16x16x32_bf16 v[64:67], v[144:147], v[194:197], v[64:67]
	v_mfma_f32_16x16x32_bf16 v[60:63], v[170:173], v[194:197], v[60:63]
	v_mfma_f32_16x16x32_bf16 v[56:59], v[144:147], v[216:219], v[56:59]
	v_mfma_f32_16x16x32_bf16 v[52:55], v[170:173], v[216:219], v[52:55]
	v_mfma_f32_16x16x32_bf16 v[40:43], v[144:147], v[224:227], v[40:43]
	v_mfma_f32_16x16x32_bf16 v[36:39], v[170:173], v[224:227], v[36:39]
	v_mfma_f32_16x16x32_bf16 v[24:27], v[144:147], v[236:239], v[24:27]
	v_mfma_f32_16x16x32_bf16 v[20:23], v[170:173], v[236:239], v[20:23]
	v_mfma_f32_16x16x32_bf16 v[64:67], v[148:151], v[212:215], v[64:67]
	v_mfma_f32_16x16x32_bf16 v[60:63], v[174:177], v[212:215], v[60:63]
	v_mfma_f32_16x16x32_bf16 v[56:59], v[148:151], v[220:223], v[56:59]
	v_mfma_f32_16x16x32_bf16 v[52:55], v[174:177], v[220:223], v[52:55]
	v_mfma_f32_16x16x32_bf16 v[40:43], v[148:151], v[228:231], v[40:43]
	v_mfma_f32_16x16x32_bf16 v[36:39], v[174:177], v[228:231], v[36:39]
	v_mfma_f32_16x16x32_bf16 v[24:27], v[148:151], v[240:243], v[24:27]
	v_mfma_f32_16x16x32_bf16 v[20:23], v[174:177], v[240:243], v[20:23]
	v_mfma_f32_16x16x32_bf16 v[48:51], v[178:181], v[194:197], v[48:51]
	v_mfma_f32_16x16x32_bf16 v[44:47], v[186:189], v[194:197], v[44:47]
	v_mfma_f32_16x16x32_bf16 v[32:35], v[178:181], v[216:219], v[32:35]
	v_mfma_f32_16x16x32_bf16 v[28:31], v[186:189], v[216:219], v[28:31]
	v_mfma_f32_16x16x32_bf16 v[16:19], v[178:181], v[224:227], v[16:19]
	v_mfma_f32_16x16x32_bf16 v[12:15], v[186:189], v[224:227], v[12:15]
	v_mfma_f32_16x16x32_bf16 v[8:11], v[178:181], v[236:239], v[8:11]
	v_mfma_f32_16x16x32_bf16 v[4:7], v[186:189], v[236:239], v[4:7]
	v_mfma_f32_16x16x32_bf16 v[48:51], v[182:185], v[212:215], v[48:51]
	v_mfma_f32_16x16x32_bf16 v[44:47], v[190:193], v[212:215], v[44:47]
	v_mfma_f32_16x16x32_bf16 v[32:35], v[182:185], v[220:223], v[32:35]
	v_mfma_f32_16x16x32_bf16 v[28:31], v[190:193], v[220:223], v[28:31]
	v_mfma_f32_16x16x32_bf16 v[16:19], v[182:185], v[228:231], v[16:19]
	v_mfma_f32_16x16x32_bf16 v[12:15], v[190:193], v[228:231], v[12:15]
	v_mfma_f32_16x16x32_bf16 v[8:11], v[182:185], v[240:243], v[8:11]
	v_mfma_f32_16x16x32_bf16 v[4:7], v[190:193], v[240:243], v[4:7]
	s_barrier
	s_add_i32 s53, s53, 2
	s_add_u32 s42, s42, 0x100
	s_addc_u32 s43, s43, 0
	s_add_u32 s51, s51, 0x100
	s_addc_u32 s52, s52, 0
	s_cmp_gt_u32 s53, 61
	s_cbranch_scc0 .LBB0_1305
	s_and_b64 vcc, exec, s[20:21]
	s_cbranch_vccz .LBB0_1308
	s_barrier

; #define PG8_STAGE(bufoff, gbase, voff) do { _Pragma("unroll") for (int _i = 0; _i < 2; ++_i) \
;         __builtin_amdgcn_global_load_lds((const unsigned*)((const char*)(gbase) + (voff)[_i]), (PG8_LAS unsigned*)(lds + (bufoff) + ldsw + _i * 8192), 16, 0, 0); } while (0)
; #define PG8_LDA(dst, b, h) do { _Pragma("unroll") for (int m = 0; m < 4; ++m) _Pragma("unroll") for (int k = 0; k < 2; ++k) dst[m][k] = *(const PG8_LAS bf16x8*)(lds + PG8_SA(b, h) + aoff + m * 2048 + k * 1024); } while (0)
; #define PG8_LDB(dst, b, h) do { _Pragma("unroll") for (int n = 0; n < 2; ++n) _Pragma("unroll") for (int k = 0; k < 2; ++k) dst[n][k] = *(const PG8_LAS bf16x8*)(lds + PG8_SB(b, h) + boff + n * 2048 + k * 1024); } while (0)
; #define PG8_MMA(ai, bj, At, Bt) do { __builtin_amdgcn_s_setprio(1); _Pragma("unroll") for (int m = 0; m < 4; ++m) _Pragma("unroll") for (int n = 0; n < 2; ++n) _Pragma("unroll") for (int k = 0; k < 2; ++k) \
;         acc[ai][bj][m][n] = __builtin_amdgcn_mfma_f32_16x16x32_bf16(Bt[n][k], At[m][k], acc[ai][bj][m][n], 0, 0, 0); __builtin_amdgcn_s_setprio(0); } while (0)
; #define PG8_WAIT_V(n) asm volatile("s_waitcnt vmcnt(" #n ")" ::: "memory")
; #define PG8_WAIT_L(n) asm volatile("s_waitcnt lgkmcnt(" #n ")" ::: "memory")
; template <class Epi, class Sched, bool ALIGN_EPI = false, bool SP2 = false>
; __device__ __forceinline__ void gemm_phase(PG8_LAS unsigned char* lds, const Gemm g, const Sched& S, const Epi& E, const int tid) {
;     ...
;             const bool last = (t == nt - 2);
;             const char* a1 = cA + (size_t)(t + 1) * kstep;
;             const char* a2 = last ? nA : cA + (size_t)(t + 2) * kstep; const char* b2 = last ? nB : cB + (size_t)(t + 2) * kstep;
;             const char* a3 = a2 + kstep; const char* b3 = b2 + kstep;
;             if (last && has_next) S.a_ready(nxt);
;             if constexpr (SP2) {
;             PG8_LDB(B0, 0, 0); PG8_LDB(B1, 0, 1); PG8_SCHED; PG8_LDA(At, 0, 0); PG8_STAGE(PG8_SA(1, 1), a1 + hstep, voffA);
;             PG8_WAIT_V(8); PG8_WAIT_L(0); PG8_BAR; PG8_MMA(0, 0, At, B0); PG8_MMA(0, 1, At, B1); PG8_BAR; PG8_SCHED;
;             PG8_LDA(At, 0, 1); PG8_STAGE(PG8_SB(0, 0), b2, voffB); PG8_STAGE(PG8_SB(0, 1), b2 + hstep, voffB); PG8_STAGE(PG8_SA(0, 0), a2, voffA);
;             PG8_WAIT_V(8); PG8_WAIT_L(0); PG8_BAR; PG8_MMA(1, 0, At, B0); PG8_MMA(1, 1, At, B1); PG8_BAR; PG8_SCHED;
.LBB0_1477:
	s_add_u32 s12, s42, 0xfff00080
	s_addc_u32 s44, s43, -1
	s_add_i32 s52, 0, 0x10000
	s_cmp_eq_u32 s51, 60
	s_cselect_b32 s47, s29, s44
	s_cselect_b32 s46, s30, s12
	v_add_u32_e32 v152, s52, v141
	s_cselect_b32 s45, s25, s50
	s_cselect_b32 s44, s48, s49
	s_add_i32 s12, 0, 0x14000
	ds_read_b128 v[144:147], v152
	ds_read_b128 v[148:151], v152 offset:1024
	ds_read_b128 v[170:173], v152 offset:2048
	ds_read_b128 v[174:177], v152 offset:3072
	v_add_u32_e32 v152, s12, v141
	ds_read_b128 v[178:181], v152
	ds_read_b128 v[182:185], v152 offset:1024
	ds_read_b128 v[186:189], v152 offset:2048
	ds_read_b128 v[190:193], v152 offset:3072
	v_lshl_add_u64 v[152:153], s[42:43], 0, v[136:137]
	s_add_i32 m0, s5, 0xc000
	ds_read_b128 v[194:197], v143
	ds_read_b128 v[212:215], v143 offset:1024
	ds_read_b128 v[216:219], v143 offset:2048
	ds_read_b128 v[220:223], v143 offset:3072
	ds_read_b128 v[224:227], v143 offset:4096
	ds_read_b128 v[228:231], v143 offset:5120
	ds_read_b128 v[236:239], v143 offset:6144
	ds_read_b128 v[240:243], v143 offset:7168
	global_load_lds_dwordx4 v[152:153], off
	v_lshl_add_u64 v[152:153], s[42:43], 0, v[138:139]
	s_add_i32 m0, s5, 0xe000
	s_nop 0
	global_load_lds_dwordx4 v[152:153], off
	s_waitcnt vmcnt(8)
	s_waitcnt lgkmcnt(0)
	s_barrier
	s_waitcnt lgkmcnt(0)
	v_mfma_f32_16x16x32_bf16 v[128:131], v[144:147], v[194:197], v[128:131]
	v_mfma_f32_16x16x32_bf16 v[124:127], v[170:173], v[194:197], v[124:127]
	v_mfma_f32_16x16x32_bf16 v[120:123], v[144:147], v[216:219], v[120:123]
	v_mfma_f32_16x16x32_bf16 v[116:119], v[170:173], v[216:219], v[116:119]
	v_mfma_f32_16x16x32_bf16 v[104:107], v[144:147], v[224:227], v[104:107]
	v_mfma_f32_16x16x32_bf16 v[100:103], v[170:173], v[224:227], v[100:103]
	v_mfma_f32_16x16x32_bf16 v[88:91], v[144:147], v[236:239], v[88:91]
	v_mfma_f32_16x16x32_bf16 v[84:87], v[170:173], v[236:239], v[84:87]
	v_mfma_f32_16x16x32_bf16 v[128:131], v[148:151], v[212:215], v[128:131]
	v_mfma_f32_16x16x32_bf16 v[124:127], v[174:177], v[212:215], v[124:127]
	v_mfma_f32_16x16x32_bf16 v[120:123], v[148:151], v[220:223], v[120:123]
	v_mfma_f32_16x16x32_bf16 v[116:119], v[174:177], v[220:223], v[116:119]
	v_mfma_f32_16x16x32_bf16 v[104:107], v[148:151], v[228:231], v[104:107]
	v_mfma_f32_16x16x32_bf16 v[100:103], v[174:177], v[228:231], v[100:103]
	v_mfma_f32_16x16x32_bf16 v[88:91], v[148:151], v[240:243], v[88:91]
	v_mfma_f32_16x16x32_bf16 v[84:87], v[174:177], v[240:243], v[84:87]
	v_mfma_f32_16x16x32_bf16 v[112:115], v[178:181], v[194:197], v[112:115]
	v_mfma_f32_16x16x32_bf16 v[108:111], v[186:189], v[194:197], v[108:111]
	v_mfma_f32_16x16x32_bf16 v[96:99], v[178:181], v[216:219], v[96:99]
	v_mfma_f32_16x16x32_bf16 v[92:95], v[186:189], v[216:219], v[92:95]
	v_mfma_f32_16x16x32_bf16 v[80:83], v[178:181], v[224:227], v[80:83]
	v_mfma_f32_16x16x32_bf16 v[76:79], v[186:189], v[224:227], v[76:79]
	v_mfma_f32_16x16x32_bf16 v[72:75], v[178:181], v[236:239], v[72:75]
	v_mfma_f32_16x16x32_bf16 v[68:71], v[186:189], v[236:239], v[68:71]
	v_mfma_f32_16x16x32_bf16 v[112:115], v[182:185], v[212:215], v[112:115]
	v_mfma_f32_16x16x32_bf16 v[108:111], v[190:193], v[212:215], v[108:111]
	v_mfma_f32_16x16x32_bf16 v[96:99], v[182:185], v[220:223], v[96:99]
	v_mfma_f32_16x16x32_bf16 v[92:95], v[190:193], v[220:223], v[92:95]
	v_mfma_f32_16x16x32_bf16 v[80:83], v[182:185], v[228:231], v[80:83]
	v_mfma_f32_16x16x32_bf16 v[76:79], v[190:193], v[228:231], v[76:79]
	v_mfma_f32_16x16x32_bf16 v[72:75], v[182:185], v[240:243], v[72:75]
	v_mfma_f32_16x16x32_bf16 v[68:71], v[190:193], v[240:243], v[68:71]
	s_barrier
	s_add_i32 s52, s52, s4
	v_lshl_add_u64 v[152:153], s[44:45], 0, v[2:3]
	s_mov_b32 m0, s52
	ds_read_b128 v[194:197], v143 offset:16384
	ds_read_b128 v[212:215], v143 offset:17408
	ds_read_b128 v[216:219], v143 offset:18432
	ds_read_b128 v[220:223], v143 offset:19456
	ds_read_b128 v[224:227], v143 offset:20480
	ds_read_b128 v[228:231], v143 offset:21504
	ds_read_b128 v[236:239], v143 offset:22528
	ds_read_b128 v[240:243], v143 offset:23552
	global_load_lds_dwordx4 v[152:153], off
	s_add_i32 m0, s52, 0x2000
	s_add_u32 s52, s44, 0x100000
	v_lshl_add_u64 v[160:161], s[44:45], 0, v[0:1]
	s_addc_u32 s53, s45, 0
	s_add_i32 s12, s12, s4
	global_load_lds_dwordx4 v[160:161], off
	v_lshl_add_u64 v[198:199], s[52:53], 0, v[2:3]
	s_mov_b32 m0, s12
	v_lshl_add_u64 v[244:245], s[46:47], 0, v[132:133]
	global_load_lds_dwordx4 v[198:199], off
	v_lshl_add_u64 v[198:199], s[52:53], 0, v[0:1]
	s_add_i32 m0, s12, 0x2000
	s_nop 0
	global_load_lds_dwordx4 v[198:199], off
	v_lshl_add_u64 v[198:199], s[46:47], 0, v[134:135]
	s_mov_b32 m0, s5
	s_nop 0
	global_load_lds_dwordx4 v[198:199], off
	s_mov_b32 m0, s6
	s_nop 0
	global_load_lds_dwordx4 v[244:245], off
	s_waitcnt vmcnt(8)
	s_waitcnt lgkmcnt(0)
	s_barrier
; #define PG8_STAGE(bufoff, gbase, voff) do { _Pragma("unroll") for (int _i = 0; _i < 2; ++_i) \
;         __builtin_amdgcn_global_load_lds((const unsigned*)((const char*)(gbase) + (voff)[_i]), (PG8_LAS unsigned*)(lds + (bufoff) + ldsw + _i * 8192), 16, 0, 0); } while (0)
; #define PG8_LDA(dst, b, h) do { _Pragma("unroll") for (int m = 0; m < 4; ++m) _Pragma("unroll") for (int k = 0; k < 2; ++k) dst[m][k] = *(const PG8_LAS bf16x8*)(lds + PG8_SA(b, h) + aoff + m * 2048 + k * 1024); } while (0)
; #define PG8_LDB(dst, b, h) do { _Pragma("unroll") for (int n = 0; n < 2; ++n) _Pragma("unroll") for (int k = 0; k < 2; ++k) dst[n][k] = *(const PG8_LAS bf16x8*)(lds + PG8_SB(b, h) + boff + n * 2048 + k * 1024); } while (0)
; #define PG8_MMA(ai, bj, At, Bt) do { __builtin_amdgcn_s_setprio(1); _Pragma("unroll") for (int m = 0; m < 4; ++m) _Pragma("unroll") for (int n = 0; n < 2; ++n) _Pragma("unroll") for (int k = 0; k < 2; ++k) \
;         acc[ai][bj][m][n] = __builtin_amdgcn_mfma_f32_16x16x32_bf16(Bt[n][k], At[m][k], acc[ai][bj][m][n], 0, 0, 0); __builtin_amdgcn_s_setprio(0); } while (0)
; #define PG8_WAIT_V(n) asm volatile("s_waitcnt vmcnt(" #n ")" ::: "memory")
; #define PG8_WAIT_L(n) asm volatile("s_waitcnt lgkmcnt(" #n ")" ::: "memory")
; #define PG8_BAR __builtin_amdgcn_s_barrier()
; #define PG8_SCHED __builtin_amdgcn_sched_barrier(0)
; template <class Epi, class Sched, bool ALIGN_EPI = false, bool SP2 = false>
; __device__ __forceinline__ void gemm_phase(PG8_LAS unsigned char* lds, const Gemm g, const Sched& S, const Epi& E, const int tid) {
;     ...
;             PG8_WAIT_V(8); PG8_WAIT_L(0); PG8_BAR; PG8_MMA(1, 0, At, B0); PG8_MMA(1, 1, At, B1); PG8_BAR; PG8_SCHED;
;             PG8_LDB(B0, 1, 0); PG8_LDB(B1, 1, 1); PG8_SCHED; PG8_LDA(At, 1, 0); PG8_STAGE(PG8_SA(0, 1), a2 + hstep, voffA);
;             PG8_WAIT_V(8); PG8_WAIT_L(0); PG8_BAR; PG8_MMA(0, 0, At, B0); PG8_MMA(0, 1, At, B1); PG8_BAR; PG8_SCHED;
	s_waitcnt lgkmcnt(0)
	v_mfma_f32_16x16x32_bf16 v[64:67], v[144:147], v[194:197], v[64:67]
	v_mfma_f32_16x16x32_bf16 v[60:63], v[170:173], v[194:197], v[60:63]
	v_mfma_f32_16x16x32_bf16 v[56:59], v[144:147], v[216:219], v[56:59]
	v_mfma_f32_16x16x32_bf16 v[52:55], v[170:173], v[216:219], v[52:55]
	v_mfma_f32_16x16x32_bf16 v[40:43], v[144:147], v[224:227], v[40:43]
	v_mfma_f32_16x16x32_bf16 v[36:39], v[170:173], v[224:227], v[36:39]
	v_mfma_f32_16x16x32_bf16 v[24:27], v[144:147], v[236:239], v[24:27]
	v_mfma_f32_16x16x32_bf16 v[20:23], v[170:173], v[236:239], v[20:23]
	v_mfma_f32_16x16x32_bf16 v[64:67], v[148:151], v[212:215], v[64:67]
	v_mfma_f32_16x16x32_bf16 v[60:63], v[174:177], v[212:215], v[60:63]
	v_mfma_f32_16x16x32_bf16 v[56:59], v[148:151], v[220:223], v[56:59]
	v_mfma_f32_16x16x32_bf16 v[52:55], v[174:177], v[220:223], v[52:55]
	v_mfma_f32_16x16x32_bf16 v[40:43], v[148:151], v[228:231], v[40:43]
	v_mfma_f32_16x16x32_bf16 v[36:39], v[174:177], v[228:231], v[36:39]
	v_mfma_f32_16x16x32_bf16 v[24:27], v[148:151], v[240:243], v[24:27]
	v_mfma_f32_16x16x32_bf16 v[20:23], v[174:177], v[240:243], v[20:23]
	v_mfma_f32_16x16x32_bf16 v[48:51], v[178:181], v[194:197], v[48:51]
	v_mfma_f32_16x16x32_bf16 v[44:47], v[186:189], v[194:197], v[44:47]
	v_mfma_f32_16x16x32_bf16 v[32:35], v[178:181], v[216:219], v[32:35]
	v_mfma_f32_16x16x32_bf16 v[28:31], v[186:189], v[216:219], v[28:31]
	v_mfma_f32_16x16x32_bf16 v[16:19], v[178:181], v[224:227], v[16:19]
	v_mfma_f32_16x16x32_bf16 v[12:15], v[186:189], v[224:227], v[12:15]
	v_mfma_f32_16x16x32_bf16 v[8:11], v[178:181], v[236:239], v[8:11]
	v_mfma_f32_16x16x32_bf16 v[4:7], v[186:189], v[236:239], v[4:7]
	v_mfma_f32_16x16x32_bf16 v[48:51], v[182:185], v[212:215], v[48:51]
	v_mfma_f32_16x16x32_bf16 v[44:47], v[190:193], v[212:215], v[44:47]
	v_mfma_f32_16x16x32_bf16 v[32:35], v[182:185], v[220:223], v[32:35]
	v_mfma_f32_16x16x32_bf16 v[28:31], v[190:193], v[220:223], v[28:31]
	v_mfma_f32_16x16x32_bf16 v[16:19], v[182:185], v[228:231], v[16:19]
	v_mfma_f32_16x16x32_bf16 v[12:15], v[190:193], v[228:231], v[12:15]
	v_mfma_f32_16x16x32_bf16 v[8:11], v[182:185], v[240:243], v[8:11]
	v_mfma_f32_16x16x32_bf16 v[4:7], v[190:193], v[240:243], v[4:7]
	s_barrier
	s_add_i32 s12, 0, 0x18000
	v_add_u32_e32 v169, s12, v141
	s_add_i32 s52, 0, 0x1c000
	ds_read_b128 v[144:147], v169
	ds_read_b128 v[148:151], v169 offset:1024
	ds_read_b128 v[170:173], v169 offset:2048
	ds_read_b128 v[174:177], v169 offset:3072
	v_add_u32_e32 v169, s52, v141
	ds_read_b128 v[178:181], v169
	ds_read_b128 v[182:185], v169 offset:1024
	ds_read_b128 v[186:189], v169 offset:2048
	ds_read_b128 v[190:193], v169 offset:3072
	s_add_u32 s46, s46, 0x100000
	s_addc_u32 s47, s47, 0
	s_mov_b32 m0, s7
	v_lshl_add_u64 v[246:247], s[46:47], 0, v[134:135]
	ds_read_b128 v[194:197], v143 offset:32768
	ds_read_b128 v[212:215], v143 offset:33792
	ds_read_b128 v[216:219], v143 offset:34816
	ds_read_b128 v[220:223], v143 offset:35840
	ds_read_b128 v[224:227], v143 offset:36864
	ds_read_b128 v[228:231], v143 offset:37888
	ds_read_b128 v[236:239], v143 offset:38912
	ds_read_b128 v[240:243], v143 offset:39936
	global_load_lds_dwordx4 v[246:247], off
	v_lshl_add_u64 v[246:247], s[46:47], 0, v[132:133]
	s_mov_b32 m0, s8
	s_nop 0
	global_load_lds_dwordx4 v[246:247], off
	s_waitcnt vmcnt(8)
	s_waitcnt lgkmcnt(0)
	s_barrier
	s_waitcnt lgkmcnt(0)
	v_mfma_f32_16x16x32_bf16 v[128:131], v[144:147], v[194:197], v[128:131]
	v_mfma_f32_16x16x32_bf16 v[124:127], v[170:173], v[194:197], v[124:127]
	v_mfma_f32_16x16x32_bf16 v[120:123], v[144:147], v[216:219], v[120:123]
	v_mfma_f32_16x16x32_bf16 v[116:119], v[170:173], v[216:219], v[116:119]
	v_mfma_f32_16x16x32_bf16 v[104:107], v[144:147], v[224:227], v[104:107]
	v_mfma_f32_16x16x32_bf16 v[100:103], v[170:173], v[224:227], v[100:103]
	v_mfma_f32_16x16x32_bf16 v[88:91], v[144:147], v[236:239], v[88:91]
	v_mfma_f32_16x16x32_bf16 v[84:87], v[170:173], v[236:239], v[84:87]
	v_mfma_f32_16x16x32_bf16 v[128:131], v[148:151], v[212:215], v[128:131]
	v_mfma_f32_16x16x32_bf16 v[124:127], v[174:177], v[212:215], v[124:127]
	v_mfma_f32_16x16x32_bf16 v[120:123], v[148:151], v[220:223], v[120:123]
	v_mfma_f32_16x16x32_bf16 v[116:119], v[174:177], v[220:223], v[116:119]
	v_mfma_f32_16x16x32_bf16 v[104:107], v[148:151], v[228:231], v[104:107]
	v_mfma_f32_16x16x32_bf16 v[100:103], v[174:177], v[228:231], v[100:103]
	v_mfma_f32_16x16x32_bf16 v[88:91], v[148:151], v[240:243], v[88:91]
	v_mfma_f32_16x16x32_bf16 v[84:87], v[174:177], v[240:243], v[84:87]
	v_mfma_f32_16x16x32_bf16 v[112:115], v[178:181], v[194:197], v[112:115]
	v_mfma_f32_16x16x32_bf16 v[108:111], v[186:189], v[194:197], v[108:111]
	v_mfma_f32_16x16x32_bf16 v[96:99], v[178:181], v[216:219], v[96:99]
	v_mfma_f32_16x16x32_bf16 v[92:95], v[186:189], v[216:219], v[92:95]
	v_mfma_f32_16x16x32_bf16 v[80:83], v[178:181], v[224:227], v[80:83]
	v_mfma_f32_16x16x32_bf16 v[76:79], v[186:189], v[224:227], v[76:79]
	v_mfma_f32_16x16x32_bf16 v[72:75], v[178:181], v[236:239], v[72:75]
	v_mfma_f32_16x16x32_bf16 v[68:71], v[186:189], v[236:239], v[68:71]
	v_mfma_f32_16x16x32_bf16 v[112:115], v[182:185], v[212:215], v[112:115]
	v_mfma_f32_16x16x32_bf16 v[108:111], v[190:193], v[212:215], v[108:111]
	v_mfma_f32_16x16x32_bf16 v[96:99], v[182:185], v[220:223], v[96:99]
	v_mfma_f32_16x16x32_bf16 v[92:95], v[190:193], v[220:223], v[92:95]
	v_mfma_f32_16x16x32_bf16 v[80:83], v[182:185], v[228:231], v[80:83]
	v_mfma_f32_16x16x32_bf16 v[76:79], v[190:193], v[228:231], v[76:79]
	v_mfma_f32_16x16x32_bf16 v[72:75], v[182:185], v[240:243], v[72:75]
	v_mfma_f32_16x16x32_bf16 v[68:71], v[190:193], v[240:243], v[68:71]
	s_barrier
; #define PG8_STAGE(bufoff, gbase, voff) do { _Pragma("unroll") for (int _i = 0; _i < 2; ++_i) \
;         __builtin_amdgcn_global_load_lds((const unsigned*)((const char*)(gbase) + (voff)[_i]), (PG8_LAS unsigned*)(lds + (bufoff) + ldsw + _i * 8192), 16, 0, 0); } while (0)
; #define PG8_LDA(dst, b, h) do { _Pragma("unroll") for (int m = 0; m < 4; ++m) _Pragma("unroll") for (int k = 0; k < 2; ++k) dst[m][k] = *(const PG8_LAS bf16x8*)(lds + PG8_SA(b, h) + aoff + m * 2048 + k * 1024); } while (0)
; #define PG8_MMA(ai, bj, At, Bt) do { __builtin_amdgcn_s_setprio(1); _Pragma("unroll") for (int m = 0; m < 4; ++m) _Pragma("unroll") for (int n = 0; n < 2; ++n) _Pragma("unroll") for (int k = 0; k < 2; ++k) \
;         acc[ai][bj][m][n] = __builtin_amdgcn_mfma_f32_16x16x32_bf16(Bt[n][k], At[m][k], acc[ai][bj][m][n], 0, 0, 0); __builtin_amdgcn_s_setprio(0); } while (0)
; #define PG8_WAIT_V(n) asm volatile("s_waitcnt vmcnt(" #n ")" ::: "memory")
; #define PG8_WAIT_L(n) asm volatile("s_waitcnt lgkmcnt(" #n ")" ::: "memory")
; #define PG8_BAR __builtin_amdgcn_s_barrier()
; #define PG8_SCHED __builtin_amdgcn_sched_barrier(0)
; template <class Epi, class Sched, bool ALIGN_EPI = false, bool SP2 = false>
; __device__ __forceinline__ void gemm_phase(PG8_LAS unsigned char* lds, const Gemm g, const Sched& S, const Epi& E, const int tid) {
;     ...
;         for (int t = 0; t < nt; t += 2) {
;     ...
;             PG8_LDA(At, 1, 1); PG8_STAGE(PG8_SB(1, 0), b3, voffB); PG8_STAGE(PG8_SB(1, 1), b3 + hstep, voffB); PG8_STAGE(PG8_SA(1, 0), a3, voffA);
;             PG8_WAIT_V(8); PG8_WAIT_L(0); PG8_BAR; PG8_MMA(1, 0, At, B0); PG8_MMA(1, 1, At, B1); PG8_BAR; PG8_SCHED;
;     ...
;         if constexpr (ALIGN_EPI) { if (wr == 0) PG8_BAR; }
	s_add_i32 s12, s12, s4
	v_lshl_add_u64 v[152:153], v[152:153], 0, s[18:19]
	s_mov_b32 m0, s12
	ds_read_b128 v[194:197], v143 offset:49152
	ds_read_b128 v[212:215], v143 offset:50176
	ds_read_b128 v[216:219], v143 offset:51200
	ds_read_b128 v[220:223], v143 offset:52224
	ds_read_b128 v[224:227], v143 offset:53248
	ds_read_b128 v[228:231], v143 offset:54272
	ds_read_b128 v[236:239], v143 offset:55296
	ds_read_b128 v[240:243], v143 offset:56320
	global_load_lds_dwordx4 v[152:153], off
	s_add_i32 m0, s12, 0x2000
	s_add_u32 s44, s44, 0x100080
	v_lshl_add_u64 v[152:153], v[160:161], 0, s[18:19]
	s_addc_u32 s45, s45, 0
	s_add_i32 s12, s52, s4
	global_load_lds_dwordx4 v[152:153], off
	v_lshl_add_u64 v[152:153], s[44:45], 0, v[2:3]
	s_mov_b32 m0, s12
	s_nop 0
	global_load_lds_dwordx4 v[152:153], off
	v_lshl_add_u64 v[152:153], s[44:45], 0, v[0:1]
	s_add_i32 m0, s12, 0x2000
	s_nop 0
	global_load_lds_dwordx4 v[152:153], off
	v_lshl_add_u64 v[152:153], v[198:199], 0, s[18:19]
	s_mov_b32 m0, s9
	s_nop 0
	global_load_lds_dwordx4 v[152:153], off
	v_lshl_add_u64 v[152:153], v[244:245], 0, s[18:19]
	s_mov_b32 m0, s13
	s_nop 0
	global_load_lds_dwordx4 v[152:153], off
	s_waitcnt vmcnt(8)
	s_waitcnt lgkmcnt(0)
	s_barrier
	s_waitcnt lgkmcnt(0)
	v_mfma_f32_16x16x32_bf16 v[64:67], v[144:147], v[194:197], v[64:67]
	v_mfma_f32_16x16x32_bf16 v[60:63], v[170:173], v[194:197], v[60:63]
	v_mfma_f32_16x16x32_bf16 v[56:59], v[144:147], v[216:219], v[56:59]
	v_mfma_f32_16x16x32_bf16 v[52:55], v[170:173], v[216:219], v[52:55]
	v_mfma_f32_16x16x32_bf16 v[40:43], v[144:147], v[224:227], v[40:43]
	v_mfma_f32_16x16x32_bf16 v[36:39], v[170:173], v[224:227], v[36:39]
	v_mfma_f32_16x16x32_bf16 v[24:27], v[144:147], v[236:239], v[24:27]
	v_mfma_f32_16x16x32_bf16 v[20:23], v[170:173], v[236:239], v[20:23]
	v_mfma_f32_16x16x32_bf16 v[64:67], v[148:151], v[212:215], v[64:67]
	v_mfma_f32_16x16x32_bf16 v[60:63], v[174:177], v[212:215], v[60:63]
	v_mfma_f32_16x16x32_bf16 v[56:59], v[148:151], v[220:223], v[56:59]
	v_mfma_f32_16x16x32_bf16 v[52:55], v[174:177], v[220:223], v[52:55]
	v_mfma_f32_16x16x32_bf16 v[40:43], v[148:151], v[228:231], v[40:43]
	v_mfma_f32_16x16x32_bf16 v[36:39], v[174:177], v[228:231], v[36:39]
	v_mfma_f32_16x16x32_bf16 v[24:27], v[148:151], v[240:243], v[24:27]
	v_mfma_f32_16x16x32_bf16 v[20:23], v[174:177], v[240:243], v[20:23]
	v_mfma_f32_16x16x32_bf16 v[48:51], v[178:181], v[194:197], v[48:51]
	v_mfma_f32_16x16x32_bf16 v[44:47], v[186:189], v[194:197], v[44:47]
	v_mfma_f32_16x16x32_bf16 v[32:35], v[178:181], v[216:219], v[32:35]
	v_mfma_f32_16x16x32_bf16 v[28:31], v[186:189], v[216:219], v[28:31]
	v_mfma_f32_16x16x32_bf16 v[16:19], v[178:181], v[224:227], v[16:19]
	v_mfma_f32_16x16x32_bf16 v[12:15], v[186:189], v[224:227], v[12:15]
	v_mfma_f32_16x16x32_bf16 v[8:11], v[178:181], v[236:239], v[8:11]
	v_mfma_f32_16x16x32_bf16 v[4:7], v[186:189], v[236:239], v[4:7]
	v_mfma_f32_16x16x32_bf16 v[48:51], v[182:185], v[212:215], v[48:51]
	v_mfma_f32_16x16x32_bf16 v[44:47], v[190:193], v[212:215], v[44:47]
	v_mfma_f32_16x16x32_bf16 v[32:35], v[182:185], v[220:223], v[32:35]
	v_mfma_f32_16x16x32_bf16 v[28:31], v[190:193], v[220:223], v[28:31]
	v_mfma_f32_16x16x32_bf16 v[16:19], v[182:185], v[228:231], v[16:19]
	v_mfma_f32_16x16x32_bf16 v[12:15], v[190:193], v[228:231], v[12:15]
	v_mfma_f32_16x16x32_bf16 v[8:11], v[182:185], v[240:243], v[8:11]
	v_mfma_f32_16x16x32_bf16 v[4:7], v[190:193], v[240:243], v[4:7]
	s_barrier
	s_add_i32 s51, s51, 2
	s_add_u32 s42, s42, 0x100
	s_addc_u32 s43, s43, 0
	s_add_u32 s49, s49, 0x100
	s_addc_u32 s50, s50, 0
	s_cmp_gt_u32 s51, 61
	s_cbranch_scc0 .LBB0_1477
	s_and_b64 vcc, exec, s[20:21]
	s_cbranch_vccz .LBB0_1480
	s_barrier

; #define PG8_STAGE(bufoff, gbase, voff) do { _Pragma("unroll") for (int _i = 0; _i < 2; ++_i) \
;         __builtin_amdgcn_global_load_lds((const unsigned*)((const char*)(gbase) + (voff)[_i]), (PG8_LAS unsigned*)(lds + (bufoff) + ldsw + _i * 8192), 16, 0, 0); } while (0)
; #define PG8_LDA(dst, b, h) do { _Pragma("unroll") for (int m = 0; m < 4; ++m) _Pragma("unroll") for (int k = 0; k < 2; ++k) dst[m][k] = *(const PG8_LAS bf16x8*)(lds + PG8_SA(b, h) + aoff + m * 2048 + k * 1024); } while (0)
; #define PG8_LDB(dst, b, h) do { _Pragma("unroll") for (int n = 0; n < 2; ++n) _Pragma("unroll") for (int k = 0; k < 2; ++k) dst[n][k] = *(const PG8_LAS bf16x8*)(lds + PG8_SB(b, h) + boff + n * 2048 + k * 1024); } while (0)
; #define PG8_MMA(ai, bj, At, Bt) do { __builtin_amdgcn_s_setprio(1); _Pragma("unroll") for (int m = 0; m < 4; ++m) _Pragma("unroll") for (int n = 0; n < 2; ++n) _Pragma("unroll") for (int k = 0; k < 2; ++k) \
;         acc[ai][bj][m][n] = __builtin_amdgcn_mfma_f32_16x16x32_bf16(Bt[n][k], At[m][k], acc[ai][bj][m][n], 0, 0, 0); __builtin_amdgcn_s_setprio(0); } while (0)
; #define PG8_WAIT_V(n) asm volatile("s_waitcnt vmcnt(" #n ")" ::: "memory")
; #define PG8_WAIT_L(n) asm volatile("s_waitcnt lgkmcnt(" #n ")" ::: "memory")
; template <class Epi, class Sched, bool ALIGN_EPI = false, bool SP2 = false>
; __device__ __forceinline__ void gemm_phase(PG8_LAS unsigned char* lds, const Gemm g, const Sched& S, const Epi& E, const int tid) {
;     ...
;             const bool last = (t == nt - 2);
;             const char* a1 = cA + (size_t)(t + 1) * kstep;
;             const char* a2 = last ? nA : cA + (size_t)(t + 2) * kstep; const char* b2 = last ? nB : cB + (size_t)(t + 2) * kstep;
;             const char* a3 = a2 + kstep; const char* b3 = b2 + kstep;
;             if (last && has_next) S.a_ready(nxt);
;             if constexpr (SP2) {
;             PG8_LDB(B0, 0, 0); PG8_LDB(B1, 0, 1); PG8_SCHED; PG8_LDA(At, 0, 0); PG8_STAGE(PG8_SA(1, 1), a1 + hstep, voffA);
;             PG8_WAIT_V(8); PG8_WAIT_L(0); PG8_BAR; PG8_MMA(0, 0, At, B0); PG8_MMA(0, 1, At, B1); PG8_BAR; PG8_SCHED;
;             PG8_LDA(At, 0, 1); PG8_STAGE(PG8_SB(0, 0), b2, voffB); PG8_STAGE(PG8_SB(0, 1), b2 + hstep, voffB); PG8_STAGE(PG8_SA(0, 0), a2, voffA);
;             PG8_WAIT_V(8); PG8_WAIT_L(0); PG8_BAR; PG8_MMA(1, 0, At, B0); PG8_MMA(1, 1, At, B1); PG8_BAR; PG8_SCHED;
.LBB0_1496:
	s_add_u32 s12, s42, 0xfffc0080
	s_addc_u32 s44, s43, -1
	s_add_i32 s52, 0, 0x10000
	s_cmp_eq_u32 s51, 12
	s_cselect_b32 s47, s29, s44
	s_cselect_b32 s46, s30, s12
	v_add_u32_e32 v152, s52, v141
	s_cselect_b32 s45, s25, s50
	s_cselect_b32 s44, s48, s49
	s_add_i32 s12, 0, 0x14000
	ds_read_b128 v[144:147], v152
	ds_read_b128 v[148:151], v152 offset:1024
	ds_read_b128 v[170:173], v152 offset:2048
	ds_read_b128 v[174:177], v152 offset:3072
	v_add_u32_e32 v152, s12, v141
	ds_read_b128 v[178:181], v152
	ds_read_b128 v[182:185], v152 offset:1024
	ds_read_b128 v[186:189], v152 offset:2048
	ds_read_b128 v[190:193], v152 offset:3072
	v_lshl_add_u64 v[152:153], s[42:43], 0, v[136:137]
	s_add_i32 m0, s5, 0xc000
	ds_read_b128 v[194:197], v143
	ds_read_b128 v[212:215], v143 offset:1024
	ds_read_b128 v[216:219], v143 offset:2048
	ds_read_b128 v[220:223], v143 offset:3072
	ds_read_b128 v[224:227], v143 offset:4096
	ds_read_b128 v[228:231], v143 offset:5120
	ds_read_b128 v[236:239], v143 offset:6144
	ds_read_b128 v[240:243], v143 offset:7168
	global_load_lds_dwordx4 v[152:153], off
	v_lshl_add_u64 v[152:153], s[42:43], 0, v[138:139]
	s_add_i32 m0, s5, 0xe000
	s_nop 0
	global_load_lds_dwordx4 v[152:153], off
	s_waitcnt vmcnt(8)
	s_waitcnt lgkmcnt(0)
	s_barrier
	s_waitcnt lgkmcnt(0)
	v_mfma_f32_16x16x32_bf16 v[128:131], v[144:147], v[194:197], v[128:131]
	v_mfma_f32_16x16x32_bf16 v[124:127], v[170:173], v[194:197], v[124:127]
	v_mfma_f32_16x16x32_bf16 v[112:115], v[144:147], v[216:219], v[112:115]
	v_mfma_f32_16x16x32_bf16 v[108:111], v[170:173], v[216:219], v[108:111]
	v_mfma_f32_16x16x32_bf16 v[96:99], v[144:147], v[224:227], v[96:99]
	v_mfma_f32_16x16x32_bf16 v[92:95], v[170:173], v[224:227], v[92:95]
	v_mfma_f32_16x16x32_bf16 v[80:83], v[144:147], v[236:239], v[80:83]
	v_mfma_f32_16x16x32_bf16 v[76:79], v[170:173], v[236:239], v[76:79]
	v_mfma_f32_16x16x32_bf16 v[128:131], v[148:151], v[212:215], v[128:131]
	v_mfma_f32_16x16x32_bf16 v[124:127], v[174:177], v[212:215], v[124:127]
	v_mfma_f32_16x16x32_bf16 v[112:115], v[148:151], v[220:223], v[112:115]
	v_mfma_f32_16x16x32_bf16 v[108:111], v[174:177], v[220:223], v[108:111]
	v_mfma_f32_16x16x32_bf16 v[96:99], v[148:151], v[228:231], v[96:99]
	v_mfma_f32_16x16x32_bf16 v[92:95], v[174:177], v[228:231], v[92:95]
	v_mfma_f32_16x16x32_bf16 v[80:83], v[148:151], v[240:243], v[80:83]
	v_mfma_f32_16x16x32_bf16 v[76:79], v[174:177], v[240:243], v[76:79]
	v_mfma_f32_16x16x32_bf16 v[120:123], v[178:181], v[194:197], v[120:123]
	v_mfma_f32_16x16x32_bf16 v[116:119], v[186:189], v[194:197], v[116:119]
	v_mfma_f32_16x16x32_bf16 v[104:107], v[178:181], v[216:219], v[104:107]
	v_mfma_f32_16x16x32_bf16 v[100:103], v[186:189], v[216:219], v[100:103]
	v_mfma_f32_16x16x32_bf16 v[88:91], v[178:181], v[224:227], v[88:91]
	v_mfma_f32_16x16x32_bf16 v[84:87], v[186:189], v[224:227], v[84:87]
	v_mfma_f32_16x16x32_bf16 v[72:75], v[178:181], v[236:239], v[72:75]
	v_mfma_f32_16x16x32_bf16 v[68:71], v[186:189], v[236:239], v[68:71]
	v_mfma_f32_16x16x32_bf16 v[120:123], v[182:185], v[212:215], v[120:123]
	v_mfma_f32_16x16x32_bf16 v[116:119], v[190:193], v[212:215], v[116:119]
	v_mfma_f32_16x16x32_bf16 v[104:107], v[182:185], v[220:223], v[104:107]
	v_mfma_f32_16x16x32_bf16 v[100:103], v[190:193], v[220:223], v[100:103]
	v_mfma_f32_16x16x32_bf16 v[88:91], v[182:185], v[228:231], v[88:91]
	v_mfma_f32_16x16x32_bf16 v[84:87], v[190:193], v[228:231], v[84:87]
	v_mfma_f32_16x16x32_bf16 v[72:75], v[182:185], v[240:243], v[72:75]
	v_mfma_f32_16x16x32_bf16 v[68:71], v[190:193], v[240:243], v[68:71]
	s_barrier
	s_add_i32 s52, s52, s4
	v_lshl_add_u64 v[152:153], s[44:45], 0, v[2:3]
	s_mov_b32 m0, s52
	ds_read_b128 v[194:197], v143 offset:16384
	ds_read_b128 v[212:215], v143 offset:17408
	ds_read_b128 v[216:219], v143 offset:18432
	ds_read_b128 v[220:223], v143 offset:19456
	ds_read_b128 v[224:227], v143 offset:20480
	ds_read_b128 v[228:231], v143 offset:21504
	ds_read_b128 v[236:239], v143 offset:22528
	ds_read_b128 v[240:243], v143 offset:23552
	global_load_lds_dwordx4 v[152:153], off
	s_add_i32 m0, s52, 0x2000
	s_add_u32 s52, s44, 0x40000
	v_lshl_add_u64 v[160:161], s[44:45], 0, v[0:1]
	s_addc_u32 s53, s45, 0
	s_add_i32 s12, s12, s4
	global_load_lds_dwordx4 v[160:161], off
	v_lshl_add_u64 v[198:199], s[52:53], 0, v[2:3]
	s_mov_b32 m0, s12
	v_lshl_add_u64 v[244:245], s[46:47], 0, v[132:133]
	global_load_lds_dwordx4 v[198:199], off
	v_lshl_add_u64 v[198:199], s[52:53], 0, v[0:1]
	s_add_i32 m0, s12, 0x2000
	s_nop 0
	global_load_lds_dwordx4 v[198:199], off
	v_lshl_add_u64 v[198:199], s[46:47], 0, v[134:135]
	s_mov_b32 m0, s5
	s_nop 0
	global_load_lds_dwordx4 v[198:199], off
	s_mov_b32 m0, s6
	s_nop 0
	global_load_lds_dwordx4 v[244:245], off
	s_waitcnt vmcnt(8)
	s_waitcnt lgkmcnt(0)
	s_barrier
; #define PG8_STAGE(bufoff, gbase, voff) do { _Pragma("unroll") for (int _i = 0; _i < 2; ++_i) \
;         __builtin_amdgcn_global_load_lds((const unsigned*)((const char*)(gbase) + (voff)[_i]), (PG8_LAS unsigned*)(lds + (bufoff) + ldsw + _i * 8192), 16, 0, 0); } while (0)
; #define PG8_LDA(dst, b, h) do { _Pragma("unroll") for (int m = 0; m < 4; ++m) _Pragma("unroll") for (int k = 0; k < 2; ++k) dst[m][k] = *(const PG8_LAS bf16x8*)(lds + PG8_SA(b, h) + aoff + m * 2048 + k * 1024); } while (0)
; #define PG8_LDB(dst, b, h) do { _Pragma("unroll") for (int n = 0; n < 2; ++n) _Pragma("unroll") for (int k = 0; k < 2; ++k) dst[n][k] = *(const PG8_LAS bf16x8*)(lds + PG8_SB(b, h) + boff + n * 2048 + k * 1024); } while (0)
; #define PG8_MMA(ai, bj, At, Bt) do { __builtin_amdgcn_s_setprio(1); _Pragma("unroll") for (int m = 0; m < 4; ++m) _Pragma("unroll") for (int n = 0; n < 2; ++n) _Pragma("unroll") for (int k = 0; k < 2; ++k) \
;         acc[ai][bj][m][n] = __builtin_amdgcn_mfma_f32_16x16x32_bf16(Bt[n][k], At[m][k], acc[ai][bj][m][n], 0, 0, 0); __builtin_amdgcn_s_setprio(0); } while (0)
; #define PG8_WAIT_V(n) asm volatile("s_waitcnt vmcnt(" #n ")" ::: "memory")
; #define PG8_WAIT_L(n) asm volatile("s_waitcnt lgkmcnt(" #n ")" ::: "memory")
; #define PG8_BAR __builtin_amdgcn_s_barrier()
; #define PG8_SCHED __builtin_amdgcn_sched_barrier(0)
; template <class Epi, class Sched, bool ALIGN_EPI = false, bool SP2 = false>
; __device__ __forceinline__ void gemm_phase(PG8_LAS unsigned char* lds, const Gemm g, const Sched& S, const Epi& E, const int tid) {
;     ...
;             PG8_WAIT_V(8); PG8_WAIT_L(0); PG8_BAR; PG8_MMA(1, 0, At, B0); PG8_MMA(1, 1, At, B1); PG8_BAR; PG8_SCHED;
;             PG8_LDB(B0, 1, 0); PG8_LDB(B1, 1, 1); PG8_SCHED; PG8_LDA(At, 1, 0); PG8_STAGE(PG8_SA(0, 1), a2 + hstep, voffA);
;             PG8_WAIT_V(8); PG8_WAIT_L(0); PG8_BAR; PG8_MMA(0, 0, At, B0); PG8_MMA(0, 1, At, B1); PG8_BAR; PG8_SCHED;
	s_waitcnt lgkmcnt(0)
	v_mfma_f32_16x16x32_bf16 v[64:67], v[144:147], v[194:197], v[64:67]
	v_mfma_f32_16x16x32_bf16 v[60:63], v[170:173], v[194:197], v[60:63]
	v_mfma_f32_16x16x32_bf16 v[48:51], v[144:147], v[216:219], v[48:51]
	v_mfma_f32_16x16x32_bf16 v[44:47], v[170:173], v[216:219], v[44:47]
	v_mfma_f32_16x16x32_bf16 v[32:35], v[144:147], v[224:227], v[32:35]
	v_mfma_f32_16x16x32_bf16 v[28:31], v[170:173], v[224:227], v[28:31]
	v_mfma_f32_16x16x32_bf16 v[16:19], v[144:147], v[236:239], v[16:19]
	v_mfma_f32_16x16x32_bf16 v[12:15], v[170:173], v[236:239], v[12:15]
	v_mfma_f32_16x16x32_bf16 v[64:67], v[148:151], v[212:215], v[64:67]
	v_mfma_f32_16x16x32_bf16 v[60:63], v[174:177], v[212:215], v[60:63]
	v_mfma_f32_16x16x32_bf16 v[48:51], v[148:151], v[220:223], v[48:51]
	v_mfma_f32_16x16x32_bf16 v[44:47], v[174:177], v[220:223], v[44:47]
	v_mfma_f32_16x16x32_bf16 v[32:35], v[148:151], v[228:231], v[32:35]
	v_mfma_f32_16x16x32_bf16 v[28:31], v[174:177], v[228:231], v[28:31]
	v_mfma_f32_16x16x32_bf16 v[16:19], v[148:151], v[240:243], v[16:19]
	v_mfma_f32_16x16x32_bf16 v[12:15], v[174:177], v[240:243], v[12:15]
	v_mfma_f32_16x16x32_bf16 v[56:59], v[178:181], v[194:197], v[56:59]
	v_mfma_f32_16x16x32_bf16 v[52:55], v[186:189], v[194:197], v[52:55]
	v_mfma_f32_16x16x32_bf16 v[40:43], v[178:181], v[216:219], v[40:43]
	v_mfma_f32_16x16x32_bf16 v[36:39], v[186:189], v[216:219], v[36:39]
	v_mfma_f32_16x16x32_bf16 v[24:27], v[178:181], v[224:227], v[24:27]
	v_mfma_f32_16x16x32_bf16 v[20:23], v[186:189], v[224:227], v[20:23]
	v_mfma_f32_16x16x32_bf16 v[8:11], v[178:181], v[236:239], v[8:11]
	v_mfma_f32_16x16x32_bf16 v[4:7], v[186:189], v[236:239], v[4:7]
	v_mfma_f32_16x16x32_bf16 v[56:59], v[182:185], v[212:215], v[56:59]
	v_mfma_f32_16x16x32_bf16 v[52:55], v[190:193], v[212:215], v[52:55]
	v_mfma_f32_16x16x32_bf16 v[40:43], v[182:185], v[220:223], v[40:43]
	v_mfma_f32_16x16x32_bf16 v[36:39], v[190:193], v[220:223], v[36:39]
	v_mfma_f32_16x16x32_bf16 v[24:27], v[182:185], v[228:231], v[24:27]
	v_mfma_f32_16x16x32_bf16 v[20:23], v[190:193], v[228:231], v[20:23]
	v_mfma_f32_16x16x32_bf16 v[8:11], v[182:185], v[240:243], v[8:11]
	v_mfma_f32_16x16x32_bf16 v[4:7], v[190:193], v[240:243], v[4:7]
	s_barrier
	s_add_i32 s12, 0, 0x18000
	v_add_u32_e32 v169, s12, v141
	s_add_i32 s52, 0, 0x1c000
	ds_read_b128 v[144:147], v169
	ds_read_b128 v[148:151], v169 offset:1024
	ds_read_b128 v[170:173], v169 offset:2048
	ds_read_b128 v[174:177], v169 offset:3072
	v_add_u32_e32 v169, s52, v141
	ds_read_b128 v[178:181], v169
	ds_read_b128 v[182:185], v169 offset:1024
	ds_read_b128 v[186:189], v169 offset:2048
	ds_read_b128 v[190:193], v169 offset:3072
	s_add_u32 s46, s46, 0x40000
	s_addc_u32 s47, s47, 0
	s_mov_b32 m0, s7
	v_lshl_add_u64 v[246:247], s[46:47], 0, v[134:135]
	ds_read_b128 v[194:197], v143 offset:32768
	ds_read_b128 v[212:215], v143 offset:33792
	ds_read_b128 v[216:219], v143 offset:34816
	ds_read_b128 v[220:223], v143 offset:35840
	ds_read_b128 v[224:227], v143 offset:36864
	ds_read_b128 v[228:231], v143 offset:37888
	ds_read_b128 v[236:239], v143 offset:38912
	ds_read_b128 v[240:243], v143 offset:39936
	global_load_lds_dwordx4 v[246:247], off
	v_lshl_add_u64 v[246:247], s[46:47], 0, v[132:133]
	s_mov_b32 m0, s8
	s_nop 0
	global_load_lds_dwordx4 v[246:247], off
	s_waitcnt vmcnt(8)
	s_waitcnt lgkmcnt(0)
	s_barrier
	s_waitcnt lgkmcnt(0)
	v_mfma_f32_16x16x32_bf16 v[128:131], v[144:147], v[194:197], v[128:131]
	v_mfma_f32_16x16x32_bf16 v[124:127], v[170:173], v[194:197], v[124:127]
	v_mfma_f32_16x16x32_bf16 v[112:115], v[144:147], v[216:219], v[112:115]
	v_mfma_f32_16x16x32_bf16 v[108:111], v[170:173], v[216:219], v[108:111]
	v_mfma_f32_16x16x32_bf16 v[96:99], v[144:147], v[224:227], v[96:99]
	v_mfma_f32_16x16x32_bf16 v[92:95], v[170:173], v[224:227], v[92:95]
	v_mfma_f32_16x16x32_bf16 v[80:83], v[144:147], v[236:239], v[80:83]
	v_mfma_f32_16x16x32_bf16 v[76:79], v[170:173], v[236:239], v[76:79]
	v_mfma_f32_16x16x32_bf16 v[128:131], v[148:151], v[212:215], v[128:131]
	v_mfma_f32_16x16x32_bf16 v[124:127], v[174:177], v[212:215], v[124:127]
	v_mfma_f32_16x16x32_bf16 v[112:115], v[148:151], v[220:223], v[112:115]
	v_mfma_f32_16x16x32_bf16 v[108:111], v[174:177], v[220:223], v[108:111]
	v_mfma_f32_16x16x32_bf16 v[96:99], v[148:151], v[228:231], v[96:99]
	v_mfma_f32_16x16x32_bf16 v[92:95], v[174:177], v[228:231], v[92:95]
	v_mfma_f32_16x16x32_bf16 v[80:83], v[148:151], v[240:243], v[80:83]
	v_mfma_f32_16x16x32_bf16 v[76:79], v[174:177], v[240:243], v[76:79]
	v_mfma_f32_16x16x32_bf16 v[120:123], v[178:181], v[194:197], v[120:123]
	v_mfma_f32_16x16x32_bf16 v[116:119], v[186:189], v[194:197], v[116:119]
	v_mfma_f32_16x16x32_bf16 v[104:107], v[178:181], v[216:219], v[104:107]
	v_mfma_f32_16x16x32_bf16 v[100:103], v[186:189], v[216:219], v[100:103]
	v_mfma_f32_16x16x32_bf16 v[88:91], v[178:181], v[224:227], v[88:91]
	v_mfma_f32_16x16x32_bf16 v[84:87], v[186:189], v[224:227], v[84:87]
	v_mfma_f32_16x16x32_bf16 v[72:75], v[178:181], v[236:239], v[72:75]
	v_mfma_f32_16x16x32_bf16 v[68:71], v[186:189], v[236:239], v[68:71]
	v_mfma_f32_16x16x32_bf16 v[120:123], v[182:185], v[212:215], v[120:123]
	v_mfma_f32_16x16x32_bf16 v[116:119], v[190:193], v[212:215], v[116:119]
	v_mfma_f32_16x16x32_bf16 v[104:107], v[182:185], v[220:223], v[104:107]
	v_mfma_f32_16x16x32_bf16 v[100:103], v[190:193], v[220:223], v[100:103]
	v_mfma_f32_16x16x32_bf16 v[88:91], v[182:185], v[228:231], v[88:91]
	v_mfma_f32_16x16x32_bf16 v[84:87], v[190:193], v[228:231], v[84:87]
	v_mfma_f32_16x16x32_bf16 v[72:75], v[182:185], v[240:243], v[72:75]
	v_mfma_f32_16x16x32_bf16 v[68:71], v[190:193], v[240:243], v[68:71]
	s_barrier
; #define PG8_STAGE(bufoff, gbase, voff) do { _Pragma("unroll") for (int _i = 0; _i < 2; ++_i) \
;         __builtin_amdgcn_global_load_lds((const unsigned*)((const char*)(gbase) + (voff)[_i]), (PG8_LAS unsigned*)(lds + (bufoff) + ldsw + _i * 8192), 16, 0, 0); } while (0)
; #define PG8_LDA(dst, b, h) do { _Pragma("unroll") for (int m = 0; m < 4; ++m) _Pragma("unroll") for (int k = 0; k < 2; ++k) dst[m][k] = *(const PG8_LAS bf16x8*)(lds + PG8_SA(b, h) + aoff + m * 2048 + k * 1024); } while (0)
; #define PG8_MMA(ai, bj, At, Bt) do { __builtin_amdgcn_s_setprio(1); _Pragma("unroll") for (int m = 0; m < 4; ++m) _Pragma("unroll") for (int n = 0; n < 2; ++n) _Pragma("unroll") for (int k = 0; k < 2; ++k) \
;         acc[ai][bj][m][n] = __builtin_amdgcn_mfma_f32_16x16x32_bf16(Bt[n][k], At[m][k], acc[ai][bj][m][n], 0, 0, 0); __builtin_amdgcn_s_setprio(0); } while (0)
; #define PG8_WAIT_V(n) asm volatile("s_waitcnt vmcnt(" #n ")" ::: "memory")
; #define PG8_WAIT_L(n) asm volatile("s_waitcnt lgkmcnt(" #n ")" ::: "memory")
; #define PG8_BAR __builtin_amdgcn_s_barrier()
; #define PG8_SCHED __builtin_amdgcn_sched_barrier(0)
; template <class Epi, class Sched, bool ALIGN_EPI = false, bool SP2 = false>
; __device__ __forceinline__ void gemm_phase(PG8_LAS unsigned char* lds, const Gemm g, const Sched& S, const Epi& E, const int tid) {
;     ...
;         for (int t = 0; t < nt; t += 2) {
;     ...
;             PG8_LDA(At, 1, 1); PG8_STAGE(PG8_SB(1, 0), b3, voffB); PG8_STAGE(PG8_SB(1, 1), b3 + hstep, voffB); PG8_STAGE(PG8_SA(1, 0), a3, voffA);
;             PG8_WAIT_V(8); PG8_WAIT_L(0); PG8_BAR; PG8_MMA(1, 0, At, B0); PG8_MMA(1, 1, At, B1); PG8_BAR; PG8_SCHED;
;     ...
;         if constexpr (ALIGN_EPI) { if (wr == 0) PG8_BAR; }
	s_add_i32 s12, s12, s4
	v_lshl_add_u64 v[152:153], v[152:153], 0, s[18:19]
	s_mov_b32 m0, s12
	ds_read_b128 v[194:197], v143 offset:49152
	ds_read_b128 v[212:215], v143 offset:50176
	ds_read_b128 v[216:219], v143 offset:51200
	ds_read_b128 v[220:223], v143 offset:52224
	ds_read_b128 v[224:227], v143 offset:53248
	ds_read_b128 v[228:231], v143 offset:54272
	ds_read_b128 v[236:239], v143 offset:55296
	ds_read_b128 v[240:243], v143 offset:56320
	global_load_lds_dwordx4 v[152:153], off
	s_add_i32 m0, s12, 0x2000
	s_add_u32 s44, s44, 0x40080
	v_lshl_add_u64 v[152:153], v[160:161], 0, s[18:19]
	s_addc_u32 s45, s45, 0
	s_add_i32 s12, s52, s4
	global_load_lds_dwordx4 v[152:153], off
	v_lshl_add_u64 v[152:153], s[44:45], 0, v[2:3]
	s_mov_b32 m0, s12
	s_nop 0
	global_load_lds_dwordx4 v[152:153], off
	v_lshl_add_u64 v[152:153], s[44:45], 0, v[0:1]
	s_add_i32 m0, s12, 0x2000
	s_nop 0
	global_load_lds_dwordx4 v[152:153], off
	v_lshl_add_u64 v[152:153], v[198:199], 0, s[18:19]
	s_mov_b32 m0, s9
	s_nop 0
	global_load_lds_dwordx4 v[152:153], off
	v_lshl_add_u64 v[152:153], v[244:245], 0, s[18:19]
	s_mov_b32 m0, s13
	s_nop 0
	global_load_lds_dwordx4 v[152:153], off
	s_waitcnt vmcnt(8)
	s_waitcnt lgkmcnt(0)
	s_barrier
	s_waitcnt lgkmcnt(0)
	v_mfma_f32_16x16x32_bf16 v[64:67], v[144:147], v[194:197], v[64:67]
	v_mfma_f32_16x16x32_bf16 v[60:63], v[170:173], v[194:197], v[60:63]
	v_mfma_f32_16x16x32_bf16 v[48:51], v[144:147], v[216:219], v[48:51]
	v_mfma_f32_16x16x32_bf16 v[44:47], v[170:173], v[216:219], v[44:47]
	v_mfma_f32_16x16x32_bf16 v[32:35], v[144:147], v[224:227], v[32:35]
	v_mfma_f32_16x16x32_bf16 v[28:31], v[170:173], v[224:227], v[28:31]
	v_mfma_f32_16x16x32_bf16 v[16:19], v[144:147], v[236:239], v[16:19]
	v_mfma_f32_16x16x32_bf16 v[12:15], v[170:173], v[236:239], v[12:15]
	v_mfma_f32_16x16x32_bf16 v[64:67], v[148:151], v[212:215], v[64:67]
	v_mfma_f32_16x16x32_bf16 v[60:63], v[174:177], v[212:215], v[60:63]
	v_mfma_f32_16x16x32_bf16 v[48:51], v[148:151], v[220:223], v[48:51]
	v_mfma_f32_16x16x32_bf16 v[44:47], v[174:177], v[220:223], v[44:47]
	v_mfma_f32_16x16x32_bf16 v[32:35], v[148:151], v[228:231], v[32:35]
	v_mfma_f32_16x16x32_bf16 v[28:31], v[174:177], v[228:231], v[28:31]
	v_mfma_f32_16x16x32_bf16 v[16:19], v[148:151], v[240:243], v[16:19]
	v_mfma_f32_16x16x32_bf16 v[12:15], v[174:177], v[240:243], v[12:15]
	v_mfma_f32_16x16x32_bf16 v[56:59], v[178:181], v[194:197], v[56:59]
	v_mfma_f32_16x16x32_bf16 v[52:55], v[186:189], v[194:197], v[52:55]
	v_mfma_f32_16x16x32_bf16 v[40:43], v[178:181], v[216:219], v[40:43]
	v_mfma_f32_16x16x32_bf16 v[36:39], v[186:189], v[216:219], v[36:39]
	v_mfma_f32_16x16x32_bf16 v[24:27], v[178:181], v[224:227], v[24:27]
	v_mfma_f32_16x16x32_bf16 v[20:23], v[186:189], v[224:227], v[20:23]
	v_mfma_f32_16x16x32_bf16 v[8:11], v[178:181], v[236:239], v[8:11]
	v_mfma_f32_16x16x32_bf16 v[4:7], v[186:189], v[236:239], v[4:7]
	v_mfma_f32_16x16x32_bf16 v[56:59], v[182:185], v[212:215], v[56:59]
	v_mfma_f32_16x16x32_bf16 v[52:55], v[190:193], v[212:215], v[52:55]
	v_mfma_f32_16x16x32_bf16 v[40:43], v[182:185], v[220:223], v[40:43]
	v_mfma_f32_16x16x32_bf16 v[36:39], v[190:193], v[220:223], v[36:39]
	v_mfma_f32_16x16x32_bf16 v[24:27], v[182:185], v[228:231], v[24:27]
	v_mfma_f32_16x16x32_bf16 v[20:23], v[190:193], v[228:231], v[20:23]
	v_mfma_f32_16x16x32_bf16 v[8:11], v[182:185], v[240:243], v[8:11]
	v_mfma_f32_16x16x32_bf16 v[4:7], v[190:193], v[240:243], v[4:7]
	s_barrier
	s_add_i32 s51, s51, 2
	s_add_u32 s42, s42, 0x100
	s_addc_u32 s43, s43, 0
	s_add_u32 s49, s49, 0x100
	s_addc_u32 s50, s50, 0
	s_cmp_gt_u32 s51, 13
	s_cbranch_scc0 .LBB0_1496
	s_and_b64 vcc, exec, s[20:21]
	s_cbranch_vccz .LBB0_1499
	s_barrier

; #define PG8_STAGE(bufoff, gbase, voff) do { _Pragma("unroll") for (int _i = 0; _i < 2; ++_i) \
;         __builtin_amdgcn_global_load_lds((const unsigned*)((const char*)(gbase) + (voff)[_i]), (PG8_LAS unsigned*)(lds + (bufoff) + ldsw + _i * 8192), 16, 0, 0); } while (0)
; #define PG8_LDA(dst, b, h) do { _Pragma("unroll") for (int m = 0; m < 4; ++m) _Pragma("unroll") for (int k = 0; k < 2; ++k) dst[m][k] = *(const PG8_LAS bf16x8*)(lds + PG8_SA(b, h) + aoff + m * 2048 + k * 1024); } while (0)
; #define PG8_LDB(dst, b, h) do { _Pragma("unroll") for (int n = 0; n < 2; ++n) _Pragma("unroll") for (int k = 0; k < 2; ++k) dst[n][k] = *(const PG8_LAS bf16x8*)(lds + PG8_SB(b, h) + boff + n * 2048 + k * 1024); } while (0)
; #define PG8_MMA(ai, bj, At, Bt) do { __builtin_amdgcn_s_setprio(1); _Pragma("unroll") for (int m = 0; m < 4; ++m) _Pragma("unroll") for (int n = 0; n < 2; ++n) _Pragma("unroll") for (int k = 0; k < 2; ++k) \
;         acc[ai][bj][m][n] = __builtin_amdgcn_mfma_f32_16x16x32_bf16(Bt[n][k], At[m][k], acc[ai][bj][m][n], 0, 0, 0); __builtin_amdgcn_s_setprio(0); } while (0)
; #define PG8_WAIT_V(n) asm volatile("s_waitcnt vmcnt(" #n ")" ::: "memory")
; #define PG8_WAIT_L(n) asm volatile("s_waitcnt lgkmcnt(" #n ")" ::: "memory")
; template <class Epi, class Sched, bool ALIGN_EPI = false, bool SP2 = false>
; __device__ __forceinline__ void gemm_phase(PG8_LAS unsigned char* lds, const Gemm g, const Sched& S, const Epi& E, const int tid) {
;     ...
;             const bool last = (t == nt - 2);
;             const char* a1 = cA + (size_t)(t + 1) * kstep;
;             const char* a2 = last ? nA : cA + (size_t)(t + 2) * kstep; const char* b2 = last ? nB : cB + (size_t)(t + 2) * kstep;
;             const char* a3 = a2 + kstep; const char* b3 = b2 + kstep;
;             if (last && has_next) S.a_ready(nxt);
;             if constexpr (SP2) {
;             PG8_LDB(B0, 0, 0); PG8_LDB(B1, 0, 1); PG8_SCHED; PG8_LDA(At, 0, 0); PG8_STAGE(PG8_SA(1, 1), a1 + hstep, voffA);
;             PG8_WAIT_V(8); PG8_WAIT_L(0); PG8_BAR; PG8_MMA(0, 0, At, B0); PG8_MMA(0, 1, At, B1); PG8_BAR; PG8_SCHED;
;             PG8_LDA(At, 0, 1); PG8_STAGE(PG8_SB(0, 0), b2, voffB); PG8_STAGE(PG8_SB(0, 1), b2 + hstep, voffB); PG8_STAGE(PG8_SA(0, 0), a2, voffA);
;             PG8_WAIT_V(8); PG8_WAIT_L(0); PG8_BAR; PG8_MMA(1, 0, At, B0); PG8_MMA(1, 1, At, B1); PG8_BAR; PG8_SCHED;
.LBB0_1545:
	s_add_u32 s12, s36, 0xfffc0080
	s_addc_u32 s42, s37, -1
	s_add_i32 s50, 0, 0x10000
	s_cmp_eq_u32 s49, 12
	s_cselect_b32 s45, s27, s42
	s_cselect_b32 s44, s30, s12
	v_add_u32_e32 v152, s50, v145
	s_cselect_b32 s43, s25, s48
	s_cselect_b32 s42, s46, s47
	s_add_i32 s12, 0, 0x14000
	ds_read_b128 v[148:151], v152
	ds_read_b128 v[170:173], v152 offset:1024
	ds_read_b128 v[174:177], v152 offset:2048
	ds_read_b128 v[178:181], v152 offset:3072
	v_add_u32_e32 v152, s12, v145
	ds_read_b128 v[182:185], v152
	ds_read_b128 v[186:189], v152 offset:1024
	ds_read_b128 v[190:193], v152 offset:2048
	ds_read_b128 v[194:197], v152 offset:3072
	v_lshl_add_u64 v[152:153], s[36:37], 0, v[136:137]
	s_add_i32 m0, s5, 0xc000
	ds_read_b128 v[212:215], v147
	ds_read_b128 v[216:219], v147 offset:1024
	ds_read_b128 v[220:223], v147 offset:2048
	ds_read_b128 v[224:227], v147 offset:3072
	ds_read_b128 v[228:231], v147 offset:4096
	ds_read_b128 v[236:239], v147 offset:5120
	ds_read_b128 v[240:243], v147 offset:6144
	ds_read_b128 v[244:247], v147 offset:7168
	global_load_lds_dwordx4 v[152:153], off
	v_lshl_add_u64 v[152:153], s[36:37], 0, v[138:139]
	s_add_i32 m0, s5, 0xe000
	s_nop 0
	global_load_lds_dwordx4 v[152:153], off
	s_waitcnt vmcnt(8)
	s_waitcnt lgkmcnt(0)
	s_barrier
	s_waitcnt lgkmcnt(0)
	v_mfma_f32_16x16x32_bf16 v[128:131], v[148:151], v[212:215], v[128:131]
	v_mfma_f32_16x16x32_bf16 v[124:127], v[174:177], v[212:215], v[124:127]
	v_mfma_f32_16x16x32_bf16 v[120:123], v[148:151], v[220:223], v[120:123]
	v_mfma_f32_16x16x32_bf16 v[116:119], v[174:177], v[220:223], v[116:119]
	v_mfma_f32_16x16x32_bf16 v[104:107], v[148:151], v[228:231], v[104:107]
	v_mfma_f32_16x16x32_bf16 v[100:103], v[174:177], v[228:231], v[100:103]
	v_mfma_f32_16x16x32_bf16 v[88:91], v[148:151], v[240:243], v[88:91]
	v_mfma_f32_16x16x32_bf16 v[84:87], v[174:177], v[240:243], v[84:87]
	v_mfma_f32_16x16x32_bf16 v[128:131], v[170:173], v[216:219], v[128:131]
	v_mfma_f32_16x16x32_bf16 v[124:127], v[178:181], v[216:219], v[124:127]
	v_mfma_f32_16x16x32_bf16 v[120:123], v[170:173], v[224:227], v[120:123]
	v_mfma_f32_16x16x32_bf16 v[116:119], v[178:181], v[224:227], v[116:119]
	v_mfma_f32_16x16x32_bf16 v[104:107], v[170:173], v[236:239], v[104:107]
	v_mfma_f32_16x16x32_bf16 v[100:103], v[178:181], v[236:239], v[100:103]
	v_mfma_f32_16x16x32_bf16 v[88:91], v[170:173], v[244:247], v[88:91]
	v_mfma_f32_16x16x32_bf16 v[84:87], v[178:181], v[244:247], v[84:87]
	v_mfma_f32_16x16x32_bf16 v[112:115], v[182:185], v[212:215], v[112:115]
	v_mfma_f32_16x16x32_bf16 v[108:111], v[190:193], v[212:215], v[108:111]
	v_mfma_f32_16x16x32_bf16 v[96:99], v[182:185], v[220:223], v[96:99]
	v_mfma_f32_16x16x32_bf16 v[92:95], v[190:193], v[220:223], v[92:95]
	v_mfma_f32_16x16x32_bf16 v[80:83], v[182:185], v[228:231], v[80:83]
	v_mfma_f32_16x16x32_bf16 v[76:79], v[190:193], v[228:231], v[76:79]
	v_mfma_f32_16x16x32_bf16 v[72:75], v[182:185], v[240:243], v[72:75]
	v_mfma_f32_16x16x32_bf16 v[68:71], v[190:193], v[240:243], v[68:71]
	v_mfma_f32_16x16x32_bf16 v[112:115], v[186:189], v[216:219], v[112:115]
	v_mfma_f32_16x16x32_bf16 v[108:111], v[194:197], v[216:219], v[108:111]
	v_mfma_f32_16x16x32_bf16 v[96:99], v[186:189], v[224:227], v[96:99]
	v_mfma_f32_16x16x32_bf16 v[92:95], v[194:197], v[224:227], v[92:95]
	v_mfma_f32_16x16x32_bf16 v[80:83], v[186:189], v[236:239], v[80:83]
	v_mfma_f32_16x16x32_bf16 v[76:79], v[194:197], v[236:239], v[76:79]
	v_mfma_f32_16x16x32_bf16 v[72:75], v[186:189], v[244:247], v[72:75]
	v_mfma_f32_16x16x32_bf16 v[68:71], v[194:197], v[244:247], v[68:71]
	s_barrier
	s_add_i32 s50, s50, s4
	v_lshl_add_u64 v[152:153], s[42:43], 0, v[2:3]
	s_mov_b32 m0, s50
	ds_read_b128 v[212:215], v147 offset:16384
	ds_read_b128 v[216:219], v147 offset:17408
	ds_read_b128 v[220:223], v147 offset:18432
	ds_read_b128 v[224:227], v147 offset:19456
	ds_read_b128 v[228:231], v147 offset:20480
	ds_read_b128 v[236:239], v147 offset:21504
	ds_read_b128 v[240:243], v147 offset:22528
	ds_read_b128 v[244:247], v147 offset:23552
	global_load_lds_dwordx4 v[152:153], off
	s_add_i32 m0, s50, 0x2000
	s_add_u32 s50, s42, 0x40000
	v_lshl_add_u64 v[198:199], s[42:43], 0, v[0:1]
	s_addc_u32 s51, s43, 0
	s_add_i32 s12, s12, s4
	global_load_lds_dwordx4 v[198:199], off
	v_lshl_add_u64 v[248:249], s[50:51], 0, v[2:3]
	s_mov_b32 m0, s12
	v_lshl_add_u64 v[250:251], s[44:45], 0, v[132:133]
	global_load_lds_dwordx4 v[248:249], off
	v_lshl_add_u64 v[248:249], s[50:51], 0, v[0:1]
	s_add_i32 m0, s12, 0x2000
	s_nop 0
	global_load_lds_dwordx4 v[248:249], off
	v_lshl_add_u64 v[248:249], s[44:45], 0, v[134:135]
	s_mov_b32 m0, s5
	s_nop 0
	global_load_lds_dwordx4 v[248:249], off
	s_mov_b32 m0, s6
	s_nop 0
	global_load_lds_dwordx4 v[250:251], off
	s_waitcnt vmcnt(8)
	s_waitcnt lgkmcnt(0)
	s_barrier
; #define PG8_STAGE(bufoff, gbase, voff) do { _Pragma("unroll") for (int _i = 0; _i < 2; ++_i) \
;         __builtin_amdgcn_global_load_lds((const unsigned*)((const char*)(gbase) + (voff)[_i]), (PG8_LAS unsigned*)(lds + (bufoff) + ldsw + _i * 8192), 16, 0, 0); } while (0)
; #define PG8_LDA(dst, b, h) do { _Pragma("unroll") for (int m = 0; m < 4; ++m) _Pragma("unroll") for (int k = 0; k < 2; ++k) dst[m][k] = *(const PG8_LAS bf16x8*)(lds + PG8_SA(b, h) + aoff + m * 2048 + k * 1024); } while (0)
; #define PG8_LDB(dst, b, h) do { _Pragma("unroll") for (int n = 0; n < 2; ++n) _Pragma("unroll") for (int k = 0; k < 2; ++k) dst[n][k] = *(const PG8_LAS bf16x8*)(lds + PG8_SB(b, h) + boff + n * 2048 + k * 1024); } while (0)
; #define PG8_MMA(ai, bj, At, Bt) do { __builtin_amdgcn_s_setprio(1); _Pragma("unroll") for (int m = 0; m < 4; ++m) _Pragma("unroll") for (int n = 0; n < 2; ++n) _Pragma("unroll") for (int k = 0; k < 2; ++k) \
;         acc[ai][bj][m][n] = __builtin_amdgcn_mfma_f32_16x16x32_bf16(Bt[n][k], At[m][k], acc[ai][bj][m][n], 0, 0, 0); __builtin_amdgcn_s_setprio(0); } while (0)
; #define PG8_WAIT_V(n) asm volatile("s_waitcnt vmcnt(" #n ")" ::: "memory")
; #define PG8_WAIT_L(n) asm volatile("s_waitcnt lgkmcnt(" #n ")" ::: "memory")
; #define PG8_BAR __builtin_amdgcn_s_barrier()
; #define PG8_SCHED __builtin_amdgcn_sched_barrier(0)
; template <class Epi, class Sched, bool ALIGN_EPI = false, bool SP2 = false>
; __device__ __forceinline__ void gemm_phase(PG8_LAS unsigned char* lds, const Gemm g, const Sched& S, const Epi& E, const int tid) {
;     ...
;             PG8_WAIT_V(8); PG8_WAIT_L(0); PG8_BAR; PG8_MMA(1, 0, At, B0); PG8_MMA(1, 1, At, B1); PG8_BAR; PG8_SCHED;
;             PG8_LDB(B0, 1, 0); PG8_LDB(B1, 1, 1); PG8_SCHED; PG8_LDA(At, 1, 0); PG8_STAGE(PG8_SA(0, 1), a2 + hstep, voffA);
;             PG8_WAIT_V(8); PG8_WAIT_L(0); PG8_BAR; PG8_MMA(0, 0, At, B0); PG8_MMA(0, 1, At, B1); PG8_BAR; PG8_SCHED;
	s_waitcnt lgkmcnt(0)
	v_mfma_f32_16x16x32_bf16 v[64:67], v[148:151], v[212:215], v[64:67]
	v_mfma_f32_16x16x32_bf16 v[60:63], v[174:177], v[212:215], v[60:63]
	v_mfma_f32_16x16x32_bf16 v[56:59], v[148:151], v[220:223], v[56:59]
	v_mfma_f32_16x16x32_bf16 v[52:55], v[174:177], v[220:223], v[52:55]
	v_mfma_f32_16x16x32_bf16 v[40:43], v[148:151], v[228:231], v[40:43]
	v_mfma_f32_16x16x32_bf16 v[36:39], v[174:177], v[228:231], v[36:39]
	v_mfma_f32_16x16x32_bf16 v[24:27], v[148:151], v[240:243], v[24:27]
	v_mfma_f32_16x16x32_bf16 v[20:23], v[174:177], v[240:243], v[20:23]
	v_mfma_f32_16x16x32_bf16 v[64:67], v[170:173], v[216:219], v[64:67]
	v_mfma_f32_16x16x32_bf16 v[60:63], v[178:181], v[216:219], v[60:63]
	v_mfma_f32_16x16x32_bf16 v[56:59], v[170:173], v[224:227], v[56:59]
	v_mfma_f32_16x16x32_bf16 v[52:55], v[178:181], v[224:227], v[52:55]
	v_mfma_f32_16x16x32_bf16 v[40:43], v[170:173], v[236:239], v[40:43]
	v_mfma_f32_16x16x32_bf16 v[36:39], v[178:181], v[236:239], v[36:39]
	v_mfma_f32_16x16x32_bf16 v[24:27], v[170:173], v[244:247], v[24:27]
	v_mfma_f32_16x16x32_bf16 v[20:23], v[178:181], v[244:247], v[20:23]
	v_mfma_f32_16x16x32_bf16 v[48:51], v[182:185], v[212:215], v[48:51]
	v_mfma_f32_16x16x32_bf16 v[44:47], v[190:193], v[212:215], v[44:47]
	v_mfma_f32_16x16x32_bf16 v[32:35], v[182:185], v[220:223], v[32:35]
	v_mfma_f32_16x16x32_bf16 v[28:31], v[190:193], v[220:223], v[28:31]
	v_mfma_f32_16x16x32_bf16 v[16:19], v[182:185], v[228:231], v[16:19]
	v_mfma_f32_16x16x32_bf16 v[12:15], v[190:193], v[228:231], v[12:15]
	v_mfma_f32_16x16x32_bf16 v[8:11], v[182:185], v[240:243], v[8:11]
	v_mfma_f32_16x16x32_bf16 v[4:7], v[190:193], v[240:243], v[4:7]
	v_mfma_f32_16x16x32_bf16 v[48:51], v[186:189], v[216:219], v[48:51]
	v_mfma_f32_16x16x32_bf16 v[44:47], v[194:197], v[216:219], v[44:47]
	v_mfma_f32_16x16x32_bf16 v[32:35], v[186:189], v[224:227], v[32:35]
	v_mfma_f32_16x16x32_bf16 v[28:31], v[194:197], v[224:227], v[28:31]
	v_mfma_f32_16x16x32_bf16 v[16:19], v[186:189], v[236:239], v[16:19]
	v_mfma_f32_16x16x32_bf16 v[12:15], v[194:197], v[236:239], v[12:15]
	v_mfma_f32_16x16x32_bf16 v[8:11], v[186:189], v[244:247], v[8:11]
	v_mfma_f32_16x16x32_bf16 v[4:7], v[194:197], v[244:247], v[4:7]
	s_barrier
	s_add_i32 s12, 0, 0x18000
	v_add_u32_e32 v160, s12, v145
	s_add_i32 s50, 0, 0x1c000
	ds_read_b128 v[148:151], v160
	ds_read_b128 v[170:173], v160 offset:1024
	ds_read_b128 v[174:177], v160 offset:2048
	ds_read_b128 v[178:181], v160 offset:3072
	v_add_u32_e32 v160, s50, v145
	ds_read_b128 v[182:185], v160
	ds_read_b128 v[186:189], v160 offset:1024
	ds_read_b128 v[190:193], v160 offset:2048
	ds_read_b128 v[194:197], v160 offset:3072
	s_add_u32 s44, s44, 0x40000
	s_addc_u32 s45, s45, 0
	s_mov_b32 m0, s7
	v_lshl_add_u64 v[160:161], s[44:45], 0, v[134:135]
	ds_read_b128 v[212:215], v147 offset:32768
	ds_read_b128 v[216:219], v147 offset:33792
	ds_read_b128 v[220:223], v147 offset:34816
	ds_read_b128 v[224:227], v147 offset:35840
	ds_read_b128 v[228:231], v147 offset:36864
	ds_read_b128 v[236:239], v147 offset:37888
	ds_read_b128 v[240:243], v147 offset:38912
	ds_read_b128 v[244:247], v147 offset:39936
	global_load_lds_dwordx4 v[160:161], off
	v_lshl_add_u64 v[160:161], s[44:45], 0, v[132:133]
	s_mov_b32 m0, s8
	s_nop 0
	global_load_lds_dwordx4 v[160:161], off
	s_waitcnt vmcnt(8)
	s_waitcnt lgkmcnt(0)
	s_barrier
	s_waitcnt lgkmcnt(0)
	v_mfma_f32_16x16x32_bf16 v[128:131], v[148:151], v[212:215], v[128:131]
	v_mfma_f32_16x16x32_bf16 v[124:127], v[174:177], v[212:215], v[124:127]
	v_mfma_f32_16x16x32_bf16 v[120:123], v[148:151], v[220:223], v[120:123]
	v_mfma_f32_16x16x32_bf16 v[116:119], v[174:177], v[220:223], v[116:119]
	v_mfma_f32_16x16x32_bf16 v[104:107], v[148:151], v[228:231], v[104:107]
	v_mfma_f32_16x16x32_bf16 v[100:103], v[174:177], v[228:231], v[100:103]
	v_mfma_f32_16x16x32_bf16 v[88:91], v[148:151], v[240:243], v[88:91]
	v_mfma_f32_16x16x32_bf16 v[84:87], v[174:177], v[240:243], v[84:87]
	v_mfma_f32_16x16x32_bf16 v[128:131], v[170:173], v[216:219], v[128:131]
	v_mfma_f32_16x16x32_bf16 v[124:127], v[178:181], v[216:219], v[124:127]
	v_mfma_f32_16x16x32_bf16 v[120:123], v[170:173], v[224:227], v[120:123]
	v_mfma_f32_16x16x32_bf16 v[116:119], v[178:181], v[224:227], v[116:119]
	v_mfma_f32_16x16x32_bf16 v[104:107], v[170:173], v[236:239], v[104:107]
	v_mfma_f32_16x16x32_bf16 v[100:103], v[178:181], v[236:239], v[100:103]
	v_mfma_f32_16x16x32_bf16 v[88:91], v[170:173], v[244:247], v[88:91]
	v_mfma_f32_16x16x32_bf16 v[84:87], v[178:181], v[244:247], v[84:87]
	v_mfma_f32_16x16x32_bf16 v[112:115], v[182:185], v[212:215], v[112:115]
	v_mfma_f32_16x16x32_bf16 v[108:111], v[190:193], v[212:215], v[108:111]
	v_mfma_f32_16x16x32_bf16 v[96:99], v[182:185], v[220:223], v[96:99]
	v_mfma_f32_16x16x32_bf16 v[92:95], v[190:193], v[220:223], v[92:95]
	v_mfma_f32_16x16x32_bf16 v[80:83], v[182:185], v[228:231], v[80:83]
	v_mfma_f32_16x16x32_bf16 v[76:79], v[190:193], v[228:231], v[76:79]
	v_mfma_f32_16x16x32_bf16 v[72:75], v[182:185], v[240:243], v[72:75]
	v_mfma_f32_16x16x32_bf16 v[68:71], v[190:193], v[240:243], v[68:71]
	v_mfma_f32_16x16x32_bf16 v[112:115], v[186:189], v[216:219], v[112:115]
	v_mfma_f32_16x16x32_bf16 v[108:111], v[194:197], v[216:219], v[108:111]
	v_mfma_f32_16x16x32_bf16 v[96:99], v[186:189], v[224:227], v[96:99]
	v_mfma_f32_16x16x32_bf16 v[92:95], v[194:197], v[224:227], v[92:95]
	v_mfma_f32_16x16x32_bf16 v[80:83], v[186:189], v[236:239], v[80:83]
	v_mfma_f32_16x16x32_bf16 v[76:79], v[194:197], v[236:239], v[76:79]
	v_mfma_f32_16x16x32_bf16 v[72:75], v[186:189], v[244:247], v[72:75]
	v_mfma_f32_16x16x32_bf16 v[68:71], v[194:197], v[244:247], v[68:71]
	s_barrier
; #define PG8_STAGE(bufoff, gbase, voff) do { _Pragma("unroll") for (int _i = 0; _i < 2; ++_i) \
;         __builtin_amdgcn_global_load_lds((const unsigned*)((const char*)(gbase) + (voff)[_i]), (PG8_LAS unsigned*)(lds + (bufoff) + ldsw + _i * 8192), 16, 0, 0); } while (0)
; #define PG8_LDA(dst, b, h) do { _Pragma("unroll") for (int m = 0; m < 4; ++m) _Pragma("unroll") for (int k = 0; k < 2; ++k) dst[m][k] = *(const PG8_LAS bf16x8*)(lds + PG8_SA(b, h) + aoff + m * 2048 + k * 1024); } while (0)
; #define PG8_MMA(ai, bj, At, Bt) do { __builtin_amdgcn_s_setprio(1); _Pragma("unroll") for (int m = 0; m < 4; ++m) _Pragma("unroll") for (int n = 0; n < 2; ++n) _Pragma("unroll") for (int k = 0; k < 2; ++k) \
;         acc[ai][bj][m][n] = __builtin_amdgcn_mfma_f32_16x16x32_bf16(Bt[n][k], At[m][k], acc[ai][bj][m][n], 0, 0, 0); __builtin_amdgcn_s_setprio(0); } while (0)
; #define PG8_WAIT_V(n) asm volatile("s_waitcnt vmcnt(" #n ")" ::: "memory")
; #define PG8_WAIT_L(n) asm volatile("s_waitcnt lgkmcnt(" #n ")" ::: "memory")
; #define PG8_BAR __builtin_amdgcn_s_barrier()
; #define PG8_SCHED __builtin_amdgcn_sched_barrier(0)
; template <class Epi, class Sched, bool ALIGN_EPI = false, bool SP2 = false>
; __device__ __forceinline__ void gemm_phase(PG8_LAS unsigned char* lds, const Gemm g, const Sched& S, const Epi& E, const int tid) {
;     ...
;         for (int t = 0; t < nt; t += 2) {
;             const bool last = (t == nt - 2);
;     ...
;             PG8_LDA(At, 1, 1); PG8_STAGE(PG8_SB(1, 0), b3, voffB); PG8_STAGE(PG8_SB(1, 1), b3 + hstep, voffB); PG8_STAGE(PG8_SA(1, 0), a3, voffA);
;             PG8_WAIT_V(8); PG8_WAIT_L(0); PG8_BAR; PG8_MMA(1, 0, At, B0); PG8_MMA(1, 1, At, B1); PG8_BAR; PG8_SCHED;
	s_add_i32 s12, s12, s4
	v_lshl_add_u64 v[152:153], v[152:153], 0, s[18:19]
	s_mov_b32 m0, s12
	ds_read_b128 v[212:215], v147 offset:49152
	ds_read_b128 v[216:219], v147 offset:50176
	ds_read_b128 v[220:223], v147 offset:51200
	ds_read_b128 v[224:227], v147 offset:52224
	ds_read_b128 v[228:231], v147 offset:53248
	ds_read_b128 v[236:239], v147 offset:54272
	ds_read_b128 v[240:243], v147 offset:55296
	ds_read_b128 v[244:247], v147 offset:56320
	global_load_lds_dwordx4 v[152:153], off
	s_add_i32 m0, s12, 0x2000
	s_add_u32 s42, s42, 0x40080
	v_lshl_add_u64 v[152:153], v[198:199], 0, s[18:19]
	s_addc_u32 s43, s43, 0
	s_add_i32 s12, s50, s4
	global_load_lds_dwordx4 v[152:153], off
	v_lshl_add_u64 v[152:153], s[42:43], 0, v[2:3]
	s_mov_b32 m0, s12
	s_nop 0
	global_load_lds_dwordx4 v[152:153], off
	v_lshl_add_u64 v[152:153], s[42:43], 0, v[0:1]
	s_add_i32 m0, s12, 0x2000
	s_nop 0
	global_load_lds_dwordx4 v[152:153], off
	v_lshl_add_u64 v[152:153], v[248:249], 0, s[18:19]
	s_mov_b32 m0, s9
	s_nop 0
	global_load_lds_dwordx4 v[152:153], off
	v_lshl_add_u64 v[152:153], v[250:251], 0, s[18:19]
	s_mov_b32 m0, s13
	s_nop 0
	global_load_lds_dwordx4 v[152:153], off
	s_waitcnt vmcnt(8)
	s_waitcnt lgkmcnt(0)
	s_barrier
	s_waitcnt lgkmcnt(0)
	v_mfma_f32_16x16x32_bf16 v[64:67], v[148:151], v[212:215], v[64:67]
	v_mfma_f32_16x16x32_bf16 v[60:63], v[174:177], v[212:215], v[60:63]
	v_mfma_f32_16x16x32_bf16 v[56:59], v[148:151], v[220:223], v[56:59]
	v_mfma_f32_16x16x32_bf16 v[52:55], v[174:177], v[220:223], v[52:55]
	v_mfma_f32_16x16x32_bf16 v[40:43], v[148:151], v[228:231], v[40:43]
	v_mfma_f32_16x16x32_bf16 v[36:39], v[174:177], v[228:231], v[36:39]
	v_mfma_f32_16x16x32_bf16 v[24:27], v[148:151], v[240:243], v[24:27]
	v_mfma_f32_16x16x32_bf16 v[20:23], v[174:177], v[240:243], v[20:23]
	v_mfma_f32_16x16x32_bf16 v[64:67], v[170:173], v[216:219], v[64:67]
	v_mfma_f32_16x16x32_bf16 v[60:63], v[178:181], v[216:219], v[60:63]
	v_mfma_f32_16x16x32_bf16 v[56:59], v[170:173], v[224:227], v[56:59]
	v_mfma_f32_16x16x32_bf16 v[52:55], v[178:181], v[224:227], v[52:55]
	v_mfma_f32_16x16x32_bf16 v[40:43], v[170:173], v[236:239], v[40:43]
	v_mfma_f32_16x16x32_bf16 v[36:39], v[178:181], v[236:239], v[36:39]
	v_mfma_f32_16x16x32_bf16 v[24:27], v[170:173], v[244:247], v[24:27]
	v_mfma_f32_16x16x32_bf16 v[20:23], v[178:181], v[244:247], v[20:23]
	v_mfma_f32_16x16x32_bf16 v[48:51], v[182:185], v[212:215], v[48:51]
	v_mfma_f32_16x16x32_bf16 v[44:47], v[190:193], v[212:215], v[44:47]
	v_mfma_f32_16x16x32_bf16 v[32:35], v[182:185], v[220:223], v[32:35]
	v_mfma_f32_16x16x32_bf16 v[28:31], v[190:193], v[220:223], v[28:31]
	v_mfma_f32_16x16x32_bf16 v[16:19], v[182:185], v[228:231], v[16:19]
	v_mfma_f32_16x16x32_bf16 v[12:15], v[190:193], v[228:231], v[12:15]
	v_mfma_f32_16x16x32_bf16 v[8:11], v[182:185], v[240:243], v[8:11]
	v_mfma_f32_16x16x32_bf16 v[4:7], v[190:193], v[240:243], v[4:7]
	v_mfma_f32_16x16x32_bf16 v[48:51], v[186:189], v[216:219], v[48:51]
	v_mfma_f32_16x16x32_bf16 v[44:47], v[194:197], v[216:219], v[44:47]
	v_mfma_f32_16x16x32_bf16 v[32:35], v[186:189], v[224:227], v[32:35]
	v_mfma_f32_16x16x32_bf16 v[28:31], v[194:197], v[224:227], v[28:31]
	v_mfma_f32_16x16x32_bf16 v[16:19], v[186:189], v[236:239], v[16:19]
	v_mfma_f32_16x16x32_bf16 v[12:15], v[194:197], v[236:239], v[12:15]
	v_mfma_f32_16x16x32_bf16 v[8:11], v[186:189], v[244:247], v[8:11]
	v_mfma_f32_16x16x32_bf16 v[4:7], v[194:197], v[244:247], v[4:7]
	s_barrier
	s_add_i32 s49, s49, 2
	s_add_u32 s36, s36, 0x100
	s_addc_u32 s37, s37, 0
	s_add_u32 s47, s47, 0x100
	s_addc_u32 s48, s48, 0
	s_cmp_gt_u32 s49, 13
	s_cbranch_scc0 .LBB0_1545
	s_and_b64 vcc, exec, s[20:21]
	s_cbranch_vccz .LBB0_1548
	s_barrier

; #define PG8_STAGE(bufoff, gbase, voff) do { _Pragma("unroll") for (int _i = 0; _i < 2; ++_i) \
;         __builtin_amdgcn_global_load_lds((const unsigned*)((const char*)(gbase) + (voff)[_i]), (PG8_LAS unsigned*)(lds + (bufoff) + ldsw + _i * 8192), 16, 0, 0); } while (0)
; #define PG8_LDA(dst, b, h) do { _Pragma("unroll") for (int m = 0; m < 4; ++m) _Pragma("unroll") for (int k = 0; k < 2; ++k) dst[m][k] = *(const PG8_LAS bf16x8*)(lds + PG8_SA(b, h) + aoff + m * 2048 + k * 1024); } while (0)
; #define PG8_LDB(dst, b, h) do { _Pragma("unroll") for (int n = 0; n < 2; ++n) _Pragma("unroll") for (int k = 0; k < 2; ++k) dst[n][k] = *(const PG8_LAS bf16x8*)(lds + PG8_SB(b, h) + boff + n * 2048 + k * 1024); } while (0)
; #define PG8_MMA(ai, bj, At, Bt) do { __builtin_amdgcn_s_setprio(1); _Pragma("unroll") for (int m = 0; m < 4; ++m) _Pragma("unroll") for (int n = 0; n < 2; ++n) _Pragma("unroll") for (int k = 0; k < 2; ++k) \
;         acc[ai][bj][m][n] = __builtin_amdgcn_mfma_f32_16x16x32_bf16(Bt[n][k], At[m][k], acc[ai][bj][m][n], 0, 0, 0); __builtin_amdgcn_s_setprio(0); } while (0)
; #define PG8_WAIT_V(n) asm volatile("s_waitcnt vmcnt(" #n ")" ::: "memory")
; #define PG8_WAIT_L(n) asm volatile("s_waitcnt lgkmcnt(" #n ")" ::: "memory")
; #define PG8_BAR __builtin_amdgcn_s_barrier()
; template <class Epi, class Sched, bool ALIGN_EPI = false, bool SP2 = false>
; __device__ __forceinline__ void gemm_phase(PG8_LAS unsigned char* lds, const Gemm g, const Sched& S, const Epi& E, const int tid) {
;     ...
;         for (int t = 0; t < nt; t += 2) {
;             const bool last = (t == nt - 2);
;             const char* a1 = cA + (size_t)(t + 1) * kstep;
;             const char* a2 = last ? nA : cA + (size_t)(t + 2) * kstep; const char* b2 = last ? nB : cB + (size_t)(t + 2) * kstep;
;             const char* a3 = a2 + kstep; const char* b3 = b2 + kstep;
;             if (last && has_next) S.a_ready(nxt);
;             if constexpr (SP2) {
;             PG8_LDB(B0, 0, 0); PG8_LDB(B1, 0, 1); PG8_SCHED; PG8_LDA(At, 0, 0); PG8_STAGE(PG8_SA(1, 1), a1 + hstep, voffA);
;             PG8_WAIT_V(8); PG8_WAIT_L(0); PG8_BAR; PG8_MMA(0, 0, At, B0); PG8_MMA(0, 1, At, B1); PG8_BAR; PG8_SCHED;
;             PG8_LDA(At, 0, 1); PG8_STAGE(PG8_SB(0, 0), b2, voffB); PG8_STAGE(PG8_SB(0, 1), b2 + hstep, voffB); PG8_STAGE(PG8_SA(0, 0), a2, voffA);
.LBB0_1567:
	s_add_u32 s12, s36, 0xfffc0080
	s_addc_u32 s42, s37, -1
	s_add_i32 s50, 0, 0x10000
	s_cmp_eq_u32 s49, 12
	s_cselect_b32 s45, s27, s42
	s_cselect_b32 s44, s30, s12
	v_add_u32_e32 v143, s50, v141
	s_cselect_b32 s43, s25, s48
	s_cselect_b32 s42, s46, s47
	s_add_i32 s12, 0, 0x14000
	ds_read_b128 v[146:149], v143
	ds_read_b128 v[150:153], v143 offset:1024
	ds_read_b128 v[170:173], v143 offset:2048
	ds_read_b128 v[174:177], v143 offset:3072
	v_add_u32_e32 v143, s12, v141
	ds_read_b128 v[178:181], v143
	ds_read_b128 v[182:185], v143 offset:1024
	ds_read_b128 v[186:189], v143 offset:2048
	ds_read_b128 v[190:193], v143 offset:3072
	v_lshl_add_u64 v[198:199], s[36:37], 0, v[136:137]
	s_add_i32 m0, s5, 0xc000
	ds_read_b128 v[194:197], v142
	ds_read_b128 v[212:215], v142 offset:1024
	ds_read_b128 v[216:219], v142 offset:2048
	ds_read_b128 v[220:223], v142 offset:3072
	ds_read_b128 v[224:227], v142 offset:4096
	ds_read_b128 v[228:231], v142 offset:5120
	ds_read_b128 v[236:239], v142 offset:6144
	ds_read_b128 v[240:243], v142 offset:7168
	global_load_lds_dwordx4 v[198:199], off
	v_lshl_add_u64 v[198:199], s[36:37], 0, v[138:139]
	s_add_i32 m0, s5, 0xe000
	s_nop 0
	global_load_lds_dwordx4 v[198:199], off
	s_waitcnt vmcnt(8)
	s_waitcnt lgkmcnt(0)
	s_barrier
	s_waitcnt lgkmcnt(0)
	v_mfma_f32_16x16x32_bf16 v[128:131], v[146:149], v[194:197], v[128:131]
	v_mfma_f32_16x16x32_bf16 v[124:127], v[170:173], v[194:197], v[124:127]
	v_mfma_f32_16x16x32_bf16 v[120:123], v[146:149], v[216:219], v[120:123]
	v_mfma_f32_16x16x32_bf16 v[116:119], v[170:173], v[216:219], v[116:119]
	v_mfma_f32_16x16x32_bf16 v[104:107], v[146:149], v[224:227], v[104:107]
	v_mfma_f32_16x16x32_bf16 v[100:103], v[170:173], v[224:227], v[100:103]
	v_mfma_f32_16x16x32_bf16 v[88:91], v[146:149], v[236:239], v[88:91]
	v_mfma_f32_16x16x32_bf16 v[84:87], v[170:173], v[236:239], v[84:87]
	v_mfma_f32_16x16x32_bf16 v[128:131], v[150:153], v[212:215], v[128:131]
	v_mfma_f32_16x16x32_bf16 v[124:127], v[174:177], v[212:215], v[124:127]
	v_mfma_f32_16x16x32_bf16 v[120:123], v[150:153], v[220:223], v[120:123]
	v_mfma_f32_16x16x32_bf16 v[116:119], v[174:177], v[220:223], v[116:119]
	v_mfma_f32_16x16x32_bf16 v[104:107], v[150:153], v[228:231], v[104:107]
	v_mfma_f32_16x16x32_bf16 v[100:103], v[174:177], v[228:231], v[100:103]
	v_mfma_f32_16x16x32_bf16 v[88:91], v[150:153], v[240:243], v[88:91]
	v_mfma_f32_16x16x32_bf16 v[84:87], v[174:177], v[240:243], v[84:87]
	v_mfma_f32_16x16x32_bf16 v[112:115], v[178:181], v[194:197], v[112:115]
	v_mfma_f32_16x16x32_bf16 v[108:111], v[186:189], v[194:197], v[108:111]
	v_mfma_f32_16x16x32_bf16 v[96:99], v[178:181], v[216:219], v[96:99]
	v_mfma_f32_16x16x32_bf16 v[92:95], v[186:189], v[216:219], v[92:95]
	v_mfma_f32_16x16x32_bf16 v[80:83], v[178:181], v[224:227], v[80:83]
	v_mfma_f32_16x16x32_bf16 v[76:79], v[186:189], v[224:227], v[76:79]
	v_mfma_f32_16x16x32_bf16 v[72:75], v[178:181], v[236:239], v[72:75]
	v_mfma_f32_16x16x32_bf16 v[68:71], v[186:189], v[236:239], v[68:71]
	v_mfma_f32_16x16x32_bf16 v[112:115], v[182:185], v[212:215], v[112:115]
	v_mfma_f32_16x16x32_bf16 v[108:111], v[190:193], v[212:215], v[108:111]
	v_mfma_f32_16x16x32_bf16 v[96:99], v[182:185], v[220:223], v[96:99]
	v_mfma_f32_16x16x32_bf16 v[92:95], v[190:193], v[220:223], v[92:95]
	v_mfma_f32_16x16x32_bf16 v[80:83], v[182:185], v[228:231], v[80:83]
	v_mfma_f32_16x16x32_bf16 v[76:79], v[190:193], v[228:231], v[76:79]
	v_mfma_f32_16x16x32_bf16 v[72:75], v[182:185], v[240:243], v[72:75]
	v_mfma_f32_16x16x32_bf16 v[68:71], v[190:193], v[240:243], v[68:71]
	s_barrier
	s_add_i32 s50, s50, s4
	v_lshl_add_u64 v[198:199], s[42:43], 0, v[2:3]
	s_mov_b32 m0, s50
	ds_read_b128 v[194:197], v142 offset:16384
	ds_read_b128 v[212:215], v142 offset:17408
	ds_read_b128 v[216:219], v142 offset:18432
	ds_read_b128 v[220:223], v142 offset:19456
	ds_read_b128 v[224:227], v142 offset:20480
	ds_read_b128 v[228:231], v142 offset:21504
	ds_read_b128 v[236:239], v142 offset:22528
	ds_read_b128 v[240:243], v142 offset:23552
	global_load_lds_dwordx4 v[198:199], off
	s_add_i32 m0, s50, 0x2000
	s_add_u32 s50, s42, 0x40000
	v_lshl_add_u64 v[244:245], s[42:43], 0, v[0:1]
	s_addc_u32 s51, s43, 0
	s_add_i32 s12, s12, s4
	global_load_lds_dwordx4 v[244:245], off
	v_lshl_add_u64 v[246:247], s[50:51], 0, v[2:3]
	s_mov_b32 m0, s12
	v_lshl_add_u64 v[248:249], s[44:45], 0, v[132:133]
	global_load_lds_dwordx4 v[246:247], off
	v_lshl_add_u64 v[246:247], s[50:51], 0, v[0:1]
	s_add_i32 m0, s12, 0x2000
	s_nop 0
	global_load_lds_dwordx4 v[246:247], off
	v_lshl_add_u64 v[246:247], s[44:45], 0, v[134:135]
	s_mov_b32 m0, s5
	s_nop 0
	global_load_lds_dwordx4 v[246:247], off
	s_mov_b32 m0, s6
	s_nop 0
	global_load_lds_dwordx4 v[248:249], off
	s_waitcnt vmcnt(8)
	s_waitcnt lgkmcnt(0)
	s_barrier
; #define PG8_STAGE(bufoff, gbase, voff) do { _Pragma("unroll") for (int _i = 0; _i < 2; ++_i) \
;         __builtin_amdgcn_global_load_lds((const unsigned*)((const char*)(gbase) + (voff)[_i]), (PG8_LAS unsigned*)(lds + (bufoff) + ldsw + _i * 8192), 16, 0, 0); } while (0)
; #define PG8_LDA(dst, b, h) do { _Pragma("unroll") for (int m = 0; m < 4; ++m) _Pragma("unroll") for (int k = 0; k < 2; ++k) dst[m][k] = *(const PG8_LAS bf16x8*)(lds + PG8_SA(b, h) + aoff + m * 2048 + k * 1024); } while (0)
; #define PG8_LDB(dst, b, h) do { _Pragma("unroll") for (int n = 0; n < 2; ++n) _Pragma("unroll") for (int k = 0; k < 2; ++k) dst[n][k] = *(const PG8_LAS bf16x8*)(lds + PG8_SB(b, h) + boff + n * 2048 + k * 1024); } while (0)
; #define PG8_MMA(ai, bj, At, Bt) do { __builtin_amdgcn_s_setprio(1); _Pragma("unroll") for (int m = 0; m < 4; ++m) _Pragma("unroll") for (int n = 0; n < 2; ++n) _Pragma("unroll") for (int k = 0; k < 2; ++k) \
;         acc[ai][bj][m][n] = __builtin_amdgcn_mfma_f32_16x16x32_bf16(Bt[n][k], At[m][k], acc[ai][bj][m][n], 0, 0, 0); __builtin_amdgcn_s_setprio(0); } while (0)
; #define PG8_WAIT_V(n) asm volatile("s_waitcnt vmcnt(" #n ")" ::: "memory")
; #define PG8_WAIT_L(n) asm volatile("s_waitcnt lgkmcnt(" #n ")" ::: "memory")
; #define PG8_BAR __builtin_amdgcn_s_barrier()
; #define PG8_SCHED __builtin_amdgcn_sched_barrier(0)
; template <class Epi, class Sched, bool ALIGN_EPI = false, bool SP2 = false>
; __device__ __forceinline__ void gemm_phase(PG8_LAS unsigned char* lds, const Gemm g, const Sched& S, const Epi& E, const int tid) {
;     ...
;             PG8_WAIT_V(8); PG8_WAIT_L(0); PG8_BAR; PG8_MMA(1, 0, At, B0); PG8_MMA(1, 1, At, B1); PG8_BAR; PG8_SCHED;
;             PG8_LDB(B0, 1, 0); PG8_LDB(B1, 1, 1); PG8_SCHED; PG8_LDA(At, 1, 0); PG8_STAGE(PG8_SA(0, 1), a2 + hstep, voffA);
;             PG8_WAIT_V(8); PG8_WAIT_L(0); PG8_BAR; PG8_MMA(0, 0, At, B0); PG8_MMA(0, 1, At, B1); PG8_BAR; PG8_SCHED;
	s_waitcnt lgkmcnt(0)
	v_mfma_f32_16x16x32_bf16 v[64:67], v[146:149], v[194:197], v[64:67]
	v_mfma_f32_16x16x32_bf16 v[60:63], v[170:173], v[194:197], v[60:63]
	v_mfma_f32_16x16x32_bf16 v[56:59], v[146:149], v[216:219], v[56:59]
	v_mfma_f32_16x16x32_bf16 v[52:55], v[170:173], v[216:219], v[52:55]
	v_mfma_f32_16x16x32_bf16 v[40:43], v[146:149], v[224:227], v[40:43]
	v_mfma_f32_16x16x32_bf16 v[36:39], v[170:173], v[224:227], v[36:39]
	v_mfma_f32_16x16x32_bf16 v[24:27], v[146:149], v[236:239], v[24:27]
	v_mfma_f32_16x16x32_bf16 v[20:23], v[170:173], v[236:239], v[20:23]
	v_mfma_f32_16x16x32_bf16 v[64:67], v[150:153], v[212:215], v[64:67]
	v_mfma_f32_16x16x32_bf16 v[60:63], v[174:177], v[212:215], v[60:63]
	v_mfma_f32_16x16x32_bf16 v[56:59], v[150:153], v[220:223], v[56:59]
	v_mfma_f32_16x16x32_bf16 v[52:55], v[174:177], v[220:223], v[52:55]
	v_mfma_f32_16x16x32_bf16 v[40:43], v[150:153], v[228:231], v[40:43]
	v_mfma_f32_16x16x32_bf16 v[36:39], v[174:177], v[228:231], v[36:39]
	v_mfma_f32_16x16x32_bf16 v[24:27], v[150:153], v[240:243], v[24:27]
	v_mfma_f32_16x16x32_bf16 v[20:23], v[174:177], v[240:243], v[20:23]
	v_mfma_f32_16x16x32_bf16 v[48:51], v[178:181], v[194:197], v[48:51]
	v_mfma_f32_16x16x32_bf16 v[44:47], v[186:189], v[194:197], v[44:47]
	v_mfma_f32_16x16x32_bf16 v[32:35], v[178:181], v[216:219], v[32:35]
	v_mfma_f32_16x16x32_bf16 v[28:31], v[186:189], v[216:219], v[28:31]
	v_mfma_f32_16x16x32_bf16 v[16:19], v[178:181], v[224:227], v[16:19]
	v_mfma_f32_16x16x32_bf16 v[12:15], v[186:189], v[224:227], v[12:15]
	v_mfma_f32_16x16x32_bf16 v[8:11], v[178:181], v[236:239], v[8:11]
	v_mfma_f32_16x16x32_bf16 v[4:7], v[186:189], v[236:239], v[4:7]
	v_mfma_f32_16x16x32_bf16 v[48:51], v[182:185], v[212:215], v[48:51]
	v_mfma_f32_16x16x32_bf16 v[44:47], v[190:193], v[212:215], v[44:47]
	v_mfma_f32_16x16x32_bf16 v[32:35], v[182:185], v[220:223], v[32:35]
	v_mfma_f32_16x16x32_bf16 v[28:31], v[190:193], v[220:223], v[28:31]
	v_mfma_f32_16x16x32_bf16 v[16:19], v[182:185], v[228:231], v[16:19]
	v_mfma_f32_16x16x32_bf16 v[12:15], v[190:193], v[228:231], v[12:15]
	v_mfma_f32_16x16x32_bf16 v[8:11], v[182:185], v[240:243], v[8:11]
	v_mfma_f32_16x16x32_bf16 v[4:7], v[190:193], v[240:243], v[4:7]
	s_barrier
	s_add_i32 s12, 0, 0x18000
	v_add_u32_e32 v143, s12, v141
	s_add_i32 s50, 0, 0x1c000
	ds_read_b128 v[146:149], v143
	ds_read_b128 v[150:153], v143 offset:1024
	ds_read_b128 v[170:173], v143 offset:2048
	ds_read_b128 v[174:177], v143 offset:3072
	v_add_u32_e32 v143, s50, v141
	ds_read_b128 v[178:181], v143
	ds_read_b128 v[182:185], v143 offset:1024
	ds_read_b128 v[186:189], v143 offset:2048
	ds_read_b128 v[190:193], v143 offset:3072
	s_add_u32 s44, s44, 0x40000
	s_addc_u32 s45, s45, 0
	s_mov_b32 m0, s7
	v_lshl_add_u64 v[250:251], s[44:45], 0, v[134:135]
	ds_read_b128 v[194:197], v142 offset:32768
	ds_read_b128 v[212:215], v142 offset:33792
	ds_read_b128 v[216:219], v142 offset:34816
	ds_read_b128 v[220:223], v142 offset:35840
	ds_read_b128 v[224:227], v142 offset:36864
	ds_read_b128 v[228:231], v142 offset:37888
	ds_read_b128 v[236:239], v142 offset:38912
	ds_read_b128 v[240:243], v142 offset:39936
	global_load_lds_dwordx4 v[250:251], off
	v_lshl_add_u64 v[250:251], s[44:45], 0, v[132:133]
	s_mov_b32 m0, s8
	s_nop 0
	global_load_lds_dwordx4 v[250:251], off
	s_waitcnt vmcnt(8)
	s_waitcnt lgkmcnt(0)
	s_barrier
	s_waitcnt lgkmcnt(0)
	v_mfma_f32_16x16x32_bf16 v[128:131], v[146:149], v[194:197], v[128:131]
	v_mfma_f32_16x16x32_bf16 v[124:127], v[170:173], v[194:197], v[124:127]
	v_mfma_f32_16x16x32_bf16 v[120:123], v[146:149], v[216:219], v[120:123]
	v_mfma_f32_16x16x32_bf16 v[116:119], v[170:173], v[216:219], v[116:119]
	v_mfma_f32_16x16x32_bf16 v[104:107], v[146:149], v[224:227], v[104:107]
	v_mfma_f32_16x16x32_bf16 v[100:103], v[170:173], v[224:227], v[100:103]
	v_mfma_f32_16x16x32_bf16 v[88:91], v[146:149], v[236:239], v[88:91]
	v_mfma_f32_16x16x32_bf16 v[84:87], v[170:173], v[236:239], v[84:87]
	v_mfma_f32_16x16x32_bf16 v[128:131], v[150:153], v[212:215], v[128:131]
	v_mfma_f32_16x16x32_bf16 v[124:127], v[174:177], v[212:215], v[124:127]
	v_mfma_f32_16x16x32_bf16 v[120:123], v[150:153], v[220:223], v[120:123]
	v_mfma_f32_16x16x32_bf16 v[116:119], v[174:177], v[220:223], v[116:119]
	v_mfma_f32_16x16x32_bf16 v[104:107], v[150:153], v[228:231], v[104:107]
	v_mfma_f32_16x16x32_bf16 v[100:103], v[174:177], v[228:231], v[100:103]
	v_mfma_f32_16x16x32_bf16 v[88:91], v[150:153], v[240:243], v[88:91]
	v_mfma_f32_16x16x32_bf16 v[84:87], v[174:177], v[240:243], v[84:87]
	v_mfma_f32_16x16x32_bf16 v[112:115], v[178:181], v[194:197], v[112:115]
	v_mfma_f32_16x16x32_bf16 v[108:111], v[186:189], v[194:197], v[108:111]
	v_mfma_f32_16x16x32_bf16 v[96:99], v[178:181], v[216:219], v[96:99]
	v_mfma_f32_16x16x32_bf16 v[92:95], v[186:189], v[216:219], v[92:95]
	v_mfma_f32_16x16x32_bf16 v[80:83], v[178:181], v[224:227], v[80:83]
	v_mfma_f32_16x16x32_bf16 v[76:79], v[186:189], v[224:227], v[76:79]
	v_mfma_f32_16x16x32_bf16 v[72:75], v[178:181], v[236:239], v[72:75]
	v_mfma_f32_16x16x32_bf16 v[68:71], v[186:189], v[236:239], v[68:71]
	v_mfma_f32_16x16x32_bf16 v[112:115], v[182:185], v[212:215], v[112:115]
	v_mfma_f32_16x16x32_bf16 v[108:111], v[190:193], v[212:215], v[108:111]
	v_mfma_f32_16x16x32_bf16 v[96:99], v[182:185], v[220:223], v[96:99]
	v_mfma_f32_16x16x32_bf16 v[92:95], v[190:193], v[220:223], v[92:95]
	v_mfma_f32_16x16x32_bf16 v[80:83], v[182:185], v[228:231], v[80:83]
	v_mfma_f32_16x16x32_bf16 v[76:79], v[190:193], v[228:231], v[76:79]
	v_mfma_f32_16x16x32_bf16 v[72:75], v[182:185], v[240:243], v[72:75]
	v_mfma_f32_16x16x32_bf16 v[68:71], v[190:193], v[240:243], v[68:71]
	s_barrier
; #define PG8_STAGE(bufoff, gbase, voff) do { _Pragma("unroll") for (int _i = 0; _i < 2; ++_i) \
;         __builtin_amdgcn_global_load_lds((const unsigned*)((const char*)(gbase) + (voff)[_i]), (PG8_LAS unsigned*)(lds + (bufoff) + ldsw + _i * 8192), 16, 0, 0); } while (0)
; #define PG8_LDA(dst, b, h) do { _Pragma("unroll") for (int m = 0; m < 4; ++m) _Pragma("unroll") for (int k = 0; k < 2; ++k) dst[m][k] = *(const PG8_LAS bf16x8*)(lds + PG8_SA(b, h) + aoff + m * 2048 + k * 1024); } while (0)
; #define PG8_MMA(ai, bj, At, Bt) do { __builtin_amdgcn_s_setprio(1); _Pragma("unroll") for (int m = 0; m < 4; ++m) _Pragma("unroll") for (int n = 0; n < 2; ++n) _Pragma("unroll") for (int k = 0; k < 2; ++k) \
;         acc[ai][bj][m][n] = __builtin_amdgcn_mfma_f32_16x16x32_bf16(Bt[n][k], At[m][k], acc[ai][bj][m][n], 0, 0, 0); __builtin_amdgcn_s_setprio(0); } while (0)
; #define PG8_WAIT_V(n) asm volatile("s_waitcnt vmcnt(" #n ")" ::: "memory")
; #define PG8_WAIT_L(n) asm volatile("s_waitcnt lgkmcnt(" #n ")" ::: "memory")
; #define PG8_BAR __builtin_amdgcn_s_barrier()
; #define PG8_SCHED __builtin_amdgcn_sched_barrier(0)
; template <class Epi, class Sched, bool ALIGN_EPI = false, bool SP2 = false>
; __device__ __forceinline__ void gemm_phase(PG8_LAS unsigned char* lds, const Gemm g, const Sched& S, const Epi& E, const int tid) {
;     ...
;         for (int t = 0; t < nt; t += 2) {
;             const bool last = (t == nt - 2);
;     ...
;             PG8_LDA(At, 1, 1); PG8_STAGE(PG8_SB(1, 0), b3, voffB); PG8_STAGE(PG8_SB(1, 1), b3 + hstep, voffB); PG8_STAGE(PG8_SA(1, 0), a3, voffA);
;             PG8_WAIT_V(8); PG8_WAIT_L(0); PG8_BAR; PG8_MMA(1, 0, At, B0); PG8_MMA(1, 1, At, B1); PG8_BAR; PG8_SCHED;
	s_add_i32 s12, s12, s4
	v_lshl_add_u64 v[198:199], v[198:199], 0, s[18:19]
	s_mov_b32 m0, s12
	ds_read_b128 v[194:197], v142 offset:49152
	ds_read_b128 v[212:215], v142 offset:50176
	ds_read_b128 v[216:219], v142 offset:51200
	ds_read_b128 v[220:223], v142 offset:52224
	ds_read_b128 v[224:227], v142 offset:53248
	ds_read_b128 v[228:231], v142 offset:54272
	ds_read_b128 v[236:239], v142 offset:55296
	ds_read_b128 v[240:243], v142 offset:56320
	global_load_lds_dwordx4 v[198:199], off
	s_add_i32 m0, s12, 0x2000
	s_add_u32 s42, s42, 0x40080
	v_lshl_add_u64 v[198:199], v[244:245], 0, s[18:19]
	s_addc_u32 s43, s43, 0
	s_add_i32 s12, s50, s4
	global_load_lds_dwordx4 v[198:199], off
	v_lshl_add_u64 v[198:199], s[42:43], 0, v[2:3]
	s_mov_b32 m0, s12
	s_nop 0
	global_load_lds_dwordx4 v[198:199], off
	v_lshl_add_u64 v[198:199], s[42:43], 0, v[0:1]
	s_add_i32 m0, s12, 0x2000
	s_nop 0
	global_load_lds_dwordx4 v[198:199], off
	v_lshl_add_u64 v[198:199], v[246:247], 0, s[18:19]
	s_mov_b32 m0, s9
	s_nop 0
	global_load_lds_dwordx4 v[198:199], off
	v_lshl_add_u64 v[198:199], v[248:249], 0, s[18:19]
	s_mov_b32 m0, s13
	s_nop 0
	global_load_lds_dwordx4 v[198:199], off
	s_waitcnt vmcnt(8)
	s_waitcnt lgkmcnt(0)
	s_barrier
	s_waitcnt lgkmcnt(0)
	v_mfma_f32_16x16x32_bf16 v[64:67], v[146:149], v[194:197], v[64:67]
	v_mfma_f32_16x16x32_bf16 v[60:63], v[170:173], v[194:197], v[60:63]
	v_mfma_f32_16x16x32_bf16 v[56:59], v[146:149], v[216:219], v[56:59]
	v_mfma_f32_16x16x32_bf16 v[52:55], v[170:173], v[216:219], v[52:55]
	v_mfma_f32_16x16x32_bf16 v[40:43], v[146:149], v[224:227], v[40:43]
	v_mfma_f32_16x16x32_bf16 v[36:39], v[170:173], v[224:227], v[36:39]
	v_mfma_f32_16x16x32_bf16 v[24:27], v[146:149], v[236:239], v[24:27]
	v_mfma_f32_16x16x32_bf16 v[20:23], v[170:173], v[236:239], v[20:23]
	v_mfma_f32_16x16x32_bf16 v[64:67], v[150:153], v[212:215], v[64:67]
	v_mfma_f32_16x16x32_bf16 v[60:63], v[174:177], v[212:215], v[60:63]
	v_mfma_f32_16x16x32_bf16 v[56:59], v[150:153], v[220:223], v[56:59]
	v_mfma_f32_16x16x32_bf16 v[52:55], v[174:177], v[220:223], v[52:55]
	v_mfma_f32_16x16x32_bf16 v[40:43], v[150:153], v[228:231], v[40:43]
	v_mfma_f32_16x16x32_bf16 v[36:39], v[174:177], v[228:231], v[36:39]
	v_mfma_f32_16x16x32_bf16 v[24:27], v[150:153], v[240:243], v[24:27]
	v_mfma_f32_16x16x32_bf16 v[20:23], v[174:177], v[240:243], v[20:23]
	v_mfma_f32_16x16x32_bf16 v[48:51], v[178:181], v[194:197], v[48:51]
	v_mfma_f32_16x16x32_bf16 v[44:47], v[186:189], v[194:197], v[44:47]
	v_mfma_f32_16x16x32_bf16 v[32:35], v[178:181], v[216:219], v[32:35]
	v_mfma_f32_16x16x32_bf16 v[28:31], v[186:189], v[216:219], v[28:31]
	v_mfma_f32_16x16x32_bf16 v[16:19], v[178:181], v[224:227], v[16:19]
	v_mfma_f32_16x16x32_bf16 v[12:15], v[186:189], v[224:227], v[12:15]
	v_mfma_f32_16x16x32_bf16 v[8:11], v[178:181], v[236:239], v[8:11]
	v_mfma_f32_16x16x32_bf16 v[4:7], v[186:189], v[236:239], v[4:7]
	v_mfma_f32_16x16x32_bf16 v[48:51], v[182:185], v[212:215], v[48:51]
	v_mfma_f32_16x16x32_bf16 v[44:47], v[190:193], v[212:215], v[44:47]
	v_mfma_f32_16x16x32_bf16 v[32:35], v[182:185], v[220:223], v[32:35]
	v_mfma_f32_16x16x32_bf16 v[28:31], v[190:193], v[220:223], v[28:31]
	v_mfma_f32_16x16x32_bf16 v[16:19], v[182:185], v[228:231], v[16:19]
	v_mfma_f32_16x16x32_bf16 v[12:15], v[190:193], v[228:231], v[12:15]
	v_mfma_f32_16x16x32_bf16 v[8:11], v[182:185], v[240:243], v[8:11]
	v_mfma_f32_16x16x32_bf16 v[4:7], v[190:193], v[240:243], v[4:7]
	s_barrier
	s_add_i32 s49, s49, 2
	s_add_u32 s36, s36, 0x100
	s_addc_u32 s37, s37, 0
	s_add_u32 s47, s47, 0x100
	s_addc_u32 s48, s48, 0
	s_cmp_gt_u32 s49, 13
	s_cbranch_scc0 .LBB0_1567
	s_and_b64 vcc, exec, s[20:21]
	s_cbranch_vccz .LBB0_1570
	s_barrier
